# v16 + in the four ssq-scaled GEMM epilogues the leading half-workgroup issues its row sum-of-squares loads before its extra end-of-tile barrier (latency hidden behind the trailing half's last MFMA blo
# speedup vs baseline: 1.0050x; 1.0050x over previous
; #define PG8_STAGE(bufoff, gbase, voff) do { _Pragma("unroll") for (int _i = 0; _i < 2; ++_i) \
;         __builtin_amdgcn_global_load_lds((const unsigned*)((const char*)(gbase) + (voff)[_i]), (PG8_LAS unsigned*)(lds + (bufoff) + ldsw + _i * 8192), 16, 0, 0); } while (0)
; #define PG8_LDA(dst, b, h) do { _Pragma("unroll") for (int m = 0; m < 4; ++m) _Pragma("unroll") for (int k = 0; k < 2; ++k) dst[m][k] = *(const PG8_LAS bf16x8*)(lds + PG8_SA(b, h) + aoff + m * 2048 + k * 1024); } while (0)
; #define PG8_LDB(dst, b, h) do { _Pragma("unroll") for (int n = 0; n < 2; ++n) _Pragma("unroll") for (int k = 0; k < 2; ++k) dst[n][k] = *(const PG8_LAS bf16x8*)(lds + PG8_SB(b, h) + boff + n * 2048 + k * 1024); } while (0)
; #define PG8_MMA(ai, bj, At, Bt) do { __builtin_amdgcn_s_setprio(1); _Pragma("unroll") for (int m = 0; m < 4; ++m) _Pragma("unroll") for (int n = 0; n < 2; ++n) _Pragma("unroll") for (int k = 0; k < 2; ++k) \
;         acc[ai][bj][m][n] = __builtin_amdgcn_mfma_f32_16x16x32_bf16(Bt[n][k], At[m][k], acc[ai][bj][m][n], 0, 0, 0); __builtin_amdgcn_s_setprio(0); } while (0)
; #define PG8_WAIT_V(n) asm volatile("s_waitcnt vmcnt(" #n ")" ::: "memory")
; #define PG8_WAIT_L(n) asm volatile("s_waitcnt lgkmcnt(" #n ")" ::: "memory")
; template <class Epi, class Sched, bool ALIGN_EPI = false, bool SP2 = false>
; __device__ __forceinline__ void gemm_phase(PG8_LAS unsigned char* lds, const Gemm g, const Sched& S, const Epi& E) {
;     ...
;             const bool last = (t == nt - 2);
;             const char* a1 = cA + (size_t)(t + 1) * kstep;
;             const char* a2 = last ? nA : cA + (size_t)(t + 2) * kstep; const char* b2 = last ? nB : cB + (size_t)(t + 2) * kstep;
;             const char* a3 = a2 + kstep; const char* b3 = b2 + kstep;
;             if (last && has_next) S.a_ready(nxt);
;             if constexpr (SP2) {
;             PG8_LDB(B0, 0, 0); PG8_LDB(B1, 0, 1); PG8_SCHED; PG8_LDA(At, 0, 0); PG8_STAGE(PG8_SA(1, 1), a1 + hstep, voffA);
;             PG8_WAIT_V(8); PG8_WAIT_L(0); PG8_BAR; PG8_MMA(0, 0, At, B0); PG8_MMA(0, 1, At, B1); PG8_BAR; PG8_SCHED;
;             PG8_LDA(At, 0, 1); PG8_STAGE(PG8_SB(0, 0), b2, voffB); PG8_STAGE(PG8_SB(0, 1), b2 + hstep, voffB); PG8_STAGE(PG8_SA(0, 0), a2, voffA);
;             PG8_WAIT_V(8); PG8_WAIT_L(0); PG8_BAR; PG8_MMA(1, 0, At, B0); PG8_MMA(1, 1, At, B1); PG8_BAR; PG8_SCHED;
.LBB0_673:
	ds_read_b128 v[148:151], v241 offset:0
	ds_read_b128 v[156:159], v241 offset:1024
	ds_read_b128 v[166:169], v241 offset:2048
	ds_read_b128 v[170:173], v241 offset:3072
	ds_read_b128 v[174:177], v241 offset:16384
	ds_read_b128 v[178:181], v241 offset:17408
	ds_read_b128 v[182:185], v241 offset:18432
	ds_read_b128 v[186:189], v241 offset:19456
	s_add_u32 s20, s22, 0xfff00080
	s_addc_u32 s21, s23, -1
	s_cmp_eq_u32 s35, 60
	s_cselect_b32 s25, s11, s21
	s_cselect_b32 s24, s52, s20
	s_cselect_b32 s21, s13, s34
	s_cselect_b32 s20, s53, s62
	s_add_i32 m0, s19, 0xc000
	ds_read_b128 v[190:193], v161
	ds_read_b128 v[194:197], v161 offset:1024
	ds_read_b128 v[198:201], v161 offset:2048
	ds_read_b128 v[202:205], v161 offset:3072
	ds_read_b128 v[206:209], v161 offset:4096
	ds_read_b128 v[210:213], v161 offset:5120
	ds_read_b128 v[214:217], v161 offset:6144
	ds_read_b128 v[218:221], v161 offset:7168
	global_load_lds_dwordx4 v138, s[22:23]
	s_add_i32 m0, s19, 0xe000
	s_nop 0
	global_load_lds_dwordx4 v140, s[22:23]
	s_waitcnt vmcnt(8)
	s_waitcnt lgkmcnt(0)
	s_barrier
	s_waitcnt lgkmcnt(0)
	v_mfma_f32_16x16x32_bf16 v[118:121], v[148:151], v[190:193], v[118:121]
	v_mfma_f32_16x16x32_bf16 v[118:121], v[156:159], v[194:197], v[118:121]
	v_mfma_f32_16x16x32_bf16 v[102:105], v[156:159], v[202:205], v[102:105]
	v_mfma_f32_16x16x32_bf16 v[102:105], v[148:151], v[198:201], v[102:105]
	v_mfma_f32_16x16x32_bf16 v[86:89], v[148:151], v[206:209], v[86:89]
	v_mfma_f32_16x16x32_bf16 v[86:89], v[156:159], v[210:213], v[86:89]
	v_mfma_f32_16x16x32_bf16 v[70:73], v[156:159], v[218:221], v[70:73]
	v_mfma_f32_16x16x32_bf16 v[70:73], v[148:151], v[214:217], v[70:73]
	v_mfma_f32_16x16x32_bf16 v[66:69], v[166:169], v[214:217], v[66:69]
	v_mfma_f32_16x16x32_bf16 v[66:69], v[170:173], v[218:221], v[66:69]
	v_mfma_f32_16x16x32_bf16 v[82:85], v[170:173], v[210:213], v[82:85]
	v_mfma_f32_16x16x32_bf16 v[82:85], v[166:169], v[206:209], v[82:85]
	v_mfma_f32_16x16x32_bf16 v[98:101], v[166:169], v[198:201], v[98:101]
	v_mfma_f32_16x16x32_bf16 v[98:101], v[170:173], v[202:205], v[98:101]
	v_mfma_f32_16x16x32_bf16 v[114:117], v[170:173], v[194:197], v[114:117]
	v_mfma_f32_16x16x32_bf16 v[114:117], v[166:169], v[190:193], v[114:117]
	v_mfma_f32_16x16x32_bf16 v[126:129], v[174:177], v[190:193], v[126:129]
	v_mfma_f32_16x16x32_bf16 v[126:129], v[178:181], v[194:197], v[126:129]
	v_mfma_f32_16x16x32_bf16 v[110:113], v[178:181], v[202:205], v[110:113]
	v_mfma_f32_16x16x32_bf16 v[110:113], v[174:177], v[198:201], v[110:113]
	v_mfma_f32_16x16x32_bf16 v[94:97], v[174:177], v[206:209], v[94:97]
	v_mfma_f32_16x16x32_bf16 v[94:97], v[178:181], v[210:213], v[94:97]
	v_mfma_f32_16x16x32_bf16 v[78:81], v[178:181], v[218:221], v[78:81]
	v_mfma_f32_16x16x32_bf16 v[78:81], v[174:177], v[214:217], v[78:81]
	v_mfma_f32_16x16x32_bf16 v[74:77], v[182:185], v[214:217], v[74:77]
	v_mfma_f32_16x16x32_bf16 v[74:77], v[186:189], v[218:221], v[74:77]
	v_mfma_f32_16x16x32_bf16 v[90:93], v[186:189], v[210:213], v[90:93]
	v_mfma_f32_16x16x32_bf16 v[90:93], v[182:185], v[206:209], v[90:93]
	v_mfma_f32_16x16x32_bf16 v[106:109], v[182:185], v[198:201], v[106:109]
	v_mfma_f32_16x16x32_bf16 v[106:109], v[186:189], v[202:205], v[106:109]
	v_mfma_f32_16x16x32_bf16 v[122:125], v[186:189], v[194:197], v[122:125]
	v_mfma_f32_16x16x32_bf16 v[122:125], v[182:185], v[190:193], v[122:125]
	s_barrier
	s_add_i32 s63, s43, s26
	s_mov_b32 m0, s63
	ds_read_b128 v[190:193], v161 offset:16384
	ds_read_b128 v[194:197], v161 offset:17408
	ds_read_b128 v[198:201], v161 offset:18432
	ds_read_b128 v[202:205], v161 offset:19456
	ds_read_b128 v[206:209], v161 offset:20480
	ds_read_b128 v[210:213], v161 offset:21504
	ds_read_b128 v[214:217], v161 offset:22528
	ds_read_b128 v[218:221], v161 offset:23552
	global_load_lds_dwordx4 v132, s[20:21]
	s_add_i32 m0, s63, 0x2000
	s_add_u32 s64, s20, 0x100000
	s_addc_u32 s65, s21, 0
	s_add_i32 s63, s46, s26
	global_load_lds_dwordx4 v136, s[20:21]
	s_mov_b32 m0, s63
	s_add_u32 s100, s24, 0x80
	s_addc_u32 s101, s25, 0
	global_load_lds_dwordx4 v132, s[64:65]
	s_add_i32 m0, s63, 0x2000
	s_nop 0
	global_load_lds_dwordx4 v136, s[64:65]
	s_mov_b32 m0, s19
	s_nop 0
	global_load_lds_dwordx4 v130, s[24:25]
	s_mov_b32 m0, s29
	s_nop 0
	global_load_lds_dwordx4 v134, s[24:25]
	s_waitcnt vmcnt(8)
	s_waitcnt lgkmcnt(0)
	s_barrier
	s_waitcnt lgkmcnt(0)
	v_mfma_f32_16x16x32_bf16 v[54:57], v[148:151], v[190:193], v[54:57]
	v_mfma_f32_16x16x32_bf16 v[54:57], v[156:159], v[194:197], v[54:57]
	v_mfma_f32_16x16x32_bf16 v[38:41], v[156:159], v[202:205], v[38:41]
	v_mfma_f32_16x16x32_bf16 v[38:41], v[148:151], v[198:201], v[38:41]
	v_mfma_f32_16x16x32_bf16 v[22:25], v[148:151], v[206:209], v[22:25]
	v_mfma_f32_16x16x32_bf16 v[22:25], v[156:159], v[210:213], v[22:25]
	v_mfma_f32_16x16x32_bf16 v[6:9], v[156:159], v[218:221], v[6:9]
	v_mfma_f32_16x16x32_bf16 v[6:9], v[148:151], v[214:217], v[6:9]
	v_mfma_f32_16x16x32_bf16 v[2:5], v[166:169], v[214:217], v[2:5]
	v_mfma_f32_16x16x32_bf16 v[2:5], v[170:173], v[218:221], v[2:5]
	v_mfma_f32_16x16x32_bf16 v[18:21], v[170:173], v[210:213], v[18:21]
	v_mfma_f32_16x16x32_bf16 v[18:21], v[166:169], v[206:209], v[18:21]
	v_mfma_f32_16x16x32_bf16 v[34:37], v[166:169], v[198:201], v[34:37]
	v_mfma_f32_16x16x32_bf16 v[34:37], v[170:173], v[202:205], v[34:37]
	v_mfma_f32_16x16x32_bf16 v[50:53], v[170:173], v[194:197], v[50:53]
	v_mfma_f32_16x16x32_bf16 v[50:53], v[166:169], v[190:193], v[50:53]
	v_mfma_f32_16x16x32_bf16 v[62:65], v[174:177], v[190:193], v[62:65]
	v_mfma_f32_16x16x32_bf16 v[62:65], v[178:181], v[194:197], v[62:65]
	v_mfma_f32_16x16x32_bf16 v[46:49], v[178:181], v[202:205], v[46:49]
	v_mfma_f32_16x16x32_bf16 v[46:49], v[174:177], v[198:201], v[46:49]
	v_mfma_f32_16x16x32_bf16 v[30:33], v[174:177], v[206:209], v[30:33]
	v_mfma_f32_16x16x32_bf16 v[30:33], v[178:181], v[210:213], v[30:33]
	v_mfma_f32_16x16x32_bf16 v[10:13], v[178:181], v[218:221], v[10:13]
	v_mfma_f32_16x16x32_bf16 v[10:13], v[174:177], v[214:217], v[10:13]
	v_mfma_f32_16x16x32_bf16 v[14:17], v[182:185], v[214:217], v[14:17]
	v_mfma_f32_16x16x32_bf16 v[14:17], v[186:189], v[218:221], v[14:17]
	v_mfma_f32_16x16x32_bf16 v[26:29], v[186:189], v[210:213], v[26:29]
	v_mfma_f32_16x16x32_bf16 v[26:29], v[182:185], v[206:209], v[26:29]
	v_mfma_f32_16x16x32_bf16 v[42:45], v[182:185], v[198:201], v[42:45]
	v_mfma_f32_16x16x32_bf16 v[42:45], v[186:189], v[202:205], v[42:45]
	v_mfma_f32_16x16x32_bf16 v[58:61], v[186:189], v[194:197], v[58:61]
	v_mfma_f32_16x16x32_bf16 v[58:61], v[182:185], v[190:193], v[58:61]
	s_barrier
; #define PG8_STAGE(bufoff, gbase, voff) do { _Pragma("unroll") for (int _i = 0; _i < 2; ++_i) \
;         __builtin_amdgcn_global_load_lds((const unsigned*)((const char*)(gbase) + (voff)[_i]), (PG8_LAS unsigned*)(lds + (bufoff) + ldsw + _i * 8192), 16, 0, 0); } while (0)
; #define PG8_LDA(dst, b, h) do { _Pragma("unroll") for (int m = 0; m < 4; ++m) _Pragma("unroll") for (int k = 0; k < 2; ++k) dst[m][k] = *(const PG8_LAS bf16x8*)(lds + PG8_SA(b, h) + aoff + m * 2048 + k * 1024); } while (0)
; #define PG8_LDB(dst, b, h) do { _Pragma("unroll") for (int n = 0; n < 2; ++n) _Pragma("unroll") for (int k = 0; k < 2; ++k) dst[n][k] = *(const PG8_LAS bf16x8*)(lds + PG8_SB(b, h) + boff + n * 2048 + k * 1024); } while (0)
; #define PG8_MMA(ai, bj, At, Bt) do { __builtin_amdgcn_s_setprio(1); _Pragma("unroll") for (int m = 0; m < 4; ++m) _Pragma("unroll") for (int n = 0; n < 2; ++n) _Pragma("unroll") for (int k = 0; k < 2; ++k) \
;         acc[ai][bj][m][n] = __builtin_amdgcn_mfma_f32_16x16x32_bf16(Bt[n][k], At[m][k], acc[ai][bj][m][n], 0, 0, 0); __builtin_amdgcn_s_setprio(0); } while (0)
; #define PG8_WAIT_V(n) asm volatile("s_waitcnt vmcnt(" #n ")" ::: "memory")
; #define PG8_WAIT_L(n) asm volatile("s_waitcnt lgkmcnt(" #n ")" ::: "memory")
; #define PG8_BAR __builtin_amdgcn_s_barrier()
; #define PG8_SCHED __builtin_amdgcn_sched_barrier(0)
; template <class Epi, class Sched, bool ALIGN_EPI = false, bool SP2 = false>
; __device__ __forceinline__ void gemm_phase(PG8_LAS unsigned char* lds, const Gemm g, const Sched& S, const Epi& E) {
;     ...
;             PG8_LDB(B0, 1, 0); PG8_LDB(B1, 1, 1); PG8_SCHED; PG8_LDA(At, 1, 0); PG8_STAGE(PG8_SA(0, 1), a2 + hstep, voffA);
;             PG8_WAIT_V(8); PG8_WAIT_L(0); PG8_BAR; PG8_MMA(0, 0, At, B0); PG8_MMA(0, 1, At, B1); PG8_BAR; PG8_SCHED;
;             PG8_LDA(At, 1, 1); PG8_STAGE(PG8_SB(1, 0), b3, voffB); PG8_STAGE(PG8_SB(1, 1), b3 + hstep, voffB); PG8_STAGE(PG8_SA(1, 0), a3, voffA);
;             PG8_WAIT_V(8); PG8_WAIT_L(0); PG8_BAR; PG8_MMA(1, 0, At, B0); PG8_MMA(1, 1, At, B1); PG8_BAR; PG8_SCHED;
	s_add_i32 s63, 0, 0x18000
	s_add_i32 s64, 0, 0x1c000
	ds_read_b128 v[148:151], v241 offset:32768
	ds_read_b128 v[156:159], v241 offset:33792
	ds_read_b128 v[166:169], v241 offset:34816
	ds_read_b128 v[170:173], v241 offset:35840
	ds_read_b128 v[174:177], v241 offset:49152
	ds_read_b128 v[178:181], v241 offset:50176
	ds_read_b128 v[182:185], v241 offset:51200
	ds_read_b128 v[186:189], v241 offset:52224
	s_add_u32 s24, s24, 0x100000
	s_addc_u32 s25, s25, 0
	s_mov_b32 m0, s30
	ds_read_b128 v[190:193], v161 offset:32768
	ds_read_b128 v[194:197], v161 offset:33792
	ds_read_b128 v[198:201], v161 offset:34816
	ds_read_b128 v[202:205], v161 offset:35840
	ds_read_b128 v[206:209], v161 offset:36864
	ds_read_b128 v[210:213], v161 offset:37888
	ds_read_b128 v[214:217], v161 offset:38912
	ds_read_b128 v[218:221], v161 offset:39936
	global_load_lds_dwordx4 v130, s[24:25]
	s_mov_b32 m0, s31
	s_nop 0
	global_load_lds_dwordx4 v134, s[24:25]
	s_waitcnt vmcnt(8)
	s_waitcnt lgkmcnt(0)
	s_barrier
	s_waitcnt lgkmcnt(0)
	v_mfma_f32_16x16x32_bf16 v[118:121], v[148:151], v[190:193], v[118:121]
	v_mfma_f32_16x16x32_bf16 v[118:121], v[156:159], v[194:197], v[118:121]
	v_mfma_f32_16x16x32_bf16 v[102:105], v[156:159], v[202:205], v[102:105]
	v_mfma_f32_16x16x32_bf16 v[102:105], v[148:151], v[198:201], v[102:105]
	v_mfma_f32_16x16x32_bf16 v[86:89], v[148:151], v[206:209], v[86:89]
	v_mfma_f32_16x16x32_bf16 v[86:89], v[156:159], v[210:213], v[86:89]
	v_mfma_f32_16x16x32_bf16 v[70:73], v[156:159], v[218:221], v[70:73]
	v_mfma_f32_16x16x32_bf16 v[70:73], v[148:151], v[214:217], v[70:73]
	v_mfma_f32_16x16x32_bf16 v[66:69], v[166:169], v[214:217], v[66:69]
	v_mfma_f32_16x16x32_bf16 v[66:69], v[170:173], v[218:221], v[66:69]
	v_mfma_f32_16x16x32_bf16 v[82:85], v[170:173], v[210:213], v[82:85]
	v_mfma_f32_16x16x32_bf16 v[82:85], v[166:169], v[206:209], v[82:85]
	v_mfma_f32_16x16x32_bf16 v[98:101], v[166:169], v[198:201], v[98:101]
	v_mfma_f32_16x16x32_bf16 v[98:101], v[170:173], v[202:205], v[98:101]
	v_mfma_f32_16x16x32_bf16 v[114:117], v[170:173], v[194:197], v[114:117]
	v_mfma_f32_16x16x32_bf16 v[114:117], v[166:169], v[190:193], v[114:117]
	v_mfma_f32_16x16x32_bf16 v[126:129], v[174:177], v[190:193], v[126:129]
	v_mfma_f32_16x16x32_bf16 v[126:129], v[178:181], v[194:197], v[126:129]
	v_mfma_f32_16x16x32_bf16 v[110:113], v[178:181], v[202:205], v[110:113]
	v_mfma_f32_16x16x32_bf16 v[110:113], v[174:177], v[198:201], v[110:113]
	v_mfma_f32_16x16x32_bf16 v[94:97], v[174:177], v[206:209], v[94:97]
	v_mfma_f32_16x16x32_bf16 v[94:97], v[178:181], v[210:213], v[94:97]
	v_mfma_f32_16x16x32_bf16 v[78:81], v[178:181], v[218:221], v[78:81]
	v_mfma_f32_16x16x32_bf16 v[78:81], v[174:177], v[214:217], v[78:81]
	v_mfma_f32_16x16x32_bf16 v[74:77], v[182:185], v[214:217], v[74:77]
	v_mfma_f32_16x16x32_bf16 v[74:77], v[186:189], v[218:221], v[74:77]
	v_mfma_f32_16x16x32_bf16 v[90:93], v[186:189], v[210:213], v[90:93]
	v_mfma_f32_16x16x32_bf16 v[90:93], v[182:185], v[206:209], v[90:93]
	v_mfma_f32_16x16x32_bf16 v[106:109], v[182:185], v[198:201], v[106:109]
	v_mfma_f32_16x16x32_bf16 v[106:109], v[186:189], v[202:205], v[106:109]
	v_mfma_f32_16x16x32_bf16 v[122:125], v[186:189], v[194:197], v[122:125]
	v_mfma_f32_16x16x32_bf16 v[122:125], v[182:185], v[190:193], v[122:125]
	s_barrier
	s_add_i32 s24, s63, s26
	s_add_i32 m0, s24, 0xffffff80
	ds_read_b128 v[190:193], v161 offset:49152
	ds_read_b128 v[194:197], v161 offset:50176
	ds_read_b128 v[198:201], v161 offset:51200
	ds_read_b128 v[202:205], v161 offset:52224
	ds_read_b128 v[206:209], v161 offset:53248
	ds_read_b128 v[210:213], v161 offset:54272
	ds_read_b128 v[214:217], v161 offset:55296
	ds_read_b128 v[218:221], v161 offset:56320
	global_load_lds_dwordx4 v132, s[20:21] offset:128
	s_add_i32 m0, s24, 0x1f80
	s_add_i32 s24, s64, s26
	global_load_lds_dwordx4 v136, s[20:21] offset:128
	s_add_u32 s20, s20, 0x100080
	s_addc_u32 s21, s21, 0
	s_mov_b32 m0, s24
	s_nop 0
	global_load_lds_dwordx4 v132, s[20:21]
	s_add_i32 m0, s24, 0x2000
	s_nop 0
	global_load_lds_dwordx4 v136, s[20:21]
	s_mov_b32 m0, s40
	s_nop 0
	global_load_lds_dwordx4 v130, s[100:101]
	s_mov_b32 m0, s41
	s_nop 0
	global_load_lds_dwordx4 v134, s[100:101]
	s_waitcnt vmcnt(8)
	s_waitcnt lgkmcnt(0)
	s_barrier
; #define PG8_WAIT_V(n) asm volatile("s_waitcnt vmcnt(" #n ")" ::: "memory")
; #define PG8_BAR __builtin_amdgcn_s_barrier()
; __device__ __forceinline__ float ssq_rstd(const ssq_t* ssq, int row) { return __builtin_amdgcn_rsqf((float)ssq[row] * (SSQ_UNFIX * RMS_INV_D) + RMS_EPS); }
;     __device__ __forceinline__ void operator()(const f32x4 (&acc)[2][2][4][2], const Unit& u, int wr, int wc, int fr, int fq) const {
;         const int row0 = u.pm * BM + wr * 64 + fr, col0 = u.pn * BM + wc * 32 + 8 * fq;
;         float rs[2][4];
; #pragma unroll
;         for (int ai = 0; ai < 2; ++ai)
; #pragma unroll
;             for (int m = 0; m < 4; ++m) rs[ai][m] = SCALE ? ssq_rstd(ssq, row0 + ai * HALF + m * 16) : 1.0f;
; template <class Epi, class Sched, bool ALIGN_EPI = false, bool SP2 = false>
; __device__ __forceinline__ void gemm_phase(PG8_LAS unsigned char* lds, const Gemm g, const Sched& S, const Epi& E) {
;     ...
;             PG8_WAIT_V(8); PG8_WAIT_L(0); PG8_BAR; PG8_MMA(1, 0, At, B0); PG8_MMA(1, 1, At, B1); PG8_BAR; PG8_SCHED;
;             } else {
;             PG8_LDB(B0, 0, 0); PG8_SCHED; PG8_LDA(At, 0, 0); PG8_STAGE(PG8_SA(1, 1), a1 + hstep, voffA);
;             PG8_WAIT_L(8); PG8_BAR; PG8_WAIT_L(0); PG8_MMA(0, 0, At, B0); PG8_BAR; PG8_SCHED;
;             PG8_LDB(B1, 0, 1); PG8_STAGE(PG8_SB(0, 0), b2, voffB);
;             PG8_BAR; PG8_WAIT_L(0); PG8_MMA(0, 1, At, B1); PG8_BAR;
;             PG8_LDA(At, 0, 1); PG8_STAGE(PG8_SA(0, 0), a2, voffA);
;             PG8_BAR; PG8_WAIT_L(0); PG8_MMA(1, 0, At, B0); PG8_BAR; PG8_SCHED;
;             PG8_STAGE(PG8_SB(0, 1), b2 + hstep, voffB);
;             PG8_WAIT_V(6); PG8_BAR; PG8_MMA(1, 1, At, B1); PG8_BAR;
;             PG8_LDB(B0, 1, 0); PG8_SCHED; PG8_LDA(At, 1, 0); PG8_STAGE(PG8_SA(0, 1), a2 + hstep, voffA);
;             PG8_WAIT_L(8); PG8_BAR; PG8_WAIT_L(0); PG8_MMA(0, 0, At, B0); PG8_BAR; PG8_SCHED;
;             PG8_LDB(B1, 1, 1); PG8_STAGE(PG8_SB(1, 0), b3, voffB);
;             PG8_BAR; PG8_WAIT_L(0); PG8_MMA(0, 1, At, B1); PG8_BAR;
;             PG8_LDA(At, 1, 1); PG8_STAGE(PG8_SA(1, 0), a3, voffA);
;             PG8_BAR; PG8_WAIT_L(0); PG8_MMA(1, 0, At, B0); PG8_BAR; PG8_SCHED;
;             PG8_STAGE(PG8_SB(1, 1), b3 + hstep, voffB);
;             PG8_WAIT_V(6); PG8_BAR; PG8_MMA(1, 1, At, B1); PG8_BAR;
;             }
;         }
;         if constexpr (ALIGN_EPI) { if (wr == 0) PG8_BAR; }
	s_waitcnt lgkmcnt(0)
	v_mfma_f32_16x16x32_bf16 v[54:57], v[148:151], v[190:193], v[54:57]
	v_mfma_f32_16x16x32_bf16 v[54:57], v[156:159], v[194:197], v[54:57]
	v_mfma_f32_16x16x32_bf16 v[38:41], v[156:159], v[202:205], v[38:41]
	v_mfma_f32_16x16x32_bf16 v[38:41], v[148:151], v[198:201], v[38:41]
	v_mfma_f32_16x16x32_bf16 v[22:25], v[148:151], v[206:209], v[22:25]
	v_mfma_f32_16x16x32_bf16 v[22:25], v[156:159], v[210:213], v[22:25]
	v_mfma_f32_16x16x32_bf16 v[6:9], v[156:159], v[218:221], v[6:9]
	v_mfma_f32_16x16x32_bf16 v[6:9], v[148:151], v[214:217], v[6:9]
	v_mfma_f32_16x16x32_bf16 v[2:5], v[166:169], v[214:217], v[2:5]
	v_mfma_f32_16x16x32_bf16 v[2:5], v[170:173], v[218:221], v[2:5]
	v_mfma_f32_16x16x32_bf16 v[18:21], v[170:173], v[210:213], v[18:21]
	v_mfma_f32_16x16x32_bf16 v[18:21], v[166:169], v[206:209], v[18:21]
	v_mfma_f32_16x16x32_bf16 v[34:37], v[166:169], v[198:201], v[34:37]
	v_mfma_f32_16x16x32_bf16 v[34:37], v[170:173], v[202:205], v[34:37]
	v_mfma_f32_16x16x32_bf16 v[50:53], v[170:173], v[194:197], v[50:53]
	v_mfma_f32_16x16x32_bf16 v[50:53], v[166:169], v[190:193], v[50:53]
	v_mfma_f32_16x16x32_bf16 v[62:65], v[174:177], v[190:193], v[62:65]
	v_mfma_f32_16x16x32_bf16 v[62:65], v[178:181], v[194:197], v[62:65]
	v_mfma_f32_16x16x32_bf16 v[46:49], v[178:181], v[202:205], v[46:49]
	v_mfma_f32_16x16x32_bf16 v[46:49], v[174:177], v[198:201], v[46:49]
	v_mfma_f32_16x16x32_bf16 v[30:33], v[174:177], v[206:209], v[30:33]
	v_mfma_f32_16x16x32_bf16 v[30:33], v[178:181], v[210:213], v[30:33]
	v_mfma_f32_16x16x32_bf16 v[10:13], v[178:181], v[218:221], v[10:13]
	v_mfma_f32_16x16x32_bf16 v[10:13], v[174:177], v[214:217], v[10:13]
	v_mfma_f32_16x16x32_bf16 v[14:17], v[182:185], v[214:217], v[14:17]
	v_mfma_f32_16x16x32_bf16 v[14:17], v[186:189], v[218:221], v[14:17]
	v_mfma_f32_16x16x32_bf16 v[26:29], v[186:189], v[210:213], v[26:29]
	v_mfma_f32_16x16x32_bf16 v[26:29], v[182:185], v[206:209], v[26:29]
	v_mfma_f32_16x16x32_bf16 v[42:45], v[182:185], v[198:201], v[42:45]
	v_mfma_f32_16x16x32_bf16 v[42:45], v[186:189], v[202:205], v[42:45]
	v_mfma_f32_16x16x32_bf16 v[58:61], v[186:189], v[194:197], v[58:61]
	v_mfma_f32_16x16x32_bf16 v[58:61], v[182:185], v[190:193], v[58:61]
	s_barrier
	s_add_i32 s35, s35, 2
	s_add_u32 s22, s22, 0x100
	s_addc_u32 s23, s23, 0
	s_add_u32 s62, s62, 0x100
	s_addc_u32 s34, s34, 0
	s_cmp_gt_u32 s35, 61
	s_cbranch_scc0 .LBB0_673
	s_and_b64 vcc, exec, s[8:9]
	s_cbranch_vccz .LBB0_676
	v_lshl_add_u32 v150, s18, 8, v147
	v_ashrrev_i32_e32 v151, 31, v150
	v_or_b32_e32 v166, 16, v150
	v_or_b32_e32 v158, 32, v150
	v_or_b32_e32 v156, 48, v150
	v_lshl_add_u64 v[148:149], v[150:151], 3, s[2:3]
	v_ashrrev_i32_e32 v167, 31, v166
	v_ashrrev_i32_e32 v159, 31, v158
	v_ashrrev_i32_e32 v157, 31, v156
	v_lshl_add_u64 v[168:169], v[166:167], 3, s[2:3]
	v_lshl_add_u64 v[170:171], v[158:159], 3, s[2:3]
	global_load_dwordx2 v[172:173], v[148:149], off
	global_load_dwordx2 v[174:175], v[148:149], off offset:1024
	global_load_dwordx2 v[176:177], v[148:149], off offset:1152
	global_load_dwordx2 v[178:179], v[148:149], off offset:1280
	v_lshl_add_u64 v[180:181], v[156:157], 3, s[2:3]
	global_load_dwordx2 v[168:169], v[168:169], off
	s_nop 0
	global_load_dwordx2 v[170:171], v[170:171], off
	s_nop 0
	global_load_dwordx2 v[180:181], v[180:181], off
	s_nop 0
	global_load_dwordx2 v[148:149], v[148:149], off offset:1408
	s_barrier
	s_branch .Lepi_rest_676

; __device__ __forceinline__ unsigned cvt_pk_bf16(float lo, float hi) { unsigned r; asm volatile("v_cvt_pk_bf16_f32 %0, %1, %2" : "=v"(r) : "v"(lo), "v"(hi)); return r; }
; __device__ __forceinline__ unsigned cvt_pk_bf16(float lo, float hi) { unsigned r; asm volatile("v_cvt_pk_bf16_f32 %0, %1, %2" : "=v"(r) : "v"(lo), "v"(hi)); return r; }
; __device__ __forceinline__ float ssq_rstd(const ssq_t* ssq, int row) { return __builtin_amdgcn_rsqf((float)ssq[row] * (SSQ_UNFIX * RMS_INV_D) + RMS_EPS); }
;     __device__ __forceinline__ void operator()(const f32x4 (&acc)[2][2][4][2], const Unit& u, int wr, int wc, int fr, int fq) const {
;         const int row0 = u.pm * BM + wr * 64 + fr, col0 = u.pn * BM + wc * 32 + 8 * fq;
;         float rs[2][4];
; #pragma unroll
;         for (int ai = 0; ai < 2; ++ai)
; #pragma unroll
;             for (int m = 0; m < 4; ++m) rs[ai][m] = SCALE ? ssq_rstd(ssq, row0 + ai * HALF + m * 16) : 1.0f;
; #pragma unroll
;         for (int ai = 0; ai < 2; ++ai)
; #pragma unroll
;             for (int m = 0; m < 4; ++m) { const int row = row0 + ai * HALF + m * 16; bf16_t* rowp = O + (size_t)row * ldc + col0;
; #pragma unroll
;                 for (int bj = 0; bj < 2; ++bj) { const f32x2 r2 = {rs[ai][m], rs[ai][m]}; const f32x4 a0 = acc[ai][bj][m][0], a1 = acc[ai][bj][m][1];
;                     const f32x2 p0 = (f32x2){a0[0], a0[1]} * r2, p1 = (f32x2){a0[2], a0[3]} * r2, p2 = (f32x2){a1[0], a1[1]} * r2, p3 = (f32x2){a1[2], a1[3]} * r2;
;                     u32x4 w; w.x = cvt_pk_bf16(p0.x, p0.y); w.y = cvt_pk_bf16(p1.x, p1.y); w.z = cvt_pk_bf16(p2.x, p2.y); w.w = cvt_pk_bf16(p3.x, p3.y);
;                     *(u32x4*)(rowp + bj * HALF) = w; } }
.Lepi_rest_676:
	v_add_u32_e32 v157, 0x80, v150
	v_add_u32_e32 v159, 0x90, v150
	v_add_u32_e32 v163, 0xa0, v150
	s_andn2_b64 vcc, exec, s[0:1]
	s_mov_b64 s[0:1], -1
	s_waitcnt vmcnt(0)
	v_ffbh_u32_e32 v146, v173
	v_min_u32_e32 v146, 32, v146
	v_ffbh_u32_e32 v160, v169
	v_lshlrev_b64 v[172:173], v146, v[172:173]
	v_min_u32_e32 v160, 32, v160
	v_ffbh_u32_e32 v165, v171
	v_ffbh_u32_e32 v167, v181
	v_min_u32_e32 v172, 1, v172
	v_lshlrev_b64 v[168:169], v160, v[168:169]
	v_min_u32_e32 v165, 32, v165
	v_min_u32_e32 v167, 32, v167
	v_or_b32_e32 v172, v173, v172
	v_min_u32_e32 v168, 1, v168
	v_lshlrev_b64 v[170:171], v165, v[170:171]
	v_lshlrev_b64 v[180:181], v167, v[180:181]
	v_cvt_f32_u32_e32 v172, v172
	v_or_b32_e32 v168, v169, v168
	v_min_u32_e32 v170, 1, v170
	v_min_u32_e32 v173, 1, v180
	v_cvt_f32_u32_e32 v168, v168
	v_ffbh_u32_e32 v151, v175
	v_or_b32_e32 v169, v171, v170
	v_or_b32_e32 v170, v181, v173
	v_ffbh_u32_e32 v152, v177
	v_ffbh_u32_e32 v154, v179
	v_min_u32_e32 v151, 32, v151
	v_ffbh_u32_e32 v182, v149
	v_sub_u32_e32 v146, 32, v146
	v_cvt_f32_u32_e32 v170, v170
	v_min_u32_e32 v152, 32, v152
	v_min_u32_e32 v154, 32, v154
	v_lshlrev_b64 v[174:175], v151, v[174:175]
	v_min_u32_e32 v182, 32, v182
	v_sub_u32_e32 v160, 32, v160
	v_ldexp_f32 v146, v172, v146
	v_lshlrev_b64 v[176:177], v152, v[176:177]
	v_lshlrev_b64 v[178:179], v154, v[178:179]
	v_min_u32_e32 v174, 1, v174
	v_lshlrev_b64 v[148:149], v182, v[148:149]
	v_fmamk_f32 v146, v146, 0x2d800000, v162
	v_ldexp_f32 v160, v168, v160
	v_sub_u32_e32 v167, 32, v167
	v_min_u32_e32 v176, 1, v176
	v_min_u32_e32 v178, 1, v178
	v_or_b32_e32 v174, v175, v174
	v_min_u32_e32 v148, 1, v148
	v_rsq_f32_e32 v168, v146
	v_fmamk_f32 v146, v160, 0x2d800000, v162
	v_or_b32_e32 v175, v177, v176
	v_or_b32_e32 v176, v179, v178
	v_cvt_f32_u32_e32 v171, v174
	v_cvt_f32_u32_e32 v169, v169
	v_ldexp_f32 v167, v170, v167
	v_rsq_f32_e32 v170, v146
	v_or_b32_e32 v146, v149, v148
	v_cvt_f32_u32_e32 v174, v176
	v_cvt_f32_u32_e32 v146, v146
	v_sub_u32_e32 v151, 32, v151
	v_sub_u32_e32 v165, 32, v165
	v_sub_u32_e32 v154, 32, v154
	v_ldexp_f32 v151, v171, v151
	v_ldexp_f32 v165, v169, v165
	v_sub_u32_e32 v148, 32, v182
	v_lshl_or_b32 v176, s47, 8, v155
	v_ldexp_f32 v154, v174, v154
	v_fmamk_f32 v151, v151, 0x2d800000, v162
	v_fmamk_f32 v165, v165, 0x2d800000, v162
	v_ldexp_f32 v146, v146, v148
	v_ashrrev_i32_e32 v177, 31, v176
	v_mov_b64_e32 v[148:149], s[38:39]
	v_fmamk_f32 v169, v154, 0x2d800000, v162
	v_rsq_f32_e32 v160, v151
	v_rsq_f32_e32 v172, v165
	v_add_u32_e32 v165, 0xb0, v150
	v_mad_i64_i32 v[178:179], s[20:21], v150, s37, v[148:149]
	v_lshlrev_b64 v[150:151], 1, v[176:177]
	v_lshl_add_u64 v[176:177], v[178:179], 0, v[150:151]
	v_pk_mul_f32 v[118:119], v[118:119], v[168:169] op_sel_hi:[1,0]
	v_pk_mul_f32 v[120:121], v[120:121], v[168:169] op_sel_hi:[1,0]
	v_pk_mul_f32 v[178:179], v[114:115], v[168:169] op_sel_hi:[1,0]
	v_cvt_pk_bf16_f32 v114, v118, v119
	v_cvt_pk_bf16_f32 v115, v120, v121
	v_pk_mul_f32 v[180:181], v[116:117], v[168:169] op_sel_hi:[1,0]
	v_cvt_pk_bf16_f32 v116, v178, v179
	v_pk_mul_f32 v[118:119], v[122:123], v[168:169] op_sel_hi:[1,0]
	v_cvt_pk_bf16_f32 v117, v180, v181
	global_store_dwordx4 v[176:177], v[114:117], off
	v_pk_mul_f32 v[120:121], v[124:125], v[168:169] op_sel_hi:[1,0]
	v_cvt_f32_u32_e32 v173, v175
	v_pk_mul_f32 v[114:115], v[126:127], v[168:169] op_sel_hi:[1,0]
	v_pk_mul_f32 v[116:117], v[128:129], v[168:169] op_sel_hi:[1,0]
	v_cvt_pk_bf16_f32 v114, v114, v115
	v_pk_mul_f32 v[102:103], v[102:103], v[170:171] op_sel_hi:[1,0]
	v_cvt_pk_bf16_f32 v115, v116, v117
	v_cvt_pk_bf16_f32 v116, v118, v119
	v_cvt_pk_bf16_f32 v117, v120, v121
	global_store_dwordx4 v[176:177], v[114:117], off offset:256
	v_pk_mul_f32 v[104:105], v[104:105], v[170:171] op_sel_hi:[1,0]
	v_pk_mul_f32 v[118:119], v[100:101], v[170:171] op_sel_hi:[1,0]
	v_mad_i64_i32 v[114:115], s[20:21], v166, s37, v[148:149]
	v_lshl_add_u64 v[114:115], v[114:115], 0, v[150:151]
	v_pk_mul_f32 v[116:117], v[98:99], v[170:171] op_sel_hi:[1,0]
	v_cvt_pk_bf16_f32 v98, v102, v103
	v_cvt_pk_bf16_f32 v99, v104, v105
	v_fmamk_f32 v167, v167, 0x2d800000, v162
	v_cvt_pk_bf16_f32 v100, v116, v117
	v_cvt_pk_bf16_f32 v101, v118, v119
	global_store_dwordx4 v[114:115], v[98:101], off
	v_pk_mul_f32 v[102:103], v[106:107], v[170:171] op_sel_hi:[1,0]
	v_pk_mul_f32 v[104:105], v[108:109], v[170:171] op_sel_hi:[1,0]
	v_pk_mul_f32 v[98:99], v[110:111], v[170:171] op_sel_hi:[1,0]
	v_pk_mul_f32 v[100:101], v[112:113], v[170:171] op_sel_hi:[1,0]
	v_cvt_pk_bf16_f32 v98, v98, v99
	v_rsq_f32_e32 v174, v167
	v_cvt_pk_bf16_f32 v99, v100, v101
	v_cvt_pk_bf16_f32 v100, v102, v103
	v_cvt_pk_bf16_f32 v101, v104, v105
	global_store_dwordx4 v[114:115], v[98:101], off offset:256
	v_pk_mul_f32 v[86:87], v[86:87], v[172:173] op_sel_hi:[1,0]
	v_pk_mul_f32 v[88:89], v[88:89], v[172:173] op_sel_hi:[1,0]
	v_mad_i64_i32 v[98:99], s[20:21], v158, s37, v[148:149]
	v_lshl_add_u64 v[98:99], v[98:99], 0, v[150:151]
	v_pk_mul_f32 v[100:101], v[82:83], v[172:173] op_sel_hi:[1,0]
	v_cvt_pk_bf16_f32 v82, v86, v87
	v_cvt_pk_bf16_f32 v83, v88, v89
	v_pk_mul_f32 v[102:103], v[84:85], v[172:173] op_sel_hi:[1,0]
	v_cvt_pk_bf16_f32 v84, v100, v101
	v_pk_mul_f32 v[86:87], v[90:91], v[172:173] op_sel_hi:[1,0]
	v_cvt_pk_bf16_f32 v85, v102, v103
	global_store_dwordx4 v[98:99], v[82:85], off
	v_pk_mul_f32 v[88:89], v[92:93], v[172:173] op_sel_hi:[1,0]
	v_pk_mul_f32 v[70:71], v[70:71], v[174:175] op_sel_hi:[1,0]
	v_pk_mul_f32 v[82:83], v[94:95], v[172:173] op_sel_hi:[1,0]
	v_pk_mul_f32 v[84:85], v[96:97], v[172:173] op_sel_hi:[1,0]
	v_cvt_pk_bf16_f32 v82, v82, v83
; __device__ __forceinline__ unsigned cvt_pk_bf16(float lo, float hi) { unsigned r; asm volatile("v_cvt_pk_bf16_f32 %0, %1, %2" : "=v"(r) : "v"(lo), "v"(hi)); return r; }
; __device__ __forceinline__ unsigned cvt_pk_bf16(float lo, float hi) { unsigned r; asm volatile("v_cvt_pk_bf16_f32 %0, %1, %2" : "=v"(r) : "v"(lo), "v"(hi)); return r; }
; #define PG8_BAR __builtin_amdgcn_s_barrier()
;     __device__ __forceinline__ void operator()(const f32x4 (&acc)[2][2][4][2], const Unit& u, int wr, int wc, int fr, int fq) const {
;     ...
;             for (int m = 0; m < 4; ++m) { const int row = row0 + ai * HALF + m * 16; bf16_t* rowp = O + (size_t)row * ldc + col0;
; #pragma unroll
;                 for (int bj = 0; bj < 2; ++bj) { const f32x2 r2 = {rs[ai][m], rs[ai][m]}; const f32x4 a0 = acc[ai][bj][m][0], a1 = acc[ai][bj][m][1];
;                     const f32x2 p0 = (f32x2){a0[0], a0[1]} * r2, p1 = (f32x2){a0[2], a0[3]} * r2, p2 = (f32x2){a1[0], a1[1]} * r2, p3 = (f32x2){a1[2], a1[3]} * r2;
;                     u32x4 w; w.x = cvt_pk_bf16(p0.x, p0.y); w.y = cvt_pk_bf16(p1.x, p1.y); w.z = cvt_pk_bf16(p2.x, p2.y); w.w = cvt_pk_bf16(p3.x, p3.y);
;                     *(u32x4*)(rowp + bj * HALF) = w; } }
; template <class Epi, class Sched, bool ALIGN_EPI = false, bool SP2 = false>
; __device__ __forceinline__ void gemm_phase(PG8_LAS unsigned char* lds, const Gemm g, const Sched& S, const Epi& E) {
;     ...
; #pragma unroll
;         for (int a = 0; a < 2; ++a)
; #pragma unroll
;             for (int b = 0; b < 2; ++b)
; #pragma unroll
;                 for (int m = 0; m < 4; ++m)
; #pragma unroll
;                     for (int n = 0; n < 2; ++n) { d64x2 z_; asm volatile("v_mov_b64 %0, 0\n\tv_mov_b64 %1, 0" : "=v"(z_.x), "=v"(z_.y)); acc[a][b][m][n] = __builtin_bit_cast(f32x4, z_); }
;         cur = nxt; cA = nA; cB = nB; ++ui;
;         if constexpr (ALIGN_EPI) { if (wr == 1) PG8_BAR; }
	v_pk_mul_f32 v[72:73], v[72:73], v[174:175] op_sel_hi:[1,0]
	v_cvt_pk_bf16_f32 v83, v84, v85
	v_cvt_pk_bf16_f32 v84, v86, v87
	v_cvt_pk_bf16_f32 v85, v88, v89
	global_store_dwordx4 v[98:99], v[82:85], off offset:256
	v_sub_u32_e32 v152, 32, v152
	v_pk_mul_f32 v[86:87], v[68:69], v[174:175] op_sel_hi:[1,0]
	v_mad_i64_i32 v[82:83], s[20:21], v156, s37, v[148:149]
	v_lshl_add_u64 v[82:83], v[82:83], 0, v[150:151]
	v_pk_mul_f32 v[84:85], v[66:67], v[174:175] op_sel_hi:[1,0]
	v_cvt_pk_bf16_f32 v66, v70, v71
	v_cvt_pk_bf16_f32 v67, v72, v73
	v_ldexp_f32 v152, v173, v152
	v_cvt_pk_bf16_f32 v68, v84, v85
	v_cvt_pk_bf16_f32 v69, v86, v87
	global_store_dwordx4 v[82:83], v[66:69], off
	v_fmamk_f32 v152, v152, 0x2d800000, v162
	v_pk_mul_f32 v[70:71], v[74:75], v[174:175] op_sel_hi:[1,0]
	v_pk_mul_f32 v[66:67], v[78:79], v[174:175] op_sel_hi:[1,0]
	v_pk_mul_f32 v[68:69], v[80:81], v[174:175] op_sel_hi:[1,0]
	v_cvt_pk_bf16_f32 v66, v66, v67
	v_pk_mul_f32 v[72:73], v[76:77], v[174:175] op_sel_hi:[1,0]
	v_cvt_pk_bf16_f32 v67, v68, v69
	v_cvt_pk_bf16_f32 v68, v70, v71
	v_rsq_f32_e32 v154, v152
	v_cvt_pk_bf16_f32 v69, v72, v73
	global_store_dwordx4 v[82:83], v[66:69], off offset:256
	v_pk_mul_f32 v[54:55], v[54:55], v[160:161] op_sel_hi:[1,0]
	v_pk_mul_f32 v[56:57], v[56:57], v[160:161] op_sel_hi:[1,0]
	v_mad_i64_i32 v[66:67], s[20:21], v157, s37, v[148:149]
	v_lshl_add_u64 v[66:67], v[66:67], 0, v[150:151]
	v_pk_mul_f32 v[68:69], v[50:51], v[160:161] op_sel_hi:[1,0]
	v_cvt_pk_bf16_f32 v50, v54, v55
	v_cvt_pk_bf16_f32 v51, v56, v57
	v_pk_mul_f32 v[70:71], v[52:53], v[160:161] op_sel_hi:[1,0]
	v_cvt_pk_bf16_f32 v52, v68, v69
	v_pk_mul_f32 v[54:55], v[58:59], v[160:161] op_sel_hi:[1,0]
	v_cvt_pk_bf16_f32 v53, v70, v71
	global_store_dwordx4 v[66:67], v[50:53], off
	v_pk_mul_f32 v[56:57], v[60:61], v[160:161] op_sel_hi:[1,0]
	v_rsq_f32_e32 v152, v169
	v_pk_mul_f32 v[50:51], v[62:63], v[160:161] op_sel_hi:[1,0]
	v_pk_mul_f32 v[52:53], v[64:65], v[160:161] op_sel_hi:[1,0]
	v_cvt_pk_bf16_f32 v50, v50, v51
	v_pk_mul_f32 v[38:39], v[38:39], v[154:155] op_sel_hi:[1,0]
	v_cvt_pk_bf16_f32 v51, v52, v53
	v_cvt_pk_bf16_f32 v52, v54, v55
	v_cvt_pk_bf16_f32 v53, v56, v57
	global_store_dwordx4 v[66:67], v[50:53], off offset:256
	v_pk_mul_f32 v[40:41], v[40:41], v[154:155] op_sel_hi:[1,0]
	v_pk_mul_f32 v[54:55], v[36:37], v[154:155] op_sel_hi:[1,0]
	v_mad_i64_i32 v[50:51], s[20:21], v159, s37, v[148:149]
	v_lshl_add_u64 v[50:51], v[50:51], 0, v[150:151]
	v_pk_mul_f32 v[52:53], v[34:35], v[154:155] op_sel_hi:[1,0]
	v_cvt_pk_bf16_f32 v34, v38, v39
	v_cvt_pk_bf16_f32 v35, v40, v41
	v_fmamk_f32 v146, v146, 0x2d800000, v162
	v_cvt_pk_bf16_f32 v36, v52, v53
	v_cvt_pk_bf16_f32 v37, v54, v55
	global_store_dwordx4 v[50:51], v[34:37], off
	v_pk_mul_f32 v[38:39], v[42:43], v[154:155] op_sel_hi:[1,0]
	v_pk_mul_f32 v[40:41], v[44:45], v[154:155] op_sel_hi:[1,0]
	v_pk_mul_f32 v[34:35], v[46:47], v[154:155] op_sel_hi:[1,0]
	v_pk_mul_f32 v[36:37], v[48:49], v[154:155] op_sel_hi:[1,0]
	v_cvt_pk_bf16_f32 v34, v34, v35
	v_rsq_f32_e32 v146, v146
	v_cvt_pk_bf16_f32 v35, v36, v37
	v_cvt_pk_bf16_f32 v36, v38, v39
	v_cvt_pk_bf16_f32 v37, v40, v41
	global_store_dwordx4 v[50:51], v[34:37], off offset:256
	v_pk_mul_f32 v[22:23], v[22:23], v[152:153] op_sel_hi:[1,0]
	v_pk_mul_f32 v[24:25], v[24:25], v[152:153] op_sel_hi:[1,0]
	v_mad_i64_i32 v[34:35], s[20:21], v163, s37, v[148:149]
	v_lshl_add_u64 v[34:35], v[34:35], 0, v[150:151]
	v_pk_mul_f32 v[36:37], v[18:19], v[152:153] op_sel_hi:[1,0]
	v_cvt_pk_bf16_f32 v18, v22, v23
	v_cvt_pk_bf16_f32 v19, v24, v25
	v_pk_mul_f32 v[38:39], v[20:21], v[152:153] op_sel_hi:[1,0]
	v_cvt_pk_bf16_f32 v20, v36, v37
	v_pk_mul_f32 v[22:23], v[26:27], v[152:153] op_sel_hi:[1,0]
	v_cvt_pk_bf16_f32 v21, v38, v39
	global_store_dwordx4 v[34:35], v[18:21], off
	v_pk_mul_f32 v[24:25], v[28:29], v[152:153] op_sel_hi:[1,0]
	v_pk_mul_f32 v[6:7], v[6:7], v[146:147] op_sel_hi:[1,0]
	v_pk_mul_f32 v[18:19], v[30:31], v[152:153] op_sel_hi:[1,0]
	v_pk_mul_f32 v[20:21], v[32:33], v[152:153] op_sel_hi:[1,0]
	v_cvt_pk_bf16_f32 v18, v18, v19
	v_pk_mul_f32 v[8:9], v[8:9], v[146:147] op_sel_hi:[1,0]
	v_cvt_pk_bf16_f32 v19, v20, v21
	v_cvt_pk_bf16_f32 v20, v22, v23
	v_cvt_pk_bf16_f32 v21, v24, v25
	global_store_dwordx4 v[34:35], v[18:21], off offset:256
	v_pk_mul_f32 v[22:23], v[4:5], v[146:147] op_sel_hi:[1,0]
	s_nop 0
	v_mad_i64_i32 v[18:19], s[20:21], v165, s37, v[148:149]
	v_lshl_add_u64 v[18:19], v[18:19], 0, v[150:151]
	v_pk_mul_f32 v[20:21], v[2:3], v[146:147] op_sel_hi:[1,0]
	v_cvt_pk_bf16_f32 v2, v6, v7
	v_cvt_pk_bf16_f32 v3, v8, v9
	v_pk_mul_f32 v[6:7], v[14:15], v[146:147] op_sel_hi:[1,0]
	v_cvt_pk_bf16_f32 v4, v20, v21
	v_cvt_pk_bf16_f32 v5, v22, v23
	global_store_dwordx4 v[18:19], v[2:5], off
	v_pk_mul_f32 v[8:9], v[16:17], v[146:147] op_sel_hi:[1,0]
	s_nop 0
	v_pk_mul_f32 v[2:3], v[10:11], v[146:147] op_sel_hi:[1,0]
	v_pk_mul_f32 v[4:5], v[12:13], v[146:147] op_sel_hi:[1,0]
	v_cvt_pk_bf16_f32 v2, v2, v3
	s_nop 0
	v_cvt_pk_bf16_f32 v3, v4, v5
	v_cvt_pk_bf16_f32 v4, v6, v7
	v_cvt_pk_bf16_f32 v5, v8, v9
	global_store_dwordx4 v[18:19], v[2:5], off offset:256
	s_cbranch_vccnz .LBB0_669
	s_andn2_b64 vcc, exec, s[4:5]
	v_mov_b64 v[118:119], 0
	v_mov_b64 v[120:121], 0
	v_mov_b64 v[114:115], 0
	v_mov_b64 v[116:117], 0
	v_mov_b64 v[102:103], 0
	v_mov_b64 v[104:105], 0
	v_mov_b64 v[98:99], 0
	v_mov_b64 v[100:101], 0
	v_mov_b64 v[86:87], 0
	v_mov_b64 v[88:89], 0
	v_mov_b64 v[82:83], 0
	v_mov_b64 v[84:85], 0
	v_mov_b64 v[70:71], 0
	v_mov_b64 v[72:73], 0
	v_mov_b64 v[66:67], 0
	v_mov_b64 v[68:69], 0
	v_mov_b64 v[126:127], 0
	v_mov_b64 v[128:129], 0
	v_mov_b64 v[122:123], 0
	v_mov_b64 v[124:125], 0
	v_mov_b64 v[110:111], 0
	v_mov_b64 v[112:113], 0
	v_mov_b64 v[106:107], 0
	v_mov_b64 v[108:109], 0
	v_mov_b64 v[94:95], 0
	v_mov_b64 v[96:97], 0
	v_mov_b64 v[90:91], 0
	v_mov_b64 v[92:93], 0
	v_mov_b64 v[78:79], 0
	v_mov_b64 v[80:81], 0
	v_mov_b64 v[74:75], 0
	v_mov_b64 v[76:77], 0
	v_mov_b64 v[54:55], 0
	v_mov_b64 v[56:57], 0
	v_mov_b64 v[50:51], 0
	v_mov_b64 v[52:53], 0
	v_mov_b64 v[38:39], 0
	v_mov_b64 v[40:41], 0
	v_mov_b64 v[34:35], 0
	v_mov_b64 v[36:37], 0
	v_mov_b64 v[22:23], 0
	v_mov_b64 v[24:25], 0
	v_mov_b64 v[18:19], 0
	v_mov_b64 v[20:21], 0
	v_mov_b64 v[6:7], 0
	v_mov_b64 v[8:9], 0
	v_mov_b64 v[2:3], 0
	v_mov_b64 v[4:5], 0
	v_mov_b64 v[62:63], 0
	v_mov_b64 v[64:65], 0
	v_mov_b64 v[58:59], 0
	v_mov_b64 v[60:61], 0
	v_mov_b64 v[46:47], 0
	v_mov_b64 v[48:49], 0
	v_mov_b64 v[42:43], 0
	v_mov_b64 v[44:45], 0
	v_mov_b64 v[30:31], 0
	v_mov_b64 v[32:33], 0
	v_mov_b64 v[26:27], 0
	v_mov_b64 v[28:29], 0
	v_mov_b64 v[10:11], 0
	v_mov_b64 v[12:13], 0
	v_mov_b64 v[14:15], 0
	v_mov_b64 v[16:17], 0
	s_cbranch_vccnz .LBB0_668
	s_barrier
	s_branch .LBB0_668

; #define PG8_STAGE(bufoff, gbase, voff) do { _Pragma("unroll") for (int _i = 0; _i < 2; ++_i) \
;         __builtin_amdgcn_global_load_lds((const unsigned*)((const char*)(gbase) + (voff)[_i]), (PG8_LAS unsigned*)(lds + (bufoff) + ldsw + _i * 8192), 16, 0, 0); } while (0)
; #define PG8_LDA(dst, b, h) do { _Pragma("unroll") for (int m = 0; m < 4; ++m) _Pragma("unroll") for (int k = 0; k < 2; ++k) dst[m][k] = *(const PG8_LAS bf16x8*)(lds + PG8_SA(b, h) + aoff + m * 2048 + k * 1024); } while (0)
; #define PG8_LDB(dst, b, h) do { _Pragma("unroll") for (int n = 0; n < 2; ++n) _Pragma("unroll") for (int k = 0; k < 2; ++k) dst[n][k] = *(const PG8_LAS bf16x8*)(lds + PG8_SB(b, h) + boff + n * 2048 + k * 1024); } while (0)
; #define PG8_MMA(ai, bj, At, Bt) do { __builtin_amdgcn_s_setprio(1); _Pragma("unroll") for (int m = 0; m < 4; ++m) _Pragma("unroll") for (int n = 0; n < 2; ++n) _Pragma("unroll") for (int k = 0; k < 2; ++k) \
;         acc[ai][bj][m][n] = __builtin_amdgcn_mfma_f32_16x16x32_bf16(Bt[n][k], At[m][k], acc[ai][bj][m][n], 0, 0, 0); __builtin_amdgcn_s_setprio(0); } while (0)
; #define PG8_WAIT_V(n) asm volatile("s_waitcnt vmcnt(" #n ")" ::: "memory")
; #define PG8_WAIT_L(n) asm volatile("s_waitcnt lgkmcnt(" #n ")" ::: "memory")
; #define PG8_BAR __builtin_amdgcn_s_barrier()
; #define PG8_SCHED __builtin_amdgcn_sched_barrier(0)
; template <class Epi, class Sched, bool ALIGN_EPI = false, bool SP2 = false>
; __device__ __forceinline__ void gemm_phase(PG8_LAS unsigned char* lds, const Gemm g, const Sched& S, const Epi& E) {
;     ...
;             PG8_LDB(B0, 0, 0); PG8_LDB(B1, 0, 1); PG8_SCHED; PG8_LDA(At, 0, 0); PG8_STAGE(PG8_SA(1, 1), a1 + hstep, voffA);
;             PG8_WAIT_V(8); PG8_WAIT_L(0); PG8_BAR; PG8_MMA(0, 0, At, B0); PG8_MMA(0, 1, At, B1); PG8_BAR; PG8_SCHED;
;             PG8_LDA(At, 0, 1); PG8_STAGE(PG8_SB(0, 0), b2, voffB); PG8_STAGE(PG8_SB(0, 1), b2 + hstep, voffB); PG8_STAGE(PG8_SA(0, 0), a2, voffA);
;             PG8_WAIT_V(8); PG8_WAIT_L(0); PG8_BAR; PG8_MMA(1, 0, At, B0); PG8_MMA(1, 1, At, B1); PG8_BAR; PG8_SCHED;
.LBB0_1126:
	ds_read_b128 v[160:163], v241 offset:0
	ds_read_b128 v[166:169], v241 offset:1024
	ds_read_b128 v[170:173], v241 offset:2048
	ds_read_b128 v[174:177], v241 offset:3072
	ds_read_b128 v[178:181], v241 offset:16384
	ds_read_b128 v[182:185], v241 offset:17408
	ds_read_b128 v[186:189], v241 offset:18432
	ds_read_b128 v[190:193], v241 offset:19456
	s_add_u32 s22, s24, 0xfff00080
	s_addc_u32 s23, s25, -1
	s_cmp_eq_u32 s68, 60
	s_cselect_b32 s27, s15, s23
	s_cselect_b32 s26, s64, s22
	s_cselect_b32 s23, s13, s67
	s_cselect_b32 s22, s65, s66
	s_add_i32 m0, s21, 0xc000
	ds_read_b128 v[194:197], v155
	ds_read_b128 v[198:201], v155 offset:1024
	ds_read_b128 v[202:205], v155 offset:2048
	ds_read_b128 v[206:209], v155 offset:3072
	ds_read_b128 v[210:213], v155 offset:4096
	ds_read_b128 v[214:217], v155 offset:5120
	ds_read_b128 v[218:221], v155 offset:6144
	ds_read_b128 v[222:225], v155 offset:7168
	global_load_lds_dwordx4 v138, s[24:25]
	s_add_i32 m0, s21, 0xe000
	s_nop 0
	global_load_lds_dwordx4 v140, s[24:25]
	s_waitcnt vmcnt(8)
	s_waitcnt lgkmcnt(0)
	s_barrier
	s_waitcnt lgkmcnt(0)
	v_mfma_f32_16x16x32_bf16 v[122:125], v[160:163], v[194:197], v[122:125]
	v_mfma_f32_16x16x32_bf16 v[122:125], v[166:169], v[198:201], v[122:125]
	v_mfma_f32_16x16x32_bf16 v[106:109], v[166:169], v[206:209], v[106:109]
	v_mfma_f32_16x16x32_bf16 v[106:109], v[160:163], v[202:205], v[106:109]
	v_mfma_f32_16x16x32_bf16 v[90:93], v[160:163], v[210:213], v[90:93]
	v_mfma_f32_16x16x32_bf16 v[90:93], v[166:169], v[214:217], v[90:93]
	v_mfma_f32_16x16x32_bf16 v[74:77], v[166:169], v[222:225], v[74:77]
	v_mfma_f32_16x16x32_bf16 v[74:77], v[160:163], v[218:221], v[74:77]
	v_mfma_f32_16x16x32_bf16 v[62:65], v[170:173], v[218:221], v[62:65]
	v_mfma_f32_16x16x32_bf16 v[62:65], v[174:177], v[222:225], v[62:65]
	v_mfma_f32_16x16x32_bf16 v[82:85], v[174:177], v[214:217], v[82:85]
	v_mfma_f32_16x16x32_bf16 v[82:85], v[170:173], v[210:213], v[82:85]
	v_mfma_f32_16x16x32_bf16 v[98:101], v[170:173], v[202:205], v[98:101]
	v_mfma_f32_16x16x32_bf16 v[98:101], v[174:177], v[206:209], v[98:101]
	v_mfma_f32_16x16x32_bf16 v[114:117], v[174:177], v[198:201], v[114:117]
	v_mfma_f32_16x16x32_bf16 v[114:117], v[170:173], v[194:197], v[114:117]
	v_mfma_f32_16x16x32_bf16 v[126:129], v[178:181], v[194:197], v[126:129]
	v_mfma_f32_16x16x32_bf16 v[126:129], v[182:185], v[198:201], v[126:129]
	v_mfma_f32_16x16x32_bf16 v[110:113], v[182:185], v[206:209], v[110:113]
	v_mfma_f32_16x16x32_bf16 v[110:113], v[178:181], v[202:205], v[110:113]
	v_mfma_f32_16x16x32_bf16 v[94:97], v[178:181], v[210:213], v[94:97]
	v_mfma_f32_16x16x32_bf16 v[94:97], v[182:185], v[214:217], v[94:97]
	v_mfma_f32_16x16x32_bf16 v[78:81], v[182:185], v[222:225], v[78:81]
	v_mfma_f32_16x16x32_bf16 v[78:81], v[178:181], v[218:221], v[78:81]
	v_mfma_f32_16x16x32_bf16 v[70:73], v[186:189], v[218:221], v[70:73]
	v_mfma_f32_16x16x32_bf16 v[70:73], v[190:193], v[222:225], v[70:73]
	v_mfma_f32_16x16x32_bf16 v[86:89], v[190:193], v[214:217], v[86:89]
	v_mfma_f32_16x16x32_bf16 v[86:89], v[186:189], v[210:213], v[86:89]
	v_mfma_f32_16x16x32_bf16 v[102:105], v[186:189], v[202:205], v[102:105]
	v_mfma_f32_16x16x32_bf16 v[102:105], v[190:193], v[206:209], v[102:105]
	v_mfma_f32_16x16x32_bf16 v[118:121], v[190:193], v[198:201], v[118:121]
	v_mfma_f32_16x16x32_bf16 v[118:121], v[186:189], v[194:197], v[118:121]
	s_barrier
	s_add_i32 s33, s52, s29
	s_mov_b32 m0, s33
	ds_read_b128 v[194:197], v155 offset:16384
	ds_read_b128 v[198:201], v155 offset:17408
	ds_read_b128 v[202:205], v155 offset:18432
	ds_read_b128 v[206:209], v155 offset:19456
	ds_read_b128 v[210:213], v155 offset:20480
	ds_read_b128 v[214:217], v155 offset:21504
	ds_read_b128 v[218:221], v155 offset:22528
	ds_read_b128 v[222:225], v155 offset:23552
	global_load_lds_dwordx4 v132, s[22:23]
	s_add_i32 m0, s33, 0x2000
	s_add_u32 s72, s22, 0x100000
	s_addc_u32 s73, s23, 0
	s_add_i32 s33, s53, s29
	global_load_lds_dwordx4 v136, s[22:23]
	s_mov_b32 m0, s33
	s_add_u32 s100, s26, 0x80
	s_addc_u32 s101, s27, 0
	global_load_lds_dwordx4 v132, s[72:73]
	s_add_i32 m0, s33, 0x2000
	s_nop 0
	global_load_lds_dwordx4 v136, s[72:73]
	s_mov_b32 m0, s21
	s_nop 0
	global_load_lds_dwordx4 v130, s[26:27]
	s_mov_b32 m0, s36
	s_nop 0
	global_load_lds_dwordx4 v134, s[26:27]
	s_waitcnt vmcnt(8)
	s_waitcnt lgkmcnt(0)
	s_barrier
	s_waitcnt lgkmcnt(0)
	v_mfma_f32_16x16x32_bf16 v[58:61], v[160:163], v[194:197], v[58:61]
	v_mfma_f32_16x16x32_bf16 v[58:61], v[166:169], v[198:201], v[58:61]
	v_mfma_f32_16x16x32_bf16 v[42:45], v[166:169], v[206:209], v[42:45]
	v_mfma_f32_16x16x32_bf16 v[42:45], v[160:163], v[202:205], v[42:45]
	v_mfma_f32_16x16x32_bf16 v[26:29], v[160:163], v[210:213], v[26:29]
	v_mfma_f32_16x16x32_bf16 v[26:29], v[166:169], v[214:217], v[26:29]
	v_mfma_f32_16x16x32_bf16 v[10:13], v[166:169], v[222:225], v[10:13]
	v_mfma_f32_16x16x32_bf16 v[10:13], v[160:163], v[218:221], v[10:13]
	v_mfma_f32_16x16x32_bf16 v[2:5], v[170:173], v[218:221], v[2:5]
	v_mfma_f32_16x16x32_bf16 v[2:5], v[174:177], v[222:225], v[2:5]
	v_mfma_f32_16x16x32_bf16 v[18:21], v[174:177], v[214:217], v[18:21]
	v_mfma_f32_16x16x32_bf16 v[18:21], v[170:173], v[210:213], v[18:21]
	v_mfma_f32_16x16x32_bf16 v[34:37], v[170:173], v[202:205], v[34:37]
	v_mfma_f32_16x16x32_bf16 v[34:37], v[174:177], v[206:209], v[34:37]
	v_mfma_f32_16x16x32_bf16 v[50:53], v[174:177], v[198:201], v[50:53]
	v_mfma_f32_16x16x32_bf16 v[50:53], v[170:173], v[194:197], v[50:53]
	v_mfma_f32_16x16x32_bf16 v[66:69], v[178:181], v[194:197], v[66:69]
	v_mfma_f32_16x16x32_bf16 v[66:69], v[182:185], v[198:201], v[66:69]
	v_mfma_f32_16x16x32_bf16 v[46:49], v[182:185], v[206:209], v[46:49]
	v_mfma_f32_16x16x32_bf16 v[46:49], v[178:181], v[202:205], v[46:49]
	v_mfma_f32_16x16x32_bf16 v[30:33], v[178:181], v[210:213], v[30:33]
	v_mfma_f32_16x16x32_bf16 v[30:33], v[182:185], v[214:217], v[30:33]
	v_mfma_f32_16x16x32_bf16 v[14:17], v[182:185], v[222:225], v[14:17]
	v_mfma_f32_16x16x32_bf16 v[14:17], v[178:181], v[218:221], v[14:17]
	v_mfma_f32_16x16x32_bf16 v[6:9], v[186:189], v[218:221], v[6:9]
	v_mfma_f32_16x16x32_bf16 v[6:9], v[190:193], v[222:225], v[6:9]
	v_mfma_f32_16x16x32_bf16 v[22:25], v[190:193], v[214:217], v[22:25]
	v_mfma_f32_16x16x32_bf16 v[22:25], v[186:189], v[210:213], v[22:25]
	v_mfma_f32_16x16x32_bf16 v[38:41], v[186:189], v[202:205], v[38:41]
	v_mfma_f32_16x16x32_bf16 v[38:41], v[190:193], v[206:209], v[38:41]
	v_mfma_f32_16x16x32_bf16 v[54:57], v[190:193], v[198:201], v[54:57]
	v_mfma_f32_16x16x32_bf16 v[54:57], v[186:189], v[194:197], v[54:57]
	s_barrier
; #define PG8_STAGE(bufoff, gbase, voff) do { _Pragma("unroll") for (int _i = 0; _i < 2; ++_i) \
;         __builtin_amdgcn_global_load_lds((const unsigned*)((const char*)(gbase) + (voff)[_i]), (PG8_LAS unsigned*)(lds + (bufoff) + ldsw + _i * 8192), 16, 0, 0); } while (0)
; #define PG8_LDA(dst, b, h) do { _Pragma("unroll") for (int m = 0; m < 4; ++m) _Pragma("unroll") for (int k = 0; k < 2; ++k) dst[m][k] = *(const PG8_LAS bf16x8*)(lds + PG8_SA(b, h) + aoff + m * 2048 + k * 1024); } while (0)
; #define PG8_LDB(dst, b, h) do { _Pragma("unroll") for (int n = 0; n < 2; ++n) _Pragma("unroll") for (int k = 0; k < 2; ++k) dst[n][k] = *(const PG8_LAS bf16x8*)(lds + PG8_SB(b, h) + boff + n * 2048 + k * 1024); } while (0)
; #define PG8_MMA(ai, bj, At, Bt) do { __builtin_amdgcn_s_setprio(1); _Pragma("unroll") for (int m = 0; m < 4; ++m) _Pragma("unroll") for (int n = 0; n < 2; ++n) _Pragma("unroll") for (int k = 0; k < 2; ++k) \
;         acc[ai][bj][m][n] = __builtin_amdgcn_mfma_f32_16x16x32_bf16(Bt[n][k], At[m][k], acc[ai][bj][m][n], 0, 0, 0); __builtin_amdgcn_s_setprio(0); } while (0)
; #define PG8_WAIT_V(n) asm volatile("s_waitcnt vmcnt(" #n ")" ::: "memory")
; #define PG8_WAIT_L(n) asm volatile("s_waitcnt lgkmcnt(" #n ")" ::: "memory")
; #define PG8_BAR __builtin_amdgcn_s_barrier()
; #define PG8_SCHED __builtin_amdgcn_sched_barrier(0)
; template <class Epi, class Sched, bool ALIGN_EPI = false, bool SP2 = false>
; __device__ __forceinline__ void gemm_phase(PG8_LAS unsigned char* lds, const Gemm g, const Sched& S, const Epi& E) {
;     ...
;             PG8_LDB(B0, 1, 0); PG8_LDB(B1, 1, 1); PG8_SCHED; PG8_LDA(At, 1, 0); PG8_STAGE(PG8_SA(0, 1), a2 + hstep, voffA);
;             PG8_WAIT_V(8); PG8_WAIT_L(0); PG8_BAR; PG8_MMA(0, 0, At, B0); PG8_MMA(0, 1, At, B1); PG8_BAR; PG8_SCHED;
;             PG8_LDA(At, 1, 1); PG8_STAGE(PG8_SB(1, 0), b3, voffB); PG8_STAGE(PG8_SB(1, 1), b3 + hstep, voffB); PG8_STAGE(PG8_SA(1, 0), a3, voffA);
;             PG8_WAIT_V(8); PG8_WAIT_L(0); PG8_BAR; PG8_MMA(1, 0, At, B0); PG8_MMA(1, 1, At, B1); PG8_BAR; PG8_SCHED;
	s_add_i32 s33, 0, 0x18000
	s_add_i32 s42, 0, 0x1c000
	ds_read_b128 v[160:163], v241 offset:32768
	ds_read_b128 v[166:169], v241 offset:33792
	ds_read_b128 v[170:173], v241 offset:34816
	ds_read_b128 v[174:177], v241 offset:35840
	ds_read_b128 v[178:181], v241 offset:49152
	ds_read_b128 v[182:185], v241 offset:50176
	ds_read_b128 v[186:189], v241 offset:51200
	ds_read_b128 v[190:193], v241 offset:52224
	s_add_u32 s26, s26, 0x100000
	s_addc_u32 s27, s27, 0
	s_mov_b32 m0, s37
	ds_read_b128 v[194:197], v155 offset:32768
	ds_read_b128 v[198:201], v155 offset:33792
	ds_read_b128 v[202:205], v155 offset:34816
	ds_read_b128 v[206:209], v155 offset:35840
	ds_read_b128 v[210:213], v155 offset:36864
	ds_read_b128 v[214:217], v155 offset:37888
	ds_read_b128 v[218:221], v155 offset:38912
	ds_read_b128 v[222:225], v155 offset:39936
	global_load_lds_dwordx4 v130, s[26:27]
	s_mov_b32 m0, s40
	s_nop 0
	global_load_lds_dwordx4 v134, s[26:27]
	s_waitcnt vmcnt(8)
	s_waitcnt lgkmcnt(0)
	s_barrier
	s_waitcnt lgkmcnt(0)
	v_mfma_f32_16x16x32_bf16 v[122:125], v[160:163], v[194:197], v[122:125]
	v_mfma_f32_16x16x32_bf16 v[122:125], v[166:169], v[198:201], v[122:125]
	v_mfma_f32_16x16x32_bf16 v[106:109], v[166:169], v[206:209], v[106:109]
	v_mfma_f32_16x16x32_bf16 v[106:109], v[160:163], v[202:205], v[106:109]
	v_mfma_f32_16x16x32_bf16 v[90:93], v[160:163], v[210:213], v[90:93]
	v_mfma_f32_16x16x32_bf16 v[90:93], v[166:169], v[214:217], v[90:93]
	v_mfma_f32_16x16x32_bf16 v[74:77], v[166:169], v[222:225], v[74:77]
	v_mfma_f32_16x16x32_bf16 v[74:77], v[160:163], v[218:221], v[74:77]
	v_mfma_f32_16x16x32_bf16 v[62:65], v[170:173], v[218:221], v[62:65]
	v_mfma_f32_16x16x32_bf16 v[62:65], v[174:177], v[222:225], v[62:65]
	v_mfma_f32_16x16x32_bf16 v[82:85], v[174:177], v[214:217], v[82:85]
	v_mfma_f32_16x16x32_bf16 v[82:85], v[170:173], v[210:213], v[82:85]
	v_mfma_f32_16x16x32_bf16 v[98:101], v[170:173], v[202:205], v[98:101]
	v_mfma_f32_16x16x32_bf16 v[98:101], v[174:177], v[206:209], v[98:101]
	v_mfma_f32_16x16x32_bf16 v[114:117], v[174:177], v[198:201], v[114:117]
	v_mfma_f32_16x16x32_bf16 v[114:117], v[170:173], v[194:197], v[114:117]
	v_mfma_f32_16x16x32_bf16 v[126:129], v[178:181], v[194:197], v[126:129]
	v_mfma_f32_16x16x32_bf16 v[126:129], v[182:185], v[198:201], v[126:129]
	v_mfma_f32_16x16x32_bf16 v[110:113], v[182:185], v[206:209], v[110:113]
	v_mfma_f32_16x16x32_bf16 v[110:113], v[178:181], v[202:205], v[110:113]
	v_mfma_f32_16x16x32_bf16 v[94:97], v[178:181], v[210:213], v[94:97]
	v_mfma_f32_16x16x32_bf16 v[94:97], v[182:185], v[214:217], v[94:97]
	v_mfma_f32_16x16x32_bf16 v[78:81], v[182:185], v[222:225], v[78:81]
	v_mfma_f32_16x16x32_bf16 v[78:81], v[178:181], v[218:221], v[78:81]
	v_mfma_f32_16x16x32_bf16 v[70:73], v[186:189], v[218:221], v[70:73]
	v_mfma_f32_16x16x32_bf16 v[70:73], v[190:193], v[222:225], v[70:73]
	v_mfma_f32_16x16x32_bf16 v[86:89], v[190:193], v[214:217], v[86:89]
	v_mfma_f32_16x16x32_bf16 v[86:89], v[186:189], v[210:213], v[86:89]
	v_mfma_f32_16x16x32_bf16 v[102:105], v[186:189], v[202:205], v[102:105]
	v_mfma_f32_16x16x32_bf16 v[102:105], v[190:193], v[206:209], v[102:105]
	v_mfma_f32_16x16x32_bf16 v[118:121], v[190:193], v[198:201], v[118:121]
	v_mfma_f32_16x16x32_bf16 v[118:121], v[186:189], v[194:197], v[118:121]
	s_barrier
	s_add_i32 s26, s33, s29
	s_add_i32 m0, s26, 0xffffff80
	ds_read_b128 v[194:197], v155 offset:49152
	ds_read_b128 v[198:201], v155 offset:50176
	ds_read_b128 v[202:205], v155 offset:51200
	ds_read_b128 v[206:209], v155 offset:52224
	ds_read_b128 v[210:213], v155 offset:53248
	ds_read_b128 v[214:217], v155 offset:54272
	ds_read_b128 v[218:221], v155 offset:55296
	ds_read_b128 v[222:225], v155 offset:56320
	global_load_lds_dwordx4 v132, s[22:23] offset:128
	s_add_i32 m0, s26, 0x1f80
	s_add_i32 s26, s42, s29
	global_load_lds_dwordx4 v136, s[22:23] offset:128
	s_add_u32 s22, s22, 0x100080
	s_addc_u32 s23, s23, 0
	s_mov_b32 m0, s26
	s_nop 0
	global_load_lds_dwordx4 v132, s[22:23]
	s_add_i32 m0, s26, 0x2000
	s_nop 0
	global_load_lds_dwordx4 v136, s[22:23]
	s_mov_b32 m0, s46
	s_nop 0
	global_load_lds_dwordx4 v130, s[100:101]
	s_mov_b32 m0, s47
	s_nop 0
	global_load_lds_dwordx4 v134, s[100:101]
	s_waitcnt vmcnt(8)
	s_waitcnt lgkmcnt(0)
	s_barrier
; __device__ __forceinline__ float ssq_rstd(const ssq_t* ssq, int row) { return __builtin_amdgcn_rsqf((float)ssq[row] * (SSQ_UNFIX * RMS_INV_D) + RMS_EPS); }
; #define PG8_STAGE(bufoff, gbase, voff) do { _Pragma("unroll") for (int _i = 0; _i < 2; ++_i) \
;         __builtin_amdgcn_global_load_lds((const unsigned*)((const char*)(gbase) + (voff)[_i]), (PG8_LAS unsigned*)(lds + (bufoff) + ldsw + _i * 8192), 16, 0, 0); } while (0)
; #define PG8_LDA(dst, b, h) do { _Pragma("unroll") for (int m = 0; m < 4; ++m) _Pragma("unroll") for (int k = 0; k < 2; ++k) dst[m][k] = *(const PG8_LAS bf16x8*)(lds + PG8_SA(b, h) + aoff + m * 2048 + k * 1024); } while (0)
; #define PG8_MMA(ai, bj, At, Bt) do { __builtin_amdgcn_s_setprio(1); _Pragma("unroll") for (int m = 0; m < 4; ++m) _Pragma("unroll") for (int n = 0; n < 2; ++n) _Pragma("unroll") for (int k = 0; k < 2; ++k) \
;         acc[ai][bj][m][n] = __builtin_amdgcn_mfma_f32_16x16x32_bf16(Bt[n][k], At[m][k], acc[ai][bj][m][n], 0, 0, 0); __builtin_amdgcn_s_setprio(0); } while (0)
; #define PG8_WAIT_V(n) asm volatile("s_waitcnt vmcnt(" #n ")" ::: "memory")
; #define PG8_WAIT_L(n) asm volatile("s_waitcnt lgkmcnt(" #n ")" ::: "memory")
; #define PG8_BAR __builtin_amdgcn_s_barrier()
; #define PG8_SCHED __builtin_amdgcn_sched_barrier(0)
;     __device__ __forceinline__ void operator()(const f32x4 (&acc)[2][2][4][2], const Unit& u, int wr, int wc, int fr, int fq) const {
;         const int row0 = u.pm * BM + wr * 64 + fr, col0 = u.pn * BM + wc * 32 + 8 * fq;
;         float rs[2][4];
; #pragma unroll
;         for (int ai = 0; ai < 2; ++ai)
; #pragma unroll
;             for (int m = 0; m < 4; ++m) rs[ai][m] = SCALE ? ssq_rstd(ssq, row0 + ai * HALF + m * 16) : 1.0f;
; template <class Epi, class Sched, bool ALIGN_EPI = false, bool SP2 = false>
; __device__ __forceinline__ void gemm_phase(PG8_LAS unsigned char* lds, const Gemm g, const Sched& S, const Epi& E) {
;     ...
;             PG8_WAIT_V(8); PG8_WAIT_L(0); PG8_BAR; PG8_MMA(0, 0, At, B0); PG8_MMA(0, 1, At, B1); PG8_BAR; PG8_SCHED;
;             PG8_LDA(At, 1, 1); PG8_STAGE(PG8_SB(1, 0), b3, voffB); PG8_STAGE(PG8_SB(1, 1), b3 + hstep, voffB); PG8_STAGE(PG8_SA(1, 0), a3, voffA);
;             PG8_WAIT_V(8); PG8_WAIT_L(0); PG8_BAR; PG8_MMA(1, 0, At, B0); PG8_MMA(1, 1, At, B1); PG8_BAR; PG8_SCHED;
	s_waitcnt lgkmcnt(0)
	v_mfma_f32_16x16x32_bf16 v[58:61], v[160:163], v[194:197], v[58:61]
	v_mfma_f32_16x16x32_bf16 v[58:61], v[166:169], v[198:201], v[58:61]
	v_mfma_f32_16x16x32_bf16 v[42:45], v[166:169], v[206:209], v[42:45]
	v_mfma_f32_16x16x32_bf16 v[42:45], v[160:163], v[202:205], v[42:45]
	v_mfma_f32_16x16x32_bf16 v[26:29], v[160:163], v[210:213], v[26:29]
	v_mfma_f32_16x16x32_bf16 v[26:29], v[166:169], v[214:217], v[26:29]
	v_mfma_f32_16x16x32_bf16 v[10:13], v[166:169], v[222:225], v[10:13]
	v_mfma_f32_16x16x32_bf16 v[10:13], v[160:163], v[218:221], v[10:13]
	v_mfma_f32_16x16x32_bf16 v[2:5], v[170:173], v[218:221], v[2:5]
	v_mfma_f32_16x16x32_bf16 v[2:5], v[174:177], v[222:225], v[2:5]
	v_mfma_f32_16x16x32_bf16 v[18:21], v[174:177], v[214:217], v[18:21]
	v_mfma_f32_16x16x32_bf16 v[18:21], v[170:173], v[210:213], v[18:21]
	v_mfma_f32_16x16x32_bf16 v[34:37], v[170:173], v[202:205], v[34:37]
	v_mfma_f32_16x16x32_bf16 v[34:37], v[174:177], v[206:209], v[34:37]
	v_mfma_f32_16x16x32_bf16 v[50:53], v[174:177], v[198:201], v[50:53]
	v_mfma_f32_16x16x32_bf16 v[50:53], v[170:173], v[194:197], v[50:53]
	v_mfma_f32_16x16x32_bf16 v[66:69], v[178:181], v[194:197], v[66:69]
	v_mfma_f32_16x16x32_bf16 v[66:69], v[182:185], v[198:201], v[66:69]
	v_mfma_f32_16x16x32_bf16 v[46:49], v[182:185], v[206:209], v[46:49]
	v_mfma_f32_16x16x32_bf16 v[46:49], v[178:181], v[202:205], v[46:49]
	v_mfma_f32_16x16x32_bf16 v[30:33], v[178:181], v[210:213], v[30:33]
	v_mfma_f32_16x16x32_bf16 v[30:33], v[182:185], v[214:217], v[30:33]
	v_mfma_f32_16x16x32_bf16 v[14:17], v[182:185], v[222:225], v[14:17]
	v_mfma_f32_16x16x32_bf16 v[14:17], v[178:181], v[218:221], v[14:17]
	v_mfma_f32_16x16x32_bf16 v[6:9], v[186:189], v[218:221], v[6:9]
	v_mfma_f32_16x16x32_bf16 v[6:9], v[190:193], v[222:225], v[6:9]
	v_mfma_f32_16x16x32_bf16 v[22:25], v[190:193], v[214:217], v[22:25]
	v_mfma_f32_16x16x32_bf16 v[22:25], v[186:189], v[210:213], v[22:25]
	v_mfma_f32_16x16x32_bf16 v[38:41], v[186:189], v[202:205], v[38:41]
	v_mfma_f32_16x16x32_bf16 v[38:41], v[190:193], v[206:209], v[38:41]
	v_mfma_f32_16x16x32_bf16 v[54:57], v[190:193], v[198:201], v[54:57]
	v_mfma_f32_16x16x32_bf16 v[54:57], v[186:189], v[194:197], v[54:57]
	s_barrier
	s_add_i32 s68, s68, 2
	s_add_u32 s24, s24, 0x100
	s_addc_u32 s25, s25, 0
	s_add_u32 s66, s66, 0x100
	s_addc_u32 s67, s67, 0
	s_cmp_gt_u32 s68, 61
	s_cbranch_scc0 .LBB0_1126
	s_and_b64 vcc, exec, s[8:9]
	s_cbranch_vccz .LBB0_1129
	v_lshl_add_u32 v168, s20, 8, v147
	v_ashrrev_i32_e32 v169, 31, v168
	v_or_b32_e32 v166, 16, v168
	v_or_b32_e32 v160, 32, v168
	v_or_b32_e32 v156, 48, v168
	v_lshl_add_u64 v[148:149], v[168:169], 3, s[4:5]
	v_ashrrev_i32_e32 v167, 31, v166
	v_ashrrev_i32_e32 v161, 31, v160
	v_ashrrev_i32_e32 v157, 31, v156
	v_lshl_add_u64 v[162:163], v[166:167], 3, s[4:5]
	v_lshl_add_u64 v[170:171], v[160:161], 3, s[4:5]
	global_load_dwordx2 v[172:173], v[148:149], off
	global_load_dwordx2 v[174:175], v[148:149], off offset:1024
	global_load_dwordx2 v[176:177], v[148:149], off offset:1152
	global_load_dwordx2 v[178:179], v[148:149], off offset:1280
	v_lshl_add_u64 v[180:181], v[156:157], 3, s[4:5]
	global_load_dwordx2 v[182:183], v[162:163], off
	s_nop 0
	global_load_dwordx2 v[170:171], v[170:171], off
	s_nop 0
	global_load_dwordx2 v[180:181], v[180:181], off
	s_nop 0
	global_load_dwordx2 v[148:149], v[148:149], off offset:1408
	s_barrier
	s_branch .Lepi_rest_1129

; __device__ __forceinline__ unsigned cvt_pk_bf16(float lo, float hi) { unsigned r; asm volatile("v_cvt_pk_bf16_f32 %0, %1, %2" : "=v"(r) : "v"(lo), "v"(hi)); return r; }
; __device__ __forceinline__ unsigned cvt_pk_bf16(float lo, float hi) { unsigned r; asm volatile("v_cvt_pk_bf16_f32 %0, %1, %2" : "=v"(r) : "v"(lo), "v"(hi)); return r; }
; __device__ __forceinline__ float ssq_rstd(const ssq_t* ssq, int row) { return __builtin_amdgcn_rsqf((float)ssq[row] * (SSQ_UNFIX * RMS_INV_D) + RMS_EPS); }
;     __device__ __forceinline__ void operator()(const f32x4 (&acc)[2][2][4][2], const Unit& u, int wr, int wc, int fr, int fq) const {
;         const int row0 = u.pm * BM + wr * 64 + fr, col0 = u.pn * HALF + wc * 32 + 8 * fq;
;         float rs[2][4];
; #pragma unroll
;         for (int ai = 0; ai < 2; ++ai)
; #pragma unroll
;             for (int m = 0; m < 4; ++m) rs[ai][m] = ssq_rstd(ssq, row0 + ai * HALF + m * 16);
; #pragma unroll
;         for (int ai = 0; ai < 2; ++ai)
; #pragma unroll
;             for (int m = 0; m < 4; ++m) { const int row = row0 + ai * HALF + m * 16; bf16_t* rowp = O + (size_t)row * ldc + col0; float a[8];
; #pragma unroll
;                 for (int n = 0; n < 2; ++n)
; #pragma unroll
;                     for (int i = 0; i < 4; i += 2) {
;                         const f32x2 r2 = {rs[ai][m], rs[ai][m]};
;                         const f32x2 g = (f32x2){acc[ai][0][m][n][i], acc[ai][0][m][n][i + 1]} * r2, up = (f32x2){acc[ai][1][m][n][i], acc[ai][1][m][n][i + 1]} * r2;
;                         const f32x2 t = g * (f32x2){-1.4426950408889634f, -1.4426950408889634f};
;                         const f32x2 d = (f32x2){__builtin_amdgcn_exp2f(t.x), __builtin_amdgcn_exp2f(t.y)} + (f32x2){1.0f, 1.0f};
;                         const f32x2 o2 = (g * up) * (f32x2){__builtin_amdgcn_rcpf(d.x), __builtin_amdgcn_rcpf(d.y)};
;                         a[4 * n + i] = o2.x; a[4 * n + i + 1] = o2.y; }
;                 u32x4 w; w.x = cvt_pk_bf16(a[0], a[1]); w.y = cvt_pk_bf16(a[2], a[3]); w.z = cvt_pk_bf16(a[4], a[5]); w.w = cvt_pk_bf16(a[6], a[7]);
;                 *(u32x4*)rowp = w; }
.Lepi_rest_1129:
	v_add_u32_e32 v165, 0x80, v168
	v_add_u32_e32 v163, 0x90, v168
	v_add_u32_e32 v161, 0xa0, v168
	s_andn2_b64 vcc, exec, s[0:1]
	s_mov_b64 s[0:1], -1
	s_waitcnt vmcnt(0)
	v_ffbh_u32_e32 v146, v173
	v_min_u32_e32 v146, 32, v146
	v_lshlrev_b64 v[172:173], v146, v[172:173]
	v_ffbh_u32_e32 v158, v171
	v_min_u32_e32 v158, 32, v158
	v_min_u32_e32 v169, 1, v172
	v_lshlrev_b64 v[170:171], v158, v[170:171]
	v_or_b32_e32 v169, v173, v169
	v_min_u32_e32 v170, 1, v170
	v_cvt_f32_u32_e32 v169, v169
	v_ffbh_u32_e32 v150, v175
	v_ffbh_u32_e32 v152, v177
	v_ffbh_u32_e32 v154, v179
	v_ffbh_u32_e32 v162, v181
	v_or_b32_e32 v170, v171, v170
	v_min_u32_e32 v150, 32, v150
	v_min_u32_e32 v152, 32, v152
	v_min_u32_e32 v154, 32, v154
	v_min_u32_e32 v162, 32, v162
	v_cvt_f32_u32_e32 v170, v170
	v_sub_u32_e32 v146, 32, v146
	v_lshlrev_b64 v[174:175], v150, v[174:175]
	v_lshlrev_b64 v[176:177], v152, v[176:177]
	v_lshlrev_b64 v[178:179], v154, v[178:179]
	v_lshlrev_b64 v[180:181], v162, v[180:181]
	v_min_u32_e32 v172, 1, v174
	v_min_u32_e32 v174, 1, v176
	v_min_u32_e32 v176, 1, v178
	v_min_u32_e32 v178, 1, v180
	v_ldexp_f32 v146, v169, v146
	v_sub_u32_e32 v158, 32, v158
	v_or_b32_e32 v171, v181, v178
	v_fmamk_f32 v146, v146, 0x2d800000, v159
	v_cvt_f32_u32_e32 v171, v171
	v_ldexp_f32 v158, v170, v158
	v_rsq_f32_e32 v170, v146
	v_or_b32_e32 v172, v175, v172
	v_or_b32_e32 v174, v177, v174
	v_or_b32_e32 v175, v179, v176
	v_pk_mul_f32 v[122:123], v[122:123], v[170:171] op_sel_hi:[1,0]
	v_pk_mul_f32 v[124:125], v[124:125], v[170:171] op_sel_hi:[1,0]
	v_pk_mul_f32 v[176:177], v[122:123], s[10:11] op_sel_hi:[1,0]
	v_pk_mul_f32 v[178:179], v[124:125], s[10:11] op_sel_hi:[1,0]
	v_exp_f32_e32 v176, v176
	v_exp_f32_e32 v177, v177
	v_exp_f32_e32 v178, v178
	v_exp_f32_e32 v179, v179
	v_ffbh_u32_e32 v157, v183
	v_pk_add_f32 v[176:177], v[176:177], 1.0 op_sel_hi:[1,0]
	v_min_u32_e32 v157, 32, v157
	v_pk_mul_f32 v[126:127], v[126:127], v[170:171] op_sel_hi:[1,0]
	v_rcp_f32_e32 v176, v176
	v_rcp_f32_e32 v177, v177
	v_lshlrev_b64 v[182:183], v157, v[182:183]
	v_pk_mul_f32 v[122:123], v[122:123], v[126:127]
	v_pk_mul_f32 v[126:127], v[128:129], v[170:171] op_sel_hi:[1,0]
	v_pk_add_f32 v[128:129], v[178:179], 1.0 op_sel_hi:[1,0]
	v_min_u32_e32 v173, 1, v182
	v_rcp_f32_e32 v128, v128
	v_rcp_f32_e32 v129, v129
	v_or_b32_e32 v173, v183, v173
	v_pk_mul_f32 v[114:115], v[114:115], v[170:171] op_sel_hi:[1,0]
	v_cvt_f32_u32_e32 v173, v173
	v_pk_mul_f32 v[122:123], v[122:123], v[176:177]
	v_pk_mul_f32 v[176:177], v[114:115], s[10:11] op_sel_hi:[1,0]
	v_pk_mul_f32 v[124:125], v[124:125], v[126:127]
	v_exp_f32_e32 v176, v176
	v_exp_f32_e32 v177, v177
	v_pk_mul_f32 v[116:117], v[116:117], v[170:171] op_sel_hi:[1,0]
	v_ffbh_u32_e32 v167, v149
	v_cvt_f32_u32_e32 v172, v172
	v_pk_mul_f32 v[124:125], v[124:125], v[128:129]
	v_pk_mul_f32 v[128:129], v[116:117], s[10:11] op_sel_hi:[1,0]
	v_min_u32_e32 v167, 32, v167
	v_sub_u32_e32 v157, 32, v157
	v_exp_f32_e32 v128, v128
	v_exp_f32_e32 v129, v129
	v_lshlrev_b64 v[148:149], v167, v[148:149]
	v_ldexp_f32 v157, v173, v157
	v_sub_u32_e32 v150, 32, v150
	v_min_u32_e32 v148, 1, v148
	v_fmamk_f32 v146, v157, 0x2d800000, v159
	v_pk_mul_f32 v[118:119], v[118:119], v[170:171] op_sel_hi:[1,0]
	v_pk_add_f32 v[126:127], v[176:177], 1.0 op_sel_hi:[1,0]
	v_cvt_f32_u32_e32 v174, v174
	v_cvt_f32_u32_e32 v175, v175
	v_ldexp_f32 v150, v172, v150
	v_rsq_f32_e32 v172, v146
	v_or_b32_e32 v146, v149, v148
	v_pk_mul_f32 v[114:115], v[114:115], v[118:119]
	v_rcp_f32_e32 v118, v126
	v_rcp_f32_e32 v119, v127
	v_cvt_f32_u32_e32 v146, v146
	v_pk_add_f32 v[126:127], v[128:129], 1.0 op_sel_hi:[1,0]
	v_sub_u32_e32 v152, 32, v152
	v_rcp_f32_e32 v126, v126
	v_rcp_f32_e32 v127, v127
	v_sub_u32_e32 v154, 32, v154
	v_sub_u32_e32 v162, 32, v162
	v_ldexp_f32 v152, v174, v152
	v_ldexp_f32 v154, v175, v154
	v_sub_u32_e32 v148, 32, v167
	v_lshl_or_b32 v174, s63, 7, v153
	v_pk_mul_f32 v[118:119], v[114:115], v[118:119]
	v_pk_mul_f32 v[114:115], v[120:121], v[170:171] op_sel_hi:[1,0]
	v_ldexp_f32 v162, v171, v162
	v_fmamk_f32 v150, v150, 0x2d800000, v159
	v_fmamk_f32 v169, v154, 0x2d800000, v159
	v_fmamk_f32 v157, v158, 0x2d800000, v159
	v_ldexp_f32 v146, v146, v148
	v_ashrrev_i32_e32 v175, 31, v174
	v_mov_b64_e32 v[148:149], s[38:39]
	v_pk_mul_f32 v[114:115], v[116:117], v[114:115]
	v_fmamk_f32 v158, v162, 0x2d800000, v159
	v_rsq_f32_e32 v154, v150
	v_rsq_f32_e32 v162, v157
	v_rsq_f32_e32 v150, v169
	v_add_u32_e32 v157, 0xb0, v168
	v_mad_i64_i32 v[168:169], s[22:23], v168, s62, v[148:149]
	v_pk_mul_f32 v[120:121], v[114:115], v[126:127]
	v_lshlrev_b64 v[114:115], 1, v[174:175]
	v_lshl_add_u64 v[126:127], v[168:169], 0, v[114:115]
	v_cvt_pk_bf16_f32 v116, v122, v123
	v_cvt_pk_bf16_f32 v117, v124, v125
	v_pk_mul_f32 v[106:107], v[106:107], v[172:173] op_sel_hi:[1,0]
	v_cvt_pk_bf16_f32 v118, v118, v119
	v_cvt_pk_bf16_f32 v119, v120, v121
	global_store_dwordx4 v[126:127], v[116:119], off
	v_pk_mul_f32 v[108:109], v[108:109], v[172:173] op_sel_hi:[1,0]
	v_pk_mul_f32 v[110:111], v[110:111], v[172:173] op_sel_hi:[1,0]
	v_pk_mul_f32 v[116:117], v[106:107], s[10:11] op_sel_hi:[1,0]
	v_pk_mul_f32 v[120:121], v[108:109], s[10:11] op_sel_hi:[1,0]
	v_exp_f32_e32 v116, v116
	v_exp_f32_e32 v117, v117
	v_exp_f32_e32 v120, v120
	v_exp_f32_e32 v121, v121
	v_pk_mul_f32 v[106:107], v[106:107], v[110:111]
	v_pk_add_f32 v[116:117], v[116:117], 1.0 op_sel_hi:[1,0]
	v_pk_mul_f32 v[110:111], v[112:113], v[172:173] op_sel_hi:[1,0]
	v_rcp_f32_e32 v116, v116
	v_rcp_f32_e32 v117, v117
	v_pk_add_f32 v[112:113], v[120:121], 1.0 op_sel_hi:[1,0]
	v_pk_mul_f32 v[98:99], v[98:99], v[172:173] op_sel_hi:[1,0]
; __device__ __forceinline__ unsigned cvt_pk_bf16(float lo, float hi) { unsigned r; asm volatile("v_cvt_pk_bf16_f32 %0, %1, %2" : "=v"(r) : "v"(lo), "v"(hi)); return r; }
; __device__ __forceinline__ unsigned cvt_pk_bf16(float lo, float hi) { unsigned r; asm volatile("v_cvt_pk_bf16_f32 %0, %1, %2" : "=v"(r) : "v"(lo), "v"(hi)); return r; }
;     __device__ __forceinline__ void operator()(const f32x4 (&acc)[2][2][4][2], const Unit& u, int wr, int wc, int fr, int fq) const {
;     ...
;             for (int m = 0; m < 4; ++m) { const int row = row0 + ai * HALF + m * 16; bf16_t* rowp = O + (size_t)row * ldc + col0; float a[8];
; #pragma unroll
;                 for (int n = 0; n < 2; ++n)
; #pragma unroll
;                     for (int i = 0; i < 4; i += 2) {
;                         const f32x2 r2 = {rs[ai][m], rs[ai][m]};
;                         const f32x2 g = (f32x2){acc[ai][0][m][n][i], acc[ai][0][m][n][i + 1]} * r2, up = (f32x2){acc[ai][1][m][n][i], acc[ai][1][m][n][i + 1]} * r2;
;                         const f32x2 t = g * (f32x2){-1.4426950408889634f, -1.4426950408889634f};
;                         const f32x2 d = (f32x2){__builtin_amdgcn_exp2f(t.x), __builtin_amdgcn_exp2f(t.y)} + (f32x2){1.0f, 1.0f};
;                         const f32x2 o2 = (g * up) * (f32x2){__builtin_amdgcn_rcpf(d.x), __builtin_amdgcn_rcpf(d.y)};
;                         a[4 * n + i] = o2.x; a[4 * n + i + 1] = o2.y; }
;                 u32x4 w; w.x = cvt_pk_bf16(a[0], a[1]); w.y = cvt_pk_bf16(a[2], a[3]); w.z = cvt_pk_bf16(a[4], a[5]); w.w = cvt_pk_bf16(a[6], a[7]);
;                 *(u32x4*)rowp = w; }
	v_rcp_f32_e32 v112, v112
	v_rcp_f32_e32 v113, v113
	v_pk_mul_f32 v[106:107], v[106:107], v[116:117]
	v_pk_mul_f32 v[116:117], v[98:99], s[10:11] op_sel_hi:[1,0]
	v_pk_mul_f32 v[108:109], v[108:109], v[110:111]
	v_exp_f32_e32 v116, v116
	v_exp_f32_e32 v117, v117
	v_pk_mul_f32 v[100:101], v[100:101], v[172:173] op_sel_hi:[1,0]
	v_pk_mul_f32 v[108:109], v[108:109], v[112:113]
	v_pk_mul_f32 v[112:113], v[100:101], s[10:11] op_sel_hi:[1,0]
	v_pk_mul_f32 v[102:103], v[102:103], v[172:173] op_sel_hi:[1,0]
	v_exp_f32_e32 v112, v112
	v_exp_f32_e32 v113, v113
	v_pk_add_f32 v[110:111], v[116:117], 1.0 op_sel_hi:[1,0]
	v_pk_mul_f32 v[98:99], v[98:99], v[102:103]
	v_rcp_f32_e32 v102, v110
	v_rcp_f32_e32 v103, v111
	v_pk_add_f32 v[110:111], v[112:113], 1.0 op_sel_hi:[1,0]
	v_mad_i64_i32 v[118:119], s[22:23], v166, s62, v[148:149]
	v_rcp_f32_e32 v110, v110
	v_rcp_f32_e32 v111, v111
	v_pk_mul_f32 v[102:103], v[98:99], v[102:103]
	v_pk_mul_f32 v[98:99], v[104:105], v[172:173] op_sel_hi:[1,0]
	v_pk_mul_f32 v[90:91], v[90:91], v[162:163] op_sel_hi:[1,0]
	v_pk_mul_f32 v[98:99], v[100:101], v[98:99]
	v_pk_mul_f32 v[92:93], v[92:93], v[162:163] op_sel_hi:[1,0]
	v_pk_mul_f32 v[104:105], v[98:99], v[110:111]
	v_lshl_add_u64 v[110:111], v[118:119], 0, v[114:115]
	v_cvt_pk_bf16_f32 v98, v106, v107
	v_cvt_pk_bf16_f32 v99, v108, v109
	v_cvt_pk_bf16_f32 v100, v102, v103
	v_cvt_pk_bf16_f32 v101, v104, v105
	global_store_dwordx4 v[110:111], v[98:101], off
	v_pk_mul_f32 v[102:103], v[92:93], s[10:11] op_sel_hi:[1,0]
	v_pk_mul_f32 v[94:95], v[94:95], v[162:163] op_sel_hi:[1,0]
	v_pk_mul_f32 v[98:99], v[90:91], s[10:11] op_sel_hi:[1,0]
	v_exp_f32_e32 v102, v102
	v_exp_f32_e32 v98, v98
	v_exp_f32_e32 v99, v99
	v_exp_f32_e32 v103, v103
	v_pk_mul_f32 v[90:91], v[90:91], v[94:95]
	v_pk_mul_f32 v[94:95], v[96:97], v[162:163] op_sel_hi:[1,0]
	v_pk_add_f32 v[98:99], v[98:99], 1.0 op_sel_hi:[1,0]
	v_pk_add_f32 v[96:97], v[102:103], 1.0 op_sel_hi:[1,0]
	v_rcp_f32_e32 v98, v98
	v_rcp_f32_e32 v99, v99
	v_rcp_f32_e32 v96, v96
	v_rcp_f32_e32 v97, v97
	v_pk_mul_f32 v[82:83], v[82:83], v[162:163] op_sel_hi:[1,0]
	v_pk_mul_f32 v[90:91], v[90:91], v[98:99]
	v_pk_mul_f32 v[98:99], v[82:83], s[10:11] op_sel_hi:[1,0]
	v_pk_mul_f32 v[92:93], v[92:93], v[94:95]
	v_exp_f32_e32 v98, v98
	v_exp_f32_e32 v99, v99
	v_pk_mul_f32 v[84:85], v[84:85], v[162:163] op_sel_hi:[1,0]
	v_pk_mul_f32 v[92:93], v[92:93], v[96:97]
	v_pk_mul_f32 v[96:97], v[84:85], s[10:11] op_sel_hi:[1,0]
	v_pk_mul_f32 v[86:87], v[86:87], v[162:163] op_sel_hi:[1,0]
	v_exp_f32_e32 v96, v96
	v_exp_f32_e32 v97, v97
	v_pk_add_f32 v[94:95], v[98:99], 1.0 op_sel_hi:[1,0]
	v_pk_mul_f32 v[82:83], v[82:83], v[86:87]
	v_rcp_f32_e32 v86, v94
	v_rcp_f32_e32 v87, v95
	v_pk_add_f32 v[94:95], v[96:97], 1.0 op_sel_hi:[1,0]
	v_rsq_f32_e32 v158, v158
	v_rcp_f32_e32 v94, v94
	v_rcp_f32_e32 v95, v95
	v_pk_mul_f32 v[86:87], v[82:83], v[86:87]
	v_pk_mul_f32 v[82:83], v[88:89], v[162:163] op_sel_hi:[1,0]
	v_mad_i64_i32 v[100:101], s[22:23], v160, s62, v[148:149]
	v_pk_mul_f32 v[82:83], v[84:85], v[82:83]
	v_pk_mul_f32 v[74:75], v[74:75], v[158:159] op_sel_hi:[1,0]
	v_pk_mul_f32 v[88:89], v[82:83], v[94:95]
	v_lshl_add_u64 v[94:95], v[100:101], 0, v[114:115]
	v_cvt_pk_bf16_f32 v82, v90, v91
	v_cvt_pk_bf16_f32 v83, v92, v93
	v_cvt_pk_bf16_f32 v84, v86, v87
	v_cvt_pk_bf16_f32 v85, v88, v89
	global_store_dwordx4 v[94:95], v[82:85], off
	v_pk_mul_f32 v[76:77], v[76:77], v[158:159] op_sel_hi:[1,0]
	v_pk_mul_f32 v[78:79], v[78:79], v[158:159] op_sel_hi:[1,0]
	v_pk_mul_f32 v[82:83], v[74:75], s[10:11] op_sel_hi:[1,0]
	v_pk_mul_f32 v[86:87], v[76:77], s[10:11] op_sel_hi:[1,0]
	v_exp_f32_e32 v82, v82
	v_exp_f32_e32 v83, v83
	v_exp_f32_e32 v86, v86
	v_exp_f32_e32 v87, v87
	v_pk_mul_f32 v[74:75], v[74:75], v[78:79]
	v_pk_add_f32 v[82:83], v[82:83], 1.0 op_sel_hi:[1,0]
	v_pk_mul_f32 v[78:79], v[80:81], v[158:159] op_sel_hi:[1,0]
	v_rcp_f32_e32 v82, v82
	v_rcp_f32_e32 v83, v83
	v_pk_add_f32 v[80:81], v[86:87], 1.0 op_sel_hi:[1,0]
	v_pk_mul_f32 v[62:63], v[62:63], v[158:159] op_sel_hi:[1,0]
	v_rcp_f32_e32 v80, v80
	v_rcp_f32_e32 v81, v81
	v_pk_mul_f32 v[74:75], v[74:75], v[82:83]
	v_pk_mul_f32 v[82:83], v[62:63], s[10:11] op_sel_hi:[1,0]
	v_pk_mul_f32 v[76:77], v[76:77], v[78:79]
	v_exp_f32_e32 v82, v82
	v_exp_f32_e32 v83, v83
	v_pk_mul_f32 v[64:65], v[64:65], v[158:159] op_sel_hi:[1,0]
	v_pk_mul_f32 v[76:77], v[76:77], v[80:81]
	v_pk_mul_f32 v[80:81], v[64:65], s[10:11] op_sel_hi:[1,0]
	v_pk_mul_f32 v[70:71], v[70:71], v[158:159] op_sel_hi:[1,0]
	v_exp_f32_e32 v80, v80
	v_exp_f32_e32 v81, v81
	v_pk_add_f32 v[78:79], v[82:83], 1.0 op_sel_hi:[1,0]
	v_pk_mul_f32 v[62:63], v[62:63], v[70:71]
	v_rcp_f32_e32 v70, v78
	v_rcp_f32_e32 v71, v79
	v_pk_add_f32 v[78:79], v[80:81], 1.0 op_sel_hi:[1,0]
	v_mad_i64_i32 v[84:85], s[22:23], v156, s62, v[148:149]
	v_rcp_f32_e32 v78, v78
	v_rcp_f32_e32 v79, v79
	v_pk_mul_f32 v[70:71], v[62:63], v[70:71]
	v_pk_mul_f32 v[62:63], v[72:73], v[158:159] op_sel_hi:[1,0]
	v_pk_mul_f32 v[58:59], v[58:59], v[154:155] op_sel_hi:[1,0]
	v_pk_mul_f32 v[62:63], v[64:65], v[62:63]
	v_pk_mul_f32 v[60:61], v[60:61], v[154:155] op_sel_hi:[1,0]
	v_pk_mul_f32 v[72:73], v[62:63], v[78:79]
	v_lshl_add_u64 v[78:79], v[84:85], 0, v[114:115]
	v_cvt_pk_bf16_f32 v62, v74, v75
	v_cvt_pk_bf16_f32 v63, v76, v77
	v_cvt_pk_bf16_f32 v64, v70, v71
	v_cvt_pk_bf16_f32 v65, v72, v73
	global_store_dwordx4 v[78:79], v[62:65], off
	v_pk_mul_f32 v[70:71], v[60:61], s[10:11] op_sel_hi:[1,0]
	v_pk_mul_f32 v[66:67], v[66:67], v[154:155] op_sel_hi:[1,0]
	v_pk_mul_f32 v[62:63], v[58:59], s[10:11] op_sel_hi:[1,0]
	v_exp_f32_e32 v70, v70
	v_exp_f32_e32 v62, v62
	v_exp_f32_e32 v63, v63
; __device__ __forceinline__ unsigned cvt_pk_bf16(float lo, float hi) { unsigned r; asm volatile("v_cvt_pk_bf16_f32 %0, %1, %2" : "=v"(r) : "v"(lo), "v"(hi)); return r; }
; __device__ __forceinline__ unsigned cvt_pk_bf16(float lo, float hi) { unsigned r; asm volatile("v_cvt_pk_bf16_f32 %0, %1, %2" : "=v"(r) : "v"(lo), "v"(hi)); return r; }
;     __device__ __forceinline__ void operator()(const f32x4 (&acc)[2][2][4][2], const Unit& u, int wr, int wc, int fr, int fq) const {
;     ...
;             for (int m = 0; m < 4; ++m) { const int row = row0 + ai * HALF + m * 16; bf16_t* rowp = O + (size_t)row * ldc + col0; float a[8];
; #pragma unroll
;                 for (int n = 0; n < 2; ++n)
; #pragma unroll
;                     for (int i = 0; i < 4; i += 2) {
;                         const f32x2 r2 = {rs[ai][m], rs[ai][m]};
;                         const f32x2 g = (f32x2){acc[ai][0][m][n][i], acc[ai][0][m][n][i + 1]} * r2, up = (f32x2){acc[ai][1][m][n][i], acc[ai][1][m][n][i + 1]} * r2;
;                         const f32x2 t = g * (f32x2){-1.4426950408889634f, -1.4426950408889634f};
;                         const f32x2 d = (f32x2){__builtin_amdgcn_exp2f(t.x), __builtin_amdgcn_exp2f(t.y)} + (f32x2){1.0f, 1.0f};
;                         const f32x2 o2 = (g * up) * (f32x2){__builtin_amdgcn_rcpf(d.x), __builtin_amdgcn_rcpf(d.y)};
;                         a[4 * n + i] = o2.x; a[4 * n + i + 1] = o2.y; }
;                 u32x4 w; w.x = cvt_pk_bf16(a[0], a[1]); w.y = cvt_pk_bf16(a[2], a[3]); w.z = cvt_pk_bf16(a[4], a[5]); w.w = cvt_pk_bf16(a[6], a[7]);
;                 *(u32x4*)rowp = w; }
	v_exp_f32_e32 v71, v71
	v_pk_mul_f32 v[58:59], v[58:59], v[66:67]
	v_pk_mul_f32 v[50:51], v[50:51], v[154:155] op_sel_hi:[1,0]
	v_pk_add_f32 v[62:63], v[62:63], 1.0 op_sel_hi:[1,0]
	v_pk_add_f32 v[66:67], v[70:71], 1.0 op_sel_hi:[1,0]
	v_rcp_f32_e32 v62, v62
	v_rcp_f32_e32 v63, v63
	v_rcp_f32_e32 v66, v66
	v_rcp_f32_e32 v67, v67
	v_pk_mul_f32 v[52:53], v[52:53], v[154:155] op_sel_hi:[1,0]
	v_pk_mul_f32 v[58:59], v[58:59], v[62:63]
	v_pk_mul_f32 v[62:63], v[68:69], v[154:155] op_sel_hi:[1,0]
	v_pk_mul_f32 v[68:69], v[50:51], s[10:11] op_sel_hi:[1,0]
	v_pk_mul_f32 v[60:61], v[60:61], v[62:63]
	v_exp_f32_e32 v68, v68
	v_exp_f32_e32 v69, v69
	v_pk_mul_f32 v[60:61], v[60:61], v[66:67]
	v_pk_mul_f32 v[66:67], v[52:53], s[10:11] op_sel_hi:[1,0]
	v_pk_mul_f32 v[54:55], v[54:55], v[154:155] op_sel_hi:[1,0]
	v_exp_f32_e32 v66, v66
	v_exp_f32_e32 v67, v67
	v_pk_add_f32 v[62:63], v[68:69], 1.0 op_sel_hi:[1,0]
	v_pk_mul_f32 v[50:51], v[50:51], v[54:55]
	v_rcp_f32_e32 v54, v62
	v_rcp_f32_e32 v55, v63
	v_fmamk_f32 v152, v152, 0x2d800000, v159
	v_pk_add_f32 v[62:63], v[66:67], 1.0 op_sel_hi:[1,0]
	v_rsq_f32_e32 v152, v152
	v_rcp_f32_e32 v62, v62
	v_rcp_f32_e32 v63, v63
	v_pk_mul_f32 v[54:55], v[50:51], v[54:55]
	v_pk_mul_f32 v[50:51], v[56:57], v[154:155] op_sel_hi:[1,0]
	v_mad_i64_i32 v[64:65], s[22:23], v165, s62, v[148:149]
	v_pk_mul_f32 v[50:51], v[52:53], v[50:51]
	v_pk_mul_f32 v[42:43], v[42:43], v[152:153] op_sel_hi:[1,0]
	v_pk_mul_f32 v[56:57], v[50:51], v[62:63]
	v_lshl_add_u64 v[62:63], v[64:65], 0, v[114:115]
	v_cvt_pk_bf16_f32 v50, v58, v59
	v_cvt_pk_bf16_f32 v51, v60, v61
	v_cvt_pk_bf16_f32 v52, v54, v55
	v_cvt_pk_bf16_f32 v53, v56, v57
	global_store_dwordx4 v[62:63], v[50:53], off
	v_pk_mul_f32 v[44:45], v[44:45], v[152:153] op_sel_hi:[1,0]
	v_pk_mul_f32 v[46:47], v[46:47], v[152:153] op_sel_hi:[1,0]
	v_pk_mul_f32 v[50:51], v[42:43], s[10:11] op_sel_hi:[1,0]
	v_pk_mul_f32 v[54:55], v[44:45], s[10:11] op_sel_hi:[1,0]
	v_exp_f32_e32 v50, v50
	v_exp_f32_e32 v51, v51
	v_exp_f32_e32 v54, v54
	v_exp_f32_e32 v55, v55
	v_pk_mul_f32 v[42:43], v[42:43], v[46:47]
	v_pk_add_f32 v[50:51], v[50:51], 1.0 op_sel_hi:[1,0]
	v_pk_mul_f32 v[46:47], v[48:49], v[152:153] op_sel_hi:[1,0]
	v_rcp_f32_e32 v50, v50
	v_rcp_f32_e32 v51, v51
	v_pk_add_f32 v[48:49], v[54:55], 1.0 op_sel_hi:[1,0]
	v_pk_mul_f32 v[34:35], v[34:35], v[152:153] op_sel_hi:[1,0]
	v_rcp_f32_e32 v48, v48
	v_rcp_f32_e32 v49, v49
	v_pk_mul_f32 v[42:43], v[42:43], v[50:51]
	v_pk_mul_f32 v[50:51], v[34:35], s[10:11] op_sel_hi:[1,0]
	v_pk_mul_f32 v[44:45], v[44:45], v[46:47]
	v_exp_f32_e32 v50, v50
	v_exp_f32_e32 v51, v51
	v_pk_mul_f32 v[36:37], v[36:37], v[152:153] op_sel_hi:[1,0]
	v_pk_mul_f32 v[44:45], v[44:45], v[48:49]
	v_pk_mul_f32 v[48:49], v[36:37], s[10:11] op_sel_hi:[1,0]
	v_pk_mul_f32 v[38:39], v[38:39], v[152:153] op_sel_hi:[1,0]
	v_exp_f32_e32 v48, v48
	v_exp_f32_e32 v49, v49
	v_pk_add_f32 v[46:47], v[50:51], 1.0 op_sel_hi:[1,0]
	v_pk_mul_f32 v[34:35], v[34:35], v[38:39]
	v_rcp_f32_e32 v38, v46
	v_rcp_f32_e32 v39, v47
	v_pk_add_f32 v[46:47], v[48:49], 1.0 op_sel_hi:[1,0]
	v_mad_i64_i32 v[52:53], s[22:23], v163, s62, v[148:149]
	v_rcp_f32_e32 v46, v46
	v_rcp_f32_e32 v47, v47
	v_pk_mul_f32 v[38:39], v[34:35], v[38:39]
	v_pk_mul_f32 v[34:35], v[40:41], v[152:153] op_sel_hi:[1,0]
	v_pk_mul_f32 v[26:27], v[26:27], v[150:151] op_sel_hi:[1,0]
	v_pk_mul_f32 v[34:35], v[36:37], v[34:35]
	v_pk_mul_f32 v[28:29], v[28:29], v[150:151] op_sel_hi:[1,0]
	v_pk_mul_f32 v[40:41], v[34:35], v[46:47]
	v_lshl_add_u64 v[46:47], v[52:53], 0, v[114:115]
	v_cvt_pk_bf16_f32 v34, v42, v43
	v_cvt_pk_bf16_f32 v35, v44, v45
	v_cvt_pk_bf16_f32 v36, v38, v39
	v_cvt_pk_bf16_f32 v37, v40, v41
	global_store_dwordx4 v[46:47], v[34:37], off
	v_pk_mul_f32 v[38:39], v[28:29], s[10:11] op_sel_hi:[1,0]
	v_pk_mul_f32 v[30:31], v[30:31], v[150:151] op_sel_hi:[1,0]
	v_pk_mul_f32 v[34:35], v[26:27], s[10:11] op_sel_hi:[1,0]
	v_exp_f32_e32 v38, v38
	v_exp_f32_e32 v34, v34
	v_exp_f32_e32 v35, v35
	v_exp_f32_e32 v39, v39
	v_pk_mul_f32 v[26:27], v[26:27], v[30:31]
	v_pk_mul_f32 v[30:31], v[32:33], v[150:151] op_sel_hi:[1,0]
	v_pk_add_f32 v[34:35], v[34:35], 1.0 op_sel_hi:[1,0]
	v_pk_add_f32 v[32:33], v[38:39], 1.0 op_sel_hi:[1,0]
	v_rcp_f32_e32 v34, v34
	v_rcp_f32_e32 v35, v35
	v_rcp_f32_e32 v32, v32
	v_rcp_f32_e32 v33, v33
	v_pk_mul_f32 v[18:19], v[18:19], v[150:151] op_sel_hi:[1,0]
	v_pk_mul_f32 v[26:27], v[26:27], v[34:35]
	v_pk_mul_f32 v[34:35], v[18:19], s[10:11] op_sel_hi:[1,0]
	v_pk_mul_f32 v[28:29], v[28:29], v[30:31]
	v_exp_f32_e32 v34, v34
	v_exp_f32_e32 v35, v35
; __device__ __forceinline__ unsigned cvt_pk_bf16(float lo, float hi) { unsigned r; asm volatile("v_cvt_pk_bf16_f32 %0, %1, %2" : "=v"(r) : "v"(lo), "v"(hi)); return r; }
; __device__ __forceinline__ unsigned cvt_pk_bf16(float lo, float hi) { unsigned r; asm volatile("v_cvt_pk_bf16_f32 %0, %1, %2" : "=v"(r) : "v"(lo), "v"(hi)); return r; }
; #define PG8_BAR __builtin_amdgcn_s_barrier()
;     __device__ __forceinline__ void operator()(const f32x4 (&acc)[2][2][4][2], const Unit& u, int wr, int wc, int fr, int fq) const {
;     ...
;             for (int m = 0; m < 4; ++m) { const int row = row0 + ai * HALF + m * 16; bf16_t* rowp = O + (size_t)row * ldc + col0; float a[8];
; #pragma unroll
;                 for (int n = 0; n < 2; ++n)
; #pragma unroll
;                     for (int i = 0; i < 4; i += 2) {
;                         const f32x2 r2 = {rs[ai][m], rs[ai][m]};
;                         const f32x2 g = (f32x2){acc[ai][0][m][n][i], acc[ai][0][m][n][i + 1]} * r2, up = (f32x2){acc[ai][1][m][n][i], acc[ai][1][m][n][i + 1]} * r2;
;                         const f32x2 t = g * (f32x2){-1.4426950408889634f, -1.4426950408889634f};
;                         const f32x2 d = (f32x2){__builtin_amdgcn_exp2f(t.x), __builtin_amdgcn_exp2f(t.y)} + (f32x2){1.0f, 1.0f};
;                         const f32x2 o2 = (g * up) * (f32x2){__builtin_amdgcn_rcpf(d.x), __builtin_amdgcn_rcpf(d.y)};
;                         a[4 * n + i] = o2.x; a[4 * n + i + 1] = o2.y; }
;                 u32x4 w; w.x = cvt_pk_bf16(a[0], a[1]); w.y = cvt_pk_bf16(a[2], a[3]); w.z = cvt_pk_bf16(a[4], a[5]); w.w = cvt_pk_bf16(a[6], a[7]);
;                 *(u32x4*)rowp = w; }
; template <class Epi, class Sched, bool ALIGN_EPI = false, bool SP2 = false>
; __device__ __forceinline__ void gemm_phase(PG8_LAS unsigned char* lds, const Gemm g, const Sched& S, const Epi& E) {
;     ...
; #pragma unroll
;         for (int a = 0; a < 2; ++a)
; #pragma unroll
;             for (int b = 0; b < 2; ++b)
; #pragma unroll
;                 for (int m = 0; m < 4; ++m)
; #pragma unroll
;                     for (int n = 0; n < 2; ++n) { d64x2 z_; asm volatile("v_mov_b64 %0, 0\n\tv_mov_b64 %1, 0" : "=v"(z_.x), "=v"(z_.y)); acc[a][b][m][n] = __builtin_bit_cast(f32x4, z_); }
;         cur = nxt; cA = nA; cB = nB; ++ui;
;         if constexpr (ALIGN_EPI) { if (wr == 1) PG8_BAR; }
	v_pk_mul_f32 v[20:21], v[20:21], v[150:151] op_sel_hi:[1,0]
	v_pk_mul_f32 v[28:29], v[28:29], v[32:33]
	v_pk_mul_f32 v[32:33], v[20:21], s[10:11] op_sel_hi:[1,0]
	v_pk_mul_f32 v[22:23], v[22:23], v[150:151] op_sel_hi:[1,0]
	v_exp_f32_e32 v32, v32
	v_exp_f32_e32 v33, v33
	v_pk_add_f32 v[30:31], v[34:35], 1.0 op_sel_hi:[1,0]
	v_pk_mul_f32 v[18:19], v[18:19], v[22:23]
	v_rcp_f32_e32 v22, v30
	v_rcp_f32_e32 v23, v31
	v_fmamk_f32 v146, v146, 0x2d800000, v159
	v_pk_add_f32 v[30:31], v[32:33], 1.0 op_sel_hi:[1,0]
	v_rsq_f32_e32 v146, v146
	v_rcp_f32_e32 v30, v30
	v_rcp_f32_e32 v31, v31
	v_pk_mul_f32 v[22:23], v[18:19], v[22:23]
	v_pk_mul_f32 v[18:19], v[24:25], v[150:151] op_sel_hi:[1,0]
	v_mad_i64_i32 v[36:37], s[22:23], v161, s62, v[148:149]
	v_pk_mul_f32 v[18:19], v[20:21], v[18:19]
	v_pk_mul_f32 v[10:11], v[10:11], v[146:147] op_sel_hi:[1,0]
	v_pk_mul_f32 v[24:25], v[18:19], v[30:31]
	v_lshl_add_u64 v[30:31], v[36:37], 0, v[114:115]
	v_cvt_pk_bf16_f32 v18, v26, v27
	v_cvt_pk_bf16_f32 v19, v28, v29
	v_cvt_pk_bf16_f32 v20, v22, v23
	v_cvt_pk_bf16_f32 v21, v24, v25
	global_store_dwordx4 v[30:31], v[18:21], off
	v_pk_mul_f32 v[12:13], v[12:13], v[146:147] op_sel_hi:[1,0]
	v_pk_mul_f32 v[14:15], v[14:15], v[146:147] op_sel_hi:[1,0]
	v_pk_mul_f32 v[18:19], v[10:11], s[10:11] op_sel_hi:[1,0]
	v_pk_mul_f32 v[22:23], v[12:13], s[10:11] op_sel_hi:[1,0]
	v_exp_f32_e32 v18, v18
	v_exp_f32_e32 v19, v19
	v_exp_f32_e32 v22, v22
	v_exp_f32_e32 v23, v23
	v_pk_mul_f32 v[10:11], v[10:11], v[14:15]
	v_pk_add_f32 v[18:19], v[18:19], 1.0 op_sel_hi:[1,0]
	v_pk_mul_f32 v[14:15], v[16:17], v[146:147] op_sel_hi:[1,0]
	v_rcp_f32_e32 v18, v18
	v_rcp_f32_e32 v19, v19
	v_pk_add_f32 v[16:17], v[22:23], 1.0 op_sel_hi:[1,0]
	v_pk_mul_f32 v[2:3], v[2:3], v[146:147] op_sel_hi:[1,0]
	v_rcp_f32_e32 v16, v16
	v_rcp_f32_e32 v17, v17
	v_pk_mul_f32 v[10:11], v[10:11], v[18:19]
	v_pk_mul_f32 v[18:19], v[2:3], s[10:11] op_sel_hi:[1,0]
	v_pk_mul_f32 v[12:13], v[12:13], v[14:15]
	v_exp_f32_e32 v18, v18
	v_exp_f32_e32 v19, v19
	v_pk_mul_f32 v[4:5], v[4:5], v[146:147] op_sel_hi:[1,0]
	v_pk_mul_f32 v[12:13], v[12:13], v[16:17]
	v_pk_mul_f32 v[16:17], v[4:5], s[10:11] op_sel_hi:[1,0]
	v_pk_mul_f32 v[6:7], v[6:7], v[146:147] op_sel_hi:[1,0]
	v_exp_f32_e32 v16, v16
	v_exp_f32_e32 v17, v17
	v_pk_add_f32 v[14:15], v[18:19], 1.0 op_sel_hi:[1,0]
	v_pk_mul_f32 v[2:3], v[2:3], v[6:7]
	v_rcp_f32_e32 v6, v14
	v_rcp_f32_e32 v7, v15
	v_pk_add_f32 v[14:15], v[16:17], 1.0 op_sel_hi:[1,0]
	v_mad_i64_i32 v[20:21], s[22:23], v157, s62, v[148:149]
	v_rcp_f32_e32 v14, v14
	v_rcp_f32_e32 v15, v15
	v_pk_mul_f32 v[6:7], v[2:3], v[6:7]
	v_pk_mul_f32 v[2:3], v[8:9], v[146:147] op_sel_hi:[1,0]
	s_nop 0
	v_pk_mul_f32 v[2:3], v[4:5], v[2:3]
	s_nop 0
	v_pk_mul_f32 v[8:9], v[2:3], v[14:15]
	v_lshl_add_u64 v[14:15], v[20:21], 0, v[114:115]
	v_cvt_pk_bf16_f32 v2, v10, v11
	v_cvt_pk_bf16_f32 v3, v12, v13
	v_cvt_pk_bf16_f32 v4, v6, v7
	v_cvt_pk_bf16_f32 v5, v8, v9
	global_store_dwordx4 v[14:15], v[2:5], off
	s_cbranch_vccnz .LBB0_1122
	s_andn2_b64 vcc, exec, s[2:3]
	v_mov_b64 v[122:123], 0
	v_mov_b64 v[124:125], 0
	v_mov_b64 v[114:115], 0
	v_mov_b64 v[116:117], 0
	v_mov_b64 v[106:107], 0
	v_mov_b64 v[108:109], 0
	v_mov_b64 v[98:99], 0
	v_mov_b64 v[100:101], 0
	v_mov_b64 v[90:91], 0
	v_mov_b64 v[92:93], 0
	v_mov_b64 v[82:83], 0
	v_mov_b64 v[84:85], 0
	v_mov_b64 v[74:75], 0
	v_mov_b64 v[76:77], 0
	v_mov_b64 v[62:63], 0
	v_mov_b64 v[64:65], 0
	v_mov_b64 v[126:127], 0
	v_mov_b64 v[128:129], 0
	v_mov_b64 v[118:119], 0
	v_mov_b64 v[120:121], 0
	v_mov_b64 v[110:111], 0
	v_mov_b64 v[112:113], 0
	v_mov_b64 v[102:103], 0
	v_mov_b64 v[104:105], 0
	v_mov_b64 v[94:95], 0
	v_mov_b64 v[96:97], 0
	v_mov_b64 v[86:87], 0
	v_mov_b64 v[88:89], 0
	v_mov_b64 v[78:79], 0
	v_mov_b64 v[80:81], 0
	v_mov_b64 v[70:71], 0
	v_mov_b64 v[72:73], 0
	v_mov_b64 v[58:59], 0
	v_mov_b64 v[60:61], 0
	v_mov_b64 v[50:51], 0
	v_mov_b64 v[52:53], 0
	v_mov_b64 v[42:43], 0
	v_mov_b64 v[44:45], 0
	v_mov_b64 v[34:35], 0
	v_mov_b64 v[36:37], 0
	v_mov_b64 v[26:27], 0
	v_mov_b64 v[28:29], 0
	v_mov_b64 v[18:19], 0
	v_mov_b64 v[20:21], 0
	v_mov_b64 v[10:11], 0
	v_mov_b64 v[12:13], 0
	v_mov_b64 v[2:3], 0
	v_mov_b64 v[4:5], 0
	v_mov_b64 v[66:67], 0
	v_mov_b64 v[68:69], 0
	v_mov_b64 v[54:55], 0
	v_mov_b64 v[56:57], 0
	v_mov_b64 v[46:47], 0
	v_mov_b64 v[48:49], 0
	v_mov_b64 v[38:39], 0
	v_mov_b64 v[40:41], 0
	v_mov_b64 v[30:31], 0
	v_mov_b64 v[32:33], 0
	v_mov_b64 v[22:23], 0
	v_mov_b64 v[24:25], 0
	v_mov_b64 v[14:15], 0
	v_mov_b64 v[16:17], 0
	v_mov_b64 v[6:7], 0
	v_mov_b64 v[8:9], 0
	s_cbranch_vccnz .LBB0_1121
	s_barrier
	s_branch .LBB0_1121

; #define PG8_STAGE(bufoff, gbase, voff) do { _Pragma("unroll") for (int _i = 0; _i < 2; ++_i) \
;         __builtin_amdgcn_global_load_lds((const unsigned*)((const char*)(gbase) + (voff)[_i]), (PG8_LAS unsigned*)(lds + (bufoff) + ldsw + _i * 8192), 16, 0, 0); } while (0)
; #define PG8_LDA(dst, b, h) do { _Pragma("unroll") for (int m = 0; m < 4; ++m) _Pragma("unroll") for (int k = 0; k < 2; ++k) dst[m][k] = *(const PG8_LAS bf16x8*)(lds + PG8_SA(b, h) + aoff + m * 2048 + k * 1024); } while (0)
; #define PG8_LDB(dst, b, h) do { _Pragma("unroll") for (int n = 0; n < 2; ++n) _Pragma("unroll") for (int k = 0; k < 2; ++k) dst[n][k] = *(const PG8_LAS bf16x8*)(lds + PG8_SB(b, h) + boff + n * 2048 + k * 1024); } while (0)
; #define PG8_MMA(ai, bj, At, Bt) do { __builtin_amdgcn_s_setprio(1); _Pragma("unroll") for (int m = 0; m < 4; ++m) _Pragma("unroll") for (int n = 0; n < 2; ++n) _Pragma("unroll") for (int k = 0; k < 2; ++k) \
;         acc[ai][bj][m][n] = __builtin_amdgcn_mfma_f32_16x16x32_bf16(Bt[n][k], At[m][k], acc[ai][bj][m][n], 0, 0, 0); __builtin_amdgcn_s_setprio(0); } while (0)
; #define PG8_WAIT_V(n) asm volatile("s_waitcnt vmcnt(" #n ")" ::: "memory")
; #define PG8_WAIT_L(n) asm volatile("s_waitcnt lgkmcnt(" #n ")" ::: "memory")
; #define PG8_BAR __builtin_amdgcn_s_barrier()
; #define PG8_SCHED __builtin_amdgcn_sched_barrier(0)
; template <class Epi, class Sched, bool ALIGN_EPI = false, bool SP2 = false>
; __device__ __forceinline__ void gemm_phase(PG8_LAS unsigned char* lds, const Gemm g, const Sched& S, const Epi& E) {
;     ...
;             PG8_LDB(B0, 0, 0); PG8_LDB(B1, 0, 1); PG8_SCHED; PG8_LDA(At, 0, 0); PG8_STAGE(PG8_SA(1, 1), a1 + hstep, voffA);
;             PG8_WAIT_V(8); PG8_WAIT_L(0); PG8_BAR; PG8_MMA(0, 0, At, B0); PG8_MMA(0, 1, At, B1); PG8_BAR; PG8_SCHED;
;             PG8_LDA(At, 0, 1); PG8_STAGE(PG8_SB(0, 0), b2, voffB); PG8_STAGE(PG8_SB(0, 1), b2 + hstep, voffB); PG8_STAGE(PG8_SA(0, 0), a2, voffA);
;             PG8_WAIT_V(8); PG8_WAIT_L(0); PG8_BAR; PG8_MMA(1, 0, At, B0); PG8_MMA(1, 1, At, B1); PG8_BAR; PG8_SCHED;
.LBB0_1332:
	ds_read_b128 v[148:151], v241 offset:0
	ds_read_b128 v[156:159], v241 offset:1024
	ds_read_b128 v[166:169], v241 offset:2048
	ds_read_b128 v[170:173], v241 offset:3072
	ds_read_b128 v[174:177], v241 offset:16384
	ds_read_b128 v[178:181], v241 offset:17408
	ds_read_b128 v[182:185], v241 offset:18432
	ds_read_b128 v[186:189], v241 offset:19456
	s_add_u32 s20, s22, 0xfff00080
	s_addc_u32 s21, s23, -1
	s_cmp_eq_u32 s67, 60
	s_cselect_b32 s25, s13, s21
	s_cselect_b32 s24, s63, s20
	s_cselect_b32 s21, s11, s66
	s_cselect_b32 s20, s64, s65
	s_add_i32 m0, s19, 0xc000
	ds_read_b128 v[190:193], v155
	ds_read_b128 v[194:197], v155 offset:1024
	ds_read_b128 v[198:201], v155 offset:2048
	ds_read_b128 v[202:205], v155 offset:3072
	ds_read_b128 v[206:209], v155 offset:4096
	ds_read_b128 v[210:213], v155 offset:5120
	ds_read_b128 v[214:217], v155 offset:6144
	ds_read_b128 v[218:221], v155 offset:7168
	global_load_lds_dwordx4 v138, s[22:23]
	s_add_i32 m0, s19, 0xe000
	s_nop 0
	global_load_lds_dwordx4 v140, s[22:23]
	s_waitcnt vmcnt(8)
	s_waitcnt lgkmcnt(0)
	s_barrier
	s_waitcnt lgkmcnt(0)
	v_mfma_f32_16x16x32_bf16 v[118:121], v[148:151], v[190:193], v[118:121]
	v_mfma_f32_16x16x32_bf16 v[118:121], v[156:159], v[194:197], v[118:121]
	v_mfma_f32_16x16x32_bf16 v[102:105], v[156:159], v[202:205], v[102:105]
	v_mfma_f32_16x16x32_bf16 v[102:105], v[148:151], v[198:201], v[102:105]
	v_mfma_f32_16x16x32_bf16 v[86:89], v[148:151], v[206:209], v[86:89]
	v_mfma_f32_16x16x32_bf16 v[86:89], v[156:159], v[210:213], v[86:89]
	v_mfma_f32_16x16x32_bf16 v[70:73], v[156:159], v[218:221], v[70:73]
	v_mfma_f32_16x16x32_bf16 v[70:73], v[148:151], v[214:217], v[70:73]
	v_mfma_f32_16x16x32_bf16 v[66:69], v[166:169], v[214:217], v[66:69]
	v_mfma_f32_16x16x32_bf16 v[66:69], v[170:173], v[218:221], v[66:69]
	v_mfma_f32_16x16x32_bf16 v[82:85], v[170:173], v[210:213], v[82:85]
	v_mfma_f32_16x16x32_bf16 v[82:85], v[166:169], v[206:209], v[82:85]
	v_mfma_f32_16x16x32_bf16 v[98:101], v[166:169], v[198:201], v[98:101]
	v_mfma_f32_16x16x32_bf16 v[98:101], v[170:173], v[202:205], v[98:101]
	v_mfma_f32_16x16x32_bf16 v[114:117], v[170:173], v[194:197], v[114:117]
	v_mfma_f32_16x16x32_bf16 v[114:117], v[166:169], v[190:193], v[114:117]
	v_mfma_f32_16x16x32_bf16 v[126:129], v[174:177], v[190:193], v[126:129]
	v_mfma_f32_16x16x32_bf16 v[126:129], v[178:181], v[194:197], v[126:129]
	v_mfma_f32_16x16x32_bf16 v[110:113], v[178:181], v[202:205], v[110:113]
	v_mfma_f32_16x16x32_bf16 v[110:113], v[174:177], v[198:201], v[110:113]
	v_mfma_f32_16x16x32_bf16 v[94:97], v[174:177], v[206:209], v[94:97]
	v_mfma_f32_16x16x32_bf16 v[94:97], v[178:181], v[210:213], v[94:97]
	v_mfma_f32_16x16x32_bf16 v[78:81], v[178:181], v[218:221], v[78:81]
	v_mfma_f32_16x16x32_bf16 v[78:81], v[174:177], v[214:217], v[78:81]
	v_mfma_f32_16x16x32_bf16 v[74:77], v[182:185], v[214:217], v[74:77]
	v_mfma_f32_16x16x32_bf16 v[74:77], v[186:189], v[218:221], v[74:77]
	v_mfma_f32_16x16x32_bf16 v[90:93], v[186:189], v[210:213], v[90:93]
	v_mfma_f32_16x16x32_bf16 v[90:93], v[182:185], v[206:209], v[90:93]
	v_mfma_f32_16x16x32_bf16 v[106:109], v[182:185], v[198:201], v[106:109]
	v_mfma_f32_16x16x32_bf16 v[106:109], v[186:189], v[202:205], v[106:109]
	v_mfma_f32_16x16x32_bf16 v[122:125], v[186:189], v[194:197], v[122:125]
	v_mfma_f32_16x16x32_bf16 v[122:125], v[182:185], v[190:193], v[122:125]
	s_barrier
	s_add_i32 s33, s47, s28
	s_mov_b32 m0, s33
	ds_read_b128 v[190:193], v155 offset:16384
	ds_read_b128 v[194:197], v155 offset:17408
	ds_read_b128 v[198:201], v155 offset:18432
	ds_read_b128 v[202:205], v155 offset:19456
	ds_read_b128 v[206:209], v155 offset:20480
	ds_read_b128 v[210:213], v155 offset:21504
	ds_read_b128 v[214:217], v155 offset:22528
	ds_read_b128 v[218:221], v155 offset:23552
	global_load_lds_dwordx4 v132, s[20:21]
	s_add_i32 m0, s33, 0x2000
	s_add_u32 s68, s20, 0x100000
	s_addc_u32 s69, s21, 0
	s_add_i32 s33, s52, s28
	global_load_lds_dwordx4 v136, s[20:21]
	s_mov_b32 m0, s33
	s_add_u32 s100, s24, 0x80
	s_addc_u32 s101, s25, 0
	global_load_lds_dwordx4 v132, s[68:69]
	s_add_i32 m0, s33, 0x2000
	s_nop 0
	global_load_lds_dwordx4 v136, s[68:69]
	s_mov_b32 m0, s19
	s_nop 0
	global_load_lds_dwordx4 v130, s[24:25]
	s_mov_b32 m0, s35
	s_nop 0
	global_load_lds_dwordx4 v134, s[24:25]
	s_waitcnt vmcnt(8)
	s_waitcnt lgkmcnt(0)
	s_barrier
	s_waitcnt lgkmcnt(0)
	v_mfma_f32_16x16x32_bf16 v[54:57], v[148:151], v[190:193], v[54:57]
	v_mfma_f32_16x16x32_bf16 v[54:57], v[156:159], v[194:197], v[54:57]
	v_mfma_f32_16x16x32_bf16 v[38:41], v[156:159], v[202:205], v[38:41]
	v_mfma_f32_16x16x32_bf16 v[38:41], v[148:151], v[198:201], v[38:41]
	v_mfma_f32_16x16x32_bf16 v[22:25], v[148:151], v[206:209], v[22:25]
	v_mfma_f32_16x16x32_bf16 v[22:25], v[156:159], v[210:213], v[22:25]
	v_mfma_f32_16x16x32_bf16 v[6:9], v[156:159], v[218:221], v[6:9]
	v_mfma_f32_16x16x32_bf16 v[6:9], v[148:151], v[214:217], v[6:9]
	v_mfma_f32_16x16x32_bf16 v[2:5], v[166:169], v[214:217], v[2:5]
	v_mfma_f32_16x16x32_bf16 v[2:5], v[170:173], v[218:221], v[2:5]
	v_mfma_f32_16x16x32_bf16 v[18:21], v[170:173], v[210:213], v[18:21]
	v_mfma_f32_16x16x32_bf16 v[18:21], v[166:169], v[206:209], v[18:21]
	v_mfma_f32_16x16x32_bf16 v[34:37], v[166:169], v[198:201], v[34:37]
	v_mfma_f32_16x16x32_bf16 v[34:37], v[170:173], v[202:205], v[34:37]
	v_mfma_f32_16x16x32_bf16 v[50:53], v[170:173], v[194:197], v[50:53]
	v_mfma_f32_16x16x32_bf16 v[50:53], v[166:169], v[190:193], v[50:53]
	v_mfma_f32_16x16x32_bf16 v[62:65], v[174:177], v[190:193], v[62:65]
	v_mfma_f32_16x16x32_bf16 v[62:65], v[178:181], v[194:197], v[62:65]
	v_mfma_f32_16x16x32_bf16 v[46:49], v[178:181], v[202:205], v[46:49]
	v_mfma_f32_16x16x32_bf16 v[46:49], v[174:177], v[198:201], v[46:49]
	v_mfma_f32_16x16x32_bf16 v[30:33], v[174:177], v[206:209], v[30:33]
	v_mfma_f32_16x16x32_bf16 v[30:33], v[178:181], v[210:213], v[30:33]
	v_mfma_f32_16x16x32_bf16 v[10:13], v[178:181], v[218:221], v[10:13]
	v_mfma_f32_16x16x32_bf16 v[10:13], v[174:177], v[214:217], v[10:13]
	v_mfma_f32_16x16x32_bf16 v[14:17], v[182:185], v[214:217], v[14:17]
	v_mfma_f32_16x16x32_bf16 v[14:17], v[186:189], v[218:221], v[14:17]
	v_mfma_f32_16x16x32_bf16 v[26:29], v[186:189], v[210:213], v[26:29]
	v_mfma_f32_16x16x32_bf16 v[26:29], v[182:185], v[206:209], v[26:29]
	v_mfma_f32_16x16x32_bf16 v[42:45], v[182:185], v[198:201], v[42:45]
	v_mfma_f32_16x16x32_bf16 v[42:45], v[186:189], v[202:205], v[42:45]
	v_mfma_f32_16x16x32_bf16 v[58:61], v[186:189], v[194:197], v[58:61]
	v_mfma_f32_16x16x32_bf16 v[58:61], v[182:185], v[190:193], v[58:61]
	s_barrier
; #define PG8_STAGE(bufoff, gbase, voff) do { _Pragma("unroll") for (int _i = 0; _i < 2; ++_i) \
;         __builtin_amdgcn_global_load_lds((const unsigned*)((const char*)(gbase) + (voff)[_i]), (PG8_LAS unsigned*)(lds + (bufoff) + ldsw + _i * 8192), 16, 0, 0); } while (0)
; #define PG8_LDA(dst, b, h) do { _Pragma("unroll") for (int m = 0; m < 4; ++m) _Pragma("unroll") for (int k = 0; k < 2; ++k) dst[m][k] = *(const PG8_LAS bf16x8*)(lds + PG8_SA(b, h) + aoff + m * 2048 + k * 1024); } while (0)
; #define PG8_LDB(dst, b, h) do { _Pragma("unroll") for (int n = 0; n < 2; ++n) _Pragma("unroll") for (int k = 0; k < 2; ++k) dst[n][k] = *(const PG8_LAS bf16x8*)(lds + PG8_SB(b, h) + boff + n * 2048 + k * 1024); } while (0)
; #define PG8_MMA(ai, bj, At, Bt) do { __builtin_amdgcn_s_setprio(1); _Pragma("unroll") for (int m = 0; m < 4; ++m) _Pragma("unroll") for (int n = 0; n < 2; ++n) _Pragma("unroll") for (int k = 0; k < 2; ++k) \
;         acc[ai][bj][m][n] = __builtin_amdgcn_mfma_f32_16x16x32_bf16(Bt[n][k], At[m][k], acc[ai][bj][m][n], 0, 0, 0); __builtin_amdgcn_s_setprio(0); } while (0)
; #define PG8_WAIT_V(n) asm volatile("s_waitcnt vmcnt(" #n ")" ::: "memory")
; #define PG8_WAIT_L(n) asm volatile("s_waitcnt lgkmcnt(" #n ")" ::: "memory")
; #define PG8_BAR __builtin_amdgcn_s_barrier()
; #define PG8_SCHED __builtin_amdgcn_sched_barrier(0)
; template <class Epi, class Sched, bool ALIGN_EPI = false, bool SP2 = false>
; __device__ __forceinline__ void gemm_phase(PG8_LAS unsigned char* lds, const Gemm g, const Sched& S, const Epi& E) {
;     ...
;             PG8_LDB(B0, 1, 0); PG8_LDB(B1, 1, 1); PG8_SCHED; PG8_LDA(At, 1, 0); PG8_STAGE(PG8_SA(0, 1), a2 + hstep, voffA);
;             PG8_WAIT_V(8); PG8_WAIT_L(0); PG8_BAR; PG8_MMA(0, 0, At, B0); PG8_MMA(0, 1, At, B1); PG8_BAR; PG8_SCHED;
;             PG8_LDA(At, 1, 1); PG8_STAGE(PG8_SB(1, 0), b3, voffB); PG8_STAGE(PG8_SB(1, 1), b3 + hstep, voffB); PG8_STAGE(PG8_SA(1, 0), a3, voffA);
;             PG8_WAIT_V(8); PG8_WAIT_L(0); PG8_BAR; PG8_MMA(1, 0, At, B0); PG8_MMA(1, 1, At, B1); PG8_BAR; PG8_SCHED;
	s_add_i32 s33, 0, 0x18000
	s_add_i32 s42, 0, 0x1c000
	ds_read_b128 v[148:151], v241 offset:32768
	ds_read_b128 v[156:159], v241 offset:33792
	ds_read_b128 v[166:169], v241 offset:34816
	ds_read_b128 v[170:173], v241 offset:35840
	ds_read_b128 v[174:177], v241 offset:49152
	ds_read_b128 v[178:181], v241 offset:50176
	ds_read_b128 v[182:185], v241 offset:51200
	ds_read_b128 v[186:189], v241 offset:52224
	s_add_u32 s24, s24, 0x100000
	s_addc_u32 s25, s25, 0
	s_mov_b32 m0, s36
	ds_read_b128 v[190:193], v155 offset:32768
	ds_read_b128 v[194:197], v155 offset:33792
	ds_read_b128 v[198:201], v155 offset:34816
	ds_read_b128 v[202:205], v155 offset:35840
	ds_read_b128 v[206:209], v155 offset:36864
	ds_read_b128 v[210:213], v155 offset:37888
	ds_read_b128 v[214:217], v155 offset:38912
	ds_read_b128 v[218:221], v155 offset:39936
	global_load_lds_dwordx4 v130, s[24:25]
	s_mov_b32 m0, s37
	s_nop 0
	global_load_lds_dwordx4 v134, s[24:25]
	s_waitcnt vmcnt(8)
	s_waitcnt lgkmcnt(0)
	s_barrier
	s_waitcnt lgkmcnt(0)
	v_mfma_f32_16x16x32_bf16 v[118:121], v[148:151], v[190:193], v[118:121]
	v_mfma_f32_16x16x32_bf16 v[118:121], v[156:159], v[194:197], v[118:121]
	v_mfma_f32_16x16x32_bf16 v[102:105], v[156:159], v[202:205], v[102:105]
	v_mfma_f32_16x16x32_bf16 v[102:105], v[148:151], v[198:201], v[102:105]
	v_mfma_f32_16x16x32_bf16 v[86:89], v[148:151], v[206:209], v[86:89]
	v_mfma_f32_16x16x32_bf16 v[86:89], v[156:159], v[210:213], v[86:89]
	v_mfma_f32_16x16x32_bf16 v[70:73], v[156:159], v[218:221], v[70:73]
	v_mfma_f32_16x16x32_bf16 v[70:73], v[148:151], v[214:217], v[70:73]
	v_mfma_f32_16x16x32_bf16 v[66:69], v[166:169], v[214:217], v[66:69]
	v_mfma_f32_16x16x32_bf16 v[66:69], v[170:173], v[218:221], v[66:69]
	v_mfma_f32_16x16x32_bf16 v[82:85], v[170:173], v[210:213], v[82:85]
	v_mfma_f32_16x16x32_bf16 v[82:85], v[166:169], v[206:209], v[82:85]
	v_mfma_f32_16x16x32_bf16 v[98:101], v[166:169], v[198:201], v[98:101]
	v_mfma_f32_16x16x32_bf16 v[98:101], v[170:173], v[202:205], v[98:101]
	v_mfma_f32_16x16x32_bf16 v[114:117], v[170:173], v[194:197], v[114:117]
	v_mfma_f32_16x16x32_bf16 v[114:117], v[166:169], v[190:193], v[114:117]
	v_mfma_f32_16x16x32_bf16 v[126:129], v[174:177], v[190:193], v[126:129]
	v_mfma_f32_16x16x32_bf16 v[126:129], v[178:181], v[194:197], v[126:129]
	v_mfma_f32_16x16x32_bf16 v[110:113], v[178:181], v[202:205], v[110:113]
	v_mfma_f32_16x16x32_bf16 v[110:113], v[174:177], v[198:201], v[110:113]
	v_mfma_f32_16x16x32_bf16 v[94:97], v[174:177], v[206:209], v[94:97]
	v_mfma_f32_16x16x32_bf16 v[94:97], v[178:181], v[210:213], v[94:97]
	v_mfma_f32_16x16x32_bf16 v[78:81], v[178:181], v[218:221], v[78:81]
	v_mfma_f32_16x16x32_bf16 v[78:81], v[174:177], v[214:217], v[78:81]
	v_mfma_f32_16x16x32_bf16 v[74:77], v[182:185], v[214:217], v[74:77]
	v_mfma_f32_16x16x32_bf16 v[74:77], v[186:189], v[218:221], v[74:77]
	v_mfma_f32_16x16x32_bf16 v[90:93], v[186:189], v[210:213], v[90:93]
	v_mfma_f32_16x16x32_bf16 v[90:93], v[182:185], v[206:209], v[90:93]
	v_mfma_f32_16x16x32_bf16 v[106:109], v[182:185], v[198:201], v[106:109]
	v_mfma_f32_16x16x32_bf16 v[106:109], v[186:189], v[202:205], v[106:109]
	v_mfma_f32_16x16x32_bf16 v[122:125], v[186:189], v[194:197], v[122:125]
	v_mfma_f32_16x16x32_bf16 v[122:125], v[182:185], v[190:193], v[122:125]
	s_barrier
	s_add_i32 s24, s33, s28
	s_add_i32 m0, s24, 0xffffff80
	ds_read_b128 v[190:193], v155 offset:49152
	ds_read_b128 v[194:197], v155 offset:50176
	ds_read_b128 v[198:201], v155 offset:51200
	ds_read_b128 v[202:205], v155 offset:52224
	ds_read_b128 v[206:209], v155 offset:53248
	ds_read_b128 v[210:213], v155 offset:54272
	ds_read_b128 v[214:217], v155 offset:55296
	ds_read_b128 v[218:221], v155 offset:56320
	global_load_lds_dwordx4 v132, s[20:21] offset:128
	s_add_i32 m0, s24, 0x1f80
	s_add_i32 s24, s42, s28
	global_load_lds_dwordx4 v136, s[20:21] offset:128
	s_add_u32 s20, s20, 0x100080
	s_addc_u32 s21, s21, 0
	s_mov_b32 m0, s24
	s_nop 0
	global_load_lds_dwordx4 v132, s[20:21]
	s_add_i32 m0, s24, 0x2000
	s_nop 0
	global_load_lds_dwordx4 v136, s[20:21]
	s_mov_b32 m0, s43
	s_nop 0
	global_load_lds_dwordx4 v130, s[100:101]
	s_mov_b32 m0, s46
	s_nop 0
	global_load_lds_dwordx4 v134, s[100:101]
	s_waitcnt vmcnt(8)
	s_waitcnt lgkmcnt(0)
	s_barrier
; __device__ __forceinline__ float ssq_rstd(const ssq_t* ssq, int row) { return __builtin_amdgcn_rsqf((float)ssq[row] * (SSQ_UNFIX * RMS_INV_D) + RMS_EPS); }
; #define PG8_STAGE(bufoff, gbase, voff) do { _Pragma("unroll") for (int _i = 0; _i < 2; ++_i) \
;         __builtin_amdgcn_global_load_lds((const unsigned*)((const char*)(gbase) + (voff)[_i]), (PG8_LAS unsigned*)(lds + (bufoff) + ldsw + _i * 8192), 16, 0, 0); } while (0)
; #define PG8_LDA(dst, b, h) do { _Pragma("unroll") for (int m = 0; m < 4; ++m) _Pragma("unroll") for (int k = 0; k < 2; ++k) dst[m][k] = *(const PG8_LAS bf16x8*)(lds + PG8_SA(b, h) + aoff + m * 2048 + k * 1024); } while (0)
; #define PG8_MMA(ai, bj, At, Bt) do { __builtin_amdgcn_s_setprio(1); _Pragma("unroll") for (int m = 0; m < 4; ++m) _Pragma("unroll") for (int n = 0; n < 2; ++n) _Pragma("unroll") for (int k = 0; k < 2; ++k) \
;         acc[ai][bj][m][n] = __builtin_amdgcn_mfma_f32_16x16x32_bf16(Bt[n][k], At[m][k], acc[ai][bj][m][n], 0, 0, 0); __builtin_amdgcn_s_setprio(0); } while (0)
; #define PG8_WAIT_V(n) asm volatile("s_waitcnt vmcnt(" #n ")" ::: "memory")
; #define PG8_WAIT_L(n) asm volatile("s_waitcnt lgkmcnt(" #n ")" ::: "memory")
; #define PG8_BAR __builtin_amdgcn_s_barrier()
; #define PG8_SCHED __builtin_amdgcn_sched_barrier(0)
;     __device__ __forceinline__ void operator()(const f32x4 (&acc)[2][2][4][2], const Unit& u, int wr, int wc, int fr, int fq) const {
;         const int row0 = u.pm * BM + wr * 64 + fr, col0 = u.pn * BM + wc * 32 + 8 * fq;
;         float rs[2][4];
; #pragma unroll
;         for (int ai = 0; ai < 2; ++ai)
; #pragma unroll
;             for (int m = 0; m < 4; ++m) rs[ai][m] = SCALE ? ssq_rstd(ssq, row0 + ai * HALF + m * 16) : 1.0f;
; template <class Epi, class Sched, bool ALIGN_EPI = false, bool SP2 = false>
; __device__ __forceinline__ void gemm_phase(PG8_LAS unsigned char* lds, const Gemm g, const Sched& S, const Epi& E) {
;     ...
;             PG8_WAIT_V(8); PG8_WAIT_L(0); PG8_BAR; PG8_MMA(0, 0, At, B0); PG8_MMA(0, 1, At, B1); PG8_BAR; PG8_SCHED;
;             PG8_LDA(At, 1, 1); PG8_STAGE(PG8_SB(1, 0), b3, voffB); PG8_STAGE(PG8_SB(1, 1), b3 + hstep, voffB); PG8_STAGE(PG8_SA(1, 0), a3, voffA);
;             PG8_WAIT_V(8); PG8_WAIT_L(0); PG8_BAR; PG8_MMA(1, 0, At, B0); PG8_MMA(1, 1, At, B1); PG8_BAR; PG8_SCHED;
	s_waitcnt lgkmcnt(0)
	v_mfma_f32_16x16x32_bf16 v[54:57], v[148:151], v[190:193], v[54:57]
	v_mfma_f32_16x16x32_bf16 v[54:57], v[156:159], v[194:197], v[54:57]
	v_mfma_f32_16x16x32_bf16 v[38:41], v[156:159], v[202:205], v[38:41]
	v_mfma_f32_16x16x32_bf16 v[38:41], v[148:151], v[198:201], v[38:41]
	v_mfma_f32_16x16x32_bf16 v[22:25], v[148:151], v[206:209], v[22:25]
	v_mfma_f32_16x16x32_bf16 v[22:25], v[156:159], v[210:213], v[22:25]
	v_mfma_f32_16x16x32_bf16 v[6:9], v[156:159], v[218:221], v[6:9]
	v_mfma_f32_16x16x32_bf16 v[6:9], v[148:151], v[214:217], v[6:9]
	v_mfma_f32_16x16x32_bf16 v[2:5], v[166:169], v[214:217], v[2:5]
	v_mfma_f32_16x16x32_bf16 v[2:5], v[170:173], v[218:221], v[2:5]
	v_mfma_f32_16x16x32_bf16 v[18:21], v[170:173], v[210:213], v[18:21]
	v_mfma_f32_16x16x32_bf16 v[18:21], v[166:169], v[206:209], v[18:21]
	v_mfma_f32_16x16x32_bf16 v[34:37], v[166:169], v[198:201], v[34:37]
	v_mfma_f32_16x16x32_bf16 v[34:37], v[170:173], v[202:205], v[34:37]
	v_mfma_f32_16x16x32_bf16 v[50:53], v[170:173], v[194:197], v[50:53]
	v_mfma_f32_16x16x32_bf16 v[50:53], v[166:169], v[190:193], v[50:53]
	v_mfma_f32_16x16x32_bf16 v[62:65], v[174:177], v[190:193], v[62:65]
	v_mfma_f32_16x16x32_bf16 v[62:65], v[178:181], v[194:197], v[62:65]
	v_mfma_f32_16x16x32_bf16 v[46:49], v[178:181], v[202:205], v[46:49]
	v_mfma_f32_16x16x32_bf16 v[46:49], v[174:177], v[198:201], v[46:49]
	v_mfma_f32_16x16x32_bf16 v[30:33], v[174:177], v[206:209], v[30:33]
	v_mfma_f32_16x16x32_bf16 v[30:33], v[178:181], v[210:213], v[30:33]
	v_mfma_f32_16x16x32_bf16 v[10:13], v[178:181], v[218:221], v[10:13]
	v_mfma_f32_16x16x32_bf16 v[10:13], v[174:177], v[214:217], v[10:13]
	v_mfma_f32_16x16x32_bf16 v[14:17], v[182:185], v[214:217], v[14:17]
	v_mfma_f32_16x16x32_bf16 v[14:17], v[186:189], v[218:221], v[14:17]
	v_mfma_f32_16x16x32_bf16 v[26:29], v[186:189], v[210:213], v[26:29]
	v_mfma_f32_16x16x32_bf16 v[26:29], v[182:185], v[206:209], v[26:29]
	v_mfma_f32_16x16x32_bf16 v[42:45], v[182:185], v[198:201], v[42:45]
	v_mfma_f32_16x16x32_bf16 v[42:45], v[186:189], v[202:205], v[42:45]
	v_mfma_f32_16x16x32_bf16 v[58:61], v[186:189], v[194:197], v[58:61]
	v_mfma_f32_16x16x32_bf16 v[58:61], v[182:185], v[190:193], v[58:61]
	s_barrier
	s_add_i32 s67, s67, 2
	s_add_u32 s22, s22, 0x100
	s_addc_u32 s23, s23, 0
	s_add_u32 s65, s65, 0x100
	s_addc_u32 s66, s66, 0
	s_cmp_gt_u32 s67, 61
	s_cbranch_scc0 .LBB0_1332
	s_and_b64 vcc, exec, s[8:9]
	s_cbranch_vccz .LBB0_1335
	v_lshl_add_u32 v150, s18, 8, v1
	v_ashrrev_i32_e32 v151, 31, v150
	v_or_b32_e32 v162, 16, v150
	v_or_b32_e32 v158, 32, v150
	v_or_b32_e32 v156, 48, v150
	v_lshl_add_u64 v[148:149], v[150:151], 3, s[4:5]
	v_ashrrev_i32_e32 v163, 31, v162
	v_ashrrev_i32_e32 v159, 31, v158
	v_ashrrev_i32_e32 v157, 31, v156
	v_lshl_add_u64 v[166:167], v[162:163], 3, s[4:5]
	v_lshl_add_u64 v[168:169], v[158:159], 3, s[4:5]
	global_load_dwordx2 v[170:171], v[148:149], off
	global_load_dwordx2 v[172:173], v[148:149], off offset:1024
	global_load_dwordx2 v[174:175], v[148:149], off offset:1152
	global_load_dwordx2 v[176:177], v[148:149], off offset:1280
	v_lshl_add_u64 v[178:179], v[156:157], 3, s[4:5]
	global_load_dwordx2 v[166:167], v[166:167], off
	s_nop 0
	global_load_dwordx2 v[168:169], v[168:169], off
	s_nop 0
	global_load_dwordx2 v[178:179], v[178:179], off
	s_nop 0
	global_load_dwordx2 v[148:149], v[148:149], off offset:1408
	s_barrier
	s_branch .Lepi_rest_1335

; __device__ __forceinline__ unsigned cvt_pk_bf16(float lo, float hi) { unsigned r; asm volatile("v_cvt_pk_bf16_f32 %0, %1, %2" : "=v"(r) : "v"(lo), "v"(hi)); return r; }
; __device__ __forceinline__ unsigned cvt_pk_bf16(float lo, float hi) { unsigned r; asm volatile("v_cvt_pk_bf16_f32 %0, %1, %2" : "=v"(r) : "v"(lo), "v"(hi)); return r; }
; __device__ __forceinline__ float ssq_rstd(const ssq_t* ssq, int row) { return __builtin_amdgcn_rsqf((float)ssq[row] * (SSQ_UNFIX * RMS_INV_D) + RMS_EPS); }
;     __device__ __forceinline__ void operator()(const f32x4 (&acc)[2][2][4][2], const Unit& u, int wr, int wc, int fr, int fq) const {
;         const int row0 = u.pm * BM + wr * 64 + fr, col0 = u.pn * BM + wc * 32 + 8 * fq;
;         float rs[2][4];
; #pragma unroll
;         for (int ai = 0; ai < 2; ++ai)
; #pragma unroll
;             for (int m = 0; m < 4; ++m) rs[ai][m] = SCALE ? ssq_rstd(ssq, row0 + ai * HALF + m * 16) : 1.0f;
; #pragma unroll
;         for (int ai = 0; ai < 2; ++ai)
; #pragma unroll
;             for (int m = 0; m < 4; ++m) { const int row = row0 + ai * HALF + m * 16; bf16_t* rowp = O + (size_t)row * ldc + col0;
; #pragma unroll
;                 for (int bj = 0; bj < 2; ++bj) { const f32x2 r2 = {rs[ai][m], rs[ai][m]}; const f32x4 a0 = acc[ai][bj][m][0], a1 = acc[ai][bj][m][1];
;                     const f32x2 p0 = (f32x2){a0[0], a0[1]} * r2, p1 = (f32x2){a0[2], a0[3]} * r2, p2 = (f32x2){a1[0], a1[1]} * r2, p3 = (f32x2){a1[2], a1[3]} * r2;
;                     u32x4 w; w.x = cvt_pk_bf16(p0.x, p0.y); w.y = cvt_pk_bf16(p1.x, p1.y); w.z = cvt_pk_bf16(p2.x, p2.y); w.w = cvt_pk_bf16(p3.x, p3.y);
;                     *(u32x4*)(rowp + bj * HALF) = w; } }
.Lepi_rest_1335:
	v_add_u32_e32 v157, 0x80, v150
	v_add_u32_e32 v159, 0x90, v150
	v_add_u32_e32 v163, 0xa0, v150
	s_andn2_b64 vcc, exec, s[0:1]
	s_mov_b64 s[0:1], -1
	s_waitcnt vmcnt(0)
	v_ffbh_u32_e32 v146, v171
	v_min_u32_e32 v146, 32, v146
	v_ffbh_u32_e32 v160, v167
	v_lshlrev_b64 v[170:171], v146, v[170:171]
	v_min_u32_e32 v160, 32, v160
	v_ffbh_u32_e32 v165, v169
	v_ffbh_u32_e32 v180, v179
	v_min_u32_e32 v170, 1, v170
	v_lshlrev_b64 v[166:167], v160, v[166:167]
	v_min_u32_e32 v165, 32, v165
	v_min_u32_e32 v180, 32, v180
	v_or_b32_e32 v170, v171, v170
	v_min_u32_e32 v166, 1, v166
	v_lshlrev_b64 v[168:169], v165, v[168:169]
	v_lshlrev_b64 v[178:179], v180, v[178:179]
	v_cvt_f32_u32_e32 v170, v170
	v_or_b32_e32 v166, v167, v166
	v_min_u32_e32 v168, 1, v168
	v_min_u32_e32 v171, 1, v178
	v_cvt_f32_u32_e32 v166, v166
	v_ffbh_u32_e32 v151, v173
	v_or_b32_e32 v167, v169, v168
	v_or_b32_e32 v168, v179, v171
	v_min_u32_e32 v151, 32, v151
	v_ffbh_u32_e32 v181, v149
	v_sub_u32_e32 v146, 32, v146
	v_cvt_f32_u32_e32 v167, v167
	v_cvt_f32_u32_e32 v168, v168
	v_lshlrev_b64 v[172:173], v151, v[172:173]
	v_min_u32_e32 v181, 32, v181
	v_sub_u32_e32 v160, 32, v160
	v_ldexp_f32 v146, v170, v146
	v_min_u32_e32 v172, 1, v172
	v_lshlrev_b64 v[148:149], v181, v[148:149]
	v_fmamk_f32 v146, v146, 0x2d800000, v161
	v_ldexp_f32 v160, v166, v160
	v_ffbh_u32_e32 v152, v175
	v_ffbh_u32_e32 v154, v177
	v_sub_u32_e32 v165, 32, v165
	v_sub_u32_e32 v180, 32, v180
	v_or_b32_e32 v172, v173, v172
	v_min_u32_e32 v148, 1, v148
	v_rsq_f32_e32 v166, v146
	v_fmamk_f32 v146, v160, 0x2d800000, v161
	v_min_u32_e32 v152, 32, v152
	v_min_u32_e32 v154, 32, v154
	v_cvt_f32_u32_e32 v169, v172
	v_ldexp_f32 v165, v167, v165
	v_ldexp_f32 v167, v168, v180
	v_rsq_f32_e32 v168, v146
	v_or_b32_e32 v146, v149, v148
	v_lshlrev_b64 v[174:175], v152, v[174:175]
	v_lshlrev_b64 v[176:177], v154, v[176:177]
	v_cvt_f32_u32_e32 v146, v146
	v_min_u32_e32 v174, 1, v174
	v_min_u32_e32 v176, 1, v176
	v_sub_u32_e32 v151, 32, v151
	v_or_b32_e32 v173, v175, v174
	v_or_b32_e32 v174, v177, v176
	v_cvt_f32_u32_e32 v172, v174
	v_ldexp_f32 v151, v169, v151
	v_sub_u32_e32 v148, 32, v181
	v_lshl_or_b32 v174, s62, 8, v153
	v_fmamk_f32 v151, v151, 0x2d800000, v161
	v_fmamk_f32 v165, v165, 0x2d800000, v161
	v_ldexp_f32 v146, v146, v148
	v_ashrrev_i32_e32 v175, 31, v174
	v_mov_b64_e32 v[148:149], s[38:39]
	v_fmamk_f32 v167, v167, 0x2d800000, v161
	v_rsq_f32_e32 v160, v151
	v_rsq_f32_e32 v170, v165
	v_add_u32_e32 v165, 0xb0, v150
	v_mad_i64_i32 v[176:177], s[20:21], v150, s53, v[148:149]
	v_lshlrev_b64 v[150:151], 1, v[174:175]
	v_lshl_add_u64 v[174:175], v[176:177], 0, v[150:151]
	v_pk_mul_f32 v[118:119], v[118:119], v[166:167] op_sel_hi:[1,0]
	v_pk_mul_f32 v[120:121], v[120:121], v[166:167] op_sel_hi:[1,0]
	v_pk_mul_f32 v[176:177], v[114:115], v[166:167] op_sel_hi:[1,0]
	v_cvt_pk_bf16_f32 v114, v118, v119
	v_cvt_pk_bf16_f32 v115, v120, v121
	v_sub_u32_e32 v154, 32, v154
	v_pk_mul_f32 v[178:179], v[116:117], v[166:167] op_sel_hi:[1,0]
	v_cvt_pk_bf16_f32 v116, v176, v177
	v_ldexp_f32 v154, v172, v154
	v_cvt_pk_bf16_f32 v117, v178, v179
	global_store_dwordx4 v[174:175], v[114:117], off
	v_fmamk_f32 v169, v154, 0x2d800000, v161
	v_pk_mul_f32 v[118:119], v[122:123], v[166:167] op_sel_hi:[1,0]
	v_pk_mul_f32 v[114:115], v[126:127], v[166:167] op_sel_hi:[1,0]
	v_pk_mul_f32 v[116:117], v[128:129], v[166:167] op_sel_hi:[1,0]
	v_cvt_pk_bf16_f32 v114, v114, v115
	v_pk_mul_f32 v[120:121], v[124:125], v[166:167] op_sel_hi:[1,0]
	v_cvt_pk_bf16_f32 v115, v116, v117
	v_cvt_pk_bf16_f32 v116, v118, v119
	v_cvt_f32_u32_e32 v171, v173
	v_cvt_pk_bf16_f32 v117, v120, v121
	global_store_dwordx4 v[174:175], v[114:117], off offset:256
	v_pk_mul_f32 v[102:103], v[102:103], v[168:169] op_sel_hi:[1,0]
	v_pk_mul_f32 v[104:105], v[104:105], v[168:169] op_sel_hi:[1,0]
	v_mad_i64_i32 v[114:115], s[20:21], v162, s53, v[148:149]
	v_lshl_add_u64 v[114:115], v[114:115], 0, v[150:151]
	v_pk_mul_f32 v[116:117], v[98:99], v[168:169] op_sel_hi:[1,0]
	v_cvt_pk_bf16_f32 v98, v102, v103
	v_cvt_pk_bf16_f32 v99, v104, v105
	v_pk_mul_f32 v[118:119], v[100:101], v[168:169] op_sel_hi:[1,0]
	v_cvt_pk_bf16_f32 v100, v116, v117
	v_pk_mul_f32 v[102:103], v[106:107], v[168:169] op_sel_hi:[1,0]
	v_cvt_pk_bf16_f32 v101, v118, v119
	global_store_dwordx4 v[114:115], v[98:101], off
	v_pk_mul_f32 v[104:105], v[108:109], v[168:169] op_sel_hi:[1,0]
	v_rsq_f32_e32 v172, v167
	v_pk_mul_f32 v[98:99], v[110:111], v[168:169] op_sel_hi:[1,0]
	v_pk_mul_f32 v[100:101], v[112:113], v[168:169] op_sel_hi:[1,0]
	v_cvt_pk_bf16_f32 v98, v98, v99
	v_pk_mul_f32 v[86:87], v[86:87], v[170:171] op_sel_hi:[1,0]
	v_cvt_pk_bf16_f32 v99, v100, v101
	v_cvt_pk_bf16_f32 v100, v102, v103
	v_cvt_pk_bf16_f32 v101, v104, v105
	global_store_dwordx4 v[114:115], v[98:101], off offset:256
	v_pk_mul_f32 v[88:89], v[88:89], v[170:171] op_sel_hi:[1,0]
	v_pk_mul_f32 v[102:103], v[84:85], v[170:171] op_sel_hi:[1,0]
	v_mad_i64_i32 v[98:99], s[20:21], v158, s53, v[148:149]
	v_lshl_add_u64 v[98:99], v[98:99], 0, v[150:151]
	v_pk_mul_f32 v[100:101], v[82:83], v[170:171] op_sel_hi:[1,0]
	v_cvt_pk_bf16_f32 v82, v86, v87
	v_cvt_pk_bf16_f32 v83, v88, v89
	v_pk_mul_f32 v[86:87], v[90:91], v[170:171] op_sel_hi:[1,0]
	v_cvt_pk_bf16_f32 v84, v100, v101
	v_cvt_pk_bf16_f32 v85, v102, v103
	global_store_dwordx4 v[98:99], v[82:85], off
	v_pk_mul_f32 v[88:89], v[92:93], v[170:171] op_sel_hi:[1,0]
	v_pk_mul_f32 v[70:71], v[70:71], v[172:173] op_sel_hi:[1,0]
	v_pk_mul_f32 v[82:83], v[94:95], v[170:171] op_sel_hi:[1,0]
	v_pk_mul_f32 v[84:85], v[96:97], v[170:171] op_sel_hi:[1,0]
	v_cvt_pk_bf16_f32 v82, v82, v83
; __device__ __forceinline__ unsigned cvt_pk_bf16(float lo, float hi) { unsigned r; asm volatile("v_cvt_pk_bf16_f32 %0, %1, %2" : "=v"(r) : "v"(lo), "v"(hi)); return r; }
; __device__ __forceinline__ unsigned cvt_pk_bf16(float lo, float hi) { unsigned r; asm volatile("v_cvt_pk_bf16_f32 %0, %1, %2" : "=v"(r) : "v"(lo), "v"(hi)); return r; }
; #define PG8_BAR __builtin_amdgcn_s_barrier()
;     __device__ __forceinline__ void operator()(const f32x4 (&acc)[2][2][4][2], const Unit& u, int wr, int wc, int fr, int fq) const {
;     ...
;             for (int m = 0; m < 4; ++m) { const int row = row0 + ai * HALF + m * 16; bf16_t* rowp = O + (size_t)row * ldc + col0;
; #pragma unroll
;                 for (int bj = 0; bj < 2; ++bj) { const f32x2 r2 = {rs[ai][m], rs[ai][m]}; const f32x4 a0 = acc[ai][bj][m][0], a1 = acc[ai][bj][m][1];
;                     const f32x2 p0 = (f32x2){a0[0], a0[1]} * r2, p1 = (f32x2){a0[2], a0[3]} * r2, p2 = (f32x2){a1[0], a1[1]} * r2, p3 = (f32x2){a1[2], a1[3]} * r2;
;                     u32x4 w; w.x = cvt_pk_bf16(p0.x, p0.y); w.y = cvt_pk_bf16(p1.x, p1.y); w.z = cvt_pk_bf16(p2.x, p2.y); w.w = cvt_pk_bf16(p3.x, p3.y);
;                     *(u32x4*)(rowp + bj * HALF) = w; } }
; template <class Epi, class Sched, bool ALIGN_EPI = false, bool SP2 = false>
; __device__ __forceinline__ void gemm_phase(PG8_LAS unsigned char* lds, const Gemm g, const Sched& S, const Epi& E) {
;     ...
; #pragma unroll
;         for (int a = 0; a < 2; ++a)
; #pragma unroll
;             for (int b = 0; b < 2; ++b)
; #pragma unroll
;                 for (int m = 0; m < 4; ++m)
; #pragma unroll
;                     for (int n = 0; n < 2; ++n) { d64x2 z_; asm volatile("v_mov_b64 %0, 0\n\tv_mov_b64 %1, 0" : "=v"(z_.x), "=v"(z_.y)); acc[a][b][m][n] = __builtin_bit_cast(f32x4, z_); }
;         cur = nxt; cA = nA; cB = nB; ++ui;
;         if constexpr (ALIGN_EPI) { if (wr == 1) PG8_BAR; }
	v_pk_mul_f32 v[72:73], v[72:73], v[172:173] op_sel_hi:[1,0]
	v_cvt_pk_bf16_f32 v83, v84, v85
	v_cvt_pk_bf16_f32 v84, v86, v87
	v_cvt_pk_bf16_f32 v85, v88, v89
	global_store_dwordx4 v[98:99], v[82:85], off offset:256
	v_sub_u32_e32 v152, 32, v152
	v_pk_mul_f32 v[86:87], v[68:69], v[172:173] op_sel_hi:[1,0]
	v_mad_i64_i32 v[82:83], s[20:21], v156, s53, v[148:149]
	v_lshl_add_u64 v[82:83], v[82:83], 0, v[150:151]
	v_pk_mul_f32 v[84:85], v[66:67], v[172:173] op_sel_hi:[1,0]
	v_cvt_pk_bf16_f32 v66, v70, v71
	v_cvt_pk_bf16_f32 v67, v72, v73
	v_ldexp_f32 v152, v171, v152
	v_cvt_pk_bf16_f32 v68, v84, v85
	v_cvt_pk_bf16_f32 v69, v86, v87
	global_store_dwordx4 v[82:83], v[66:69], off
	v_fmamk_f32 v152, v152, 0x2d800000, v161
	v_pk_mul_f32 v[70:71], v[74:75], v[172:173] op_sel_hi:[1,0]
	v_pk_mul_f32 v[66:67], v[78:79], v[172:173] op_sel_hi:[1,0]
	v_pk_mul_f32 v[68:69], v[80:81], v[172:173] op_sel_hi:[1,0]
	v_cvt_pk_bf16_f32 v66, v66, v67
	v_pk_mul_f32 v[72:73], v[76:77], v[172:173] op_sel_hi:[1,0]
	v_cvt_pk_bf16_f32 v67, v68, v69
	v_cvt_pk_bf16_f32 v68, v70, v71
	v_rsq_f32_e32 v154, v152
	v_cvt_pk_bf16_f32 v69, v72, v73
	global_store_dwordx4 v[82:83], v[66:69], off offset:256
	v_pk_mul_f32 v[54:55], v[54:55], v[160:161] op_sel_hi:[1,0]
	v_pk_mul_f32 v[56:57], v[56:57], v[160:161] op_sel_hi:[1,0]
	v_mad_i64_i32 v[66:67], s[20:21], v157, s53, v[148:149]
	v_lshl_add_u64 v[66:67], v[66:67], 0, v[150:151]
	v_pk_mul_f32 v[68:69], v[50:51], v[160:161] op_sel_hi:[1,0]
	v_cvt_pk_bf16_f32 v50, v54, v55
	v_cvt_pk_bf16_f32 v51, v56, v57
	v_pk_mul_f32 v[70:71], v[52:53], v[160:161] op_sel_hi:[1,0]
	v_cvt_pk_bf16_f32 v52, v68, v69
	v_pk_mul_f32 v[54:55], v[58:59], v[160:161] op_sel_hi:[1,0]
	v_cvt_pk_bf16_f32 v53, v70, v71
	global_store_dwordx4 v[66:67], v[50:53], off
	v_pk_mul_f32 v[56:57], v[60:61], v[160:161] op_sel_hi:[1,0]
	v_rsq_f32_e32 v152, v169
	v_pk_mul_f32 v[50:51], v[62:63], v[160:161] op_sel_hi:[1,0]
	v_pk_mul_f32 v[52:53], v[64:65], v[160:161] op_sel_hi:[1,0]
	v_cvt_pk_bf16_f32 v50, v50, v51
	v_pk_mul_f32 v[38:39], v[38:39], v[154:155] op_sel_hi:[1,0]
	v_cvt_pk_bf16_f32 v51, v52, v53
	v_cvt_pk_bf16_f32 v52, v54, v55
	v_cvt_pk_bf16_f32 v53, v56, v57
	global_store_dwordx4 v[66:67], v[50:53], off offset:256
	v_pk_mul_f32 v[40:41], v[40:41], v[154:155] op_sel_hi:[1,0]
	v_pk_mul_f32 v[54:55], v[36:37], v[154:155] op_sel_hi:[1,0]
	v_mad_i64_i32 v[50:51], s[20:21], v159, s53, v[148:149]
	v_lshl_add_u64 v[50:51], v[50:51], 0, v[150:151]
	v_pk_mul_f32 v[52:53], v[34:35], v[154:155] op_sel_hi:[1,0]
	v_cvt_pk_bf16_f32 v34, v38, v39
	v_cvt_pk_bf16_f32 v35, v40, v41
	v_fmamk_f32 v146, v146, 0x2d800000, v161
	v_cvt_pk_bf16_f32 v36, v52, v53
	v_cvt_pk_bf16_f32 v37, v54, v55
	global_store_dwordx4 v[50:51], v[34:37], off
	v_pk_mul_f32 v[38:39], v[42:43], v[154:155] op_sel_hi:[1,0]
	v_pk_mul_f32 v[40:41], v[44:45], v[154:155] op_sel_hi:[1,0]
	v_pk_mul_f32 v[34:35], v[46:47], v[154:155] op_sel_hi:[1,0]
	v_pk_mul_f32 v[36:37], v[48:49], v[154:155] op_sel_hi:[1,0]
	v_cvt_pk_bf16_f32 v34, v34, v35
	v_rsq_f32_e32 v146, v146
	v_cvt_pk_bf16_f32 v35, v36, v37
	v_cvt_pk_bf16_f32 v36, v38, v39
	v_cvt_pk_bf16_f32 v37, v40, v41
	global_store_dwordx4 v[50:51], v[34:37], off offset:256
	v_pk_mul_f32 v[22:23], v[22:23], v[152:153] op_sel_hi:[1,0]
	v_pk_mul_f32 v[24:25], v[24:25], v[152:153] op_sel_hi:[1,0]
	v_mad_i64_i32 v[34:35], s[20:21], v163, s53, v[148:149]
	v_lshl_add_u64 v[34:35], v[34:35], 0, v[150:151]
	v_pk_mul_f32 v[36:37], v[18:19], v[152:153] op_sel_hi:[1,0]
	v_cvt_pk_bf16_f32 v18, v22, v23
	v_cvt_pk_bf16_f32 v19, v24, v25
	v_pk_mul_f32 v[38:39], v[20:21], v[152:153] op_sel_hi:[1,0]
	v_cvt_pk_bf16_f32 v20, v36, v37
	v_pk_mul_f32 v[22:23], v[26:27], v[152:153] op_sel_hi:[1,0]
	v_cvt_pk_bf16_f32 v21, v38, v39
	global_store_dwordx4 v[34:35], v[18:21], off
	v_pk_mul_f32 v[24:25], v[28:29], v[152:153] op_sel_hi:[1,0]
	v_pk_mul_f32 v[6:7], v[6:7], v[146:147] op_sel_hi:[1,0]
	v_pk_mul_f32 v[18:19], v[30:31], v[152:153] op_sel_hi:[1,0]
	v_pk_mul_f32 v[20:21], v[32:33], v[152:153] op_sel_hi:[1,0]
	v_cvt_pk_bf16_f32 v18, v18, v19
	v_pk_mul_f32 v[8:9], v[8:9], v[146:147] op_sel_hi:[1,0]
	v_cvt_pk_bf16_f32 v19, v20, v21
	v_cvt_pk_bf16_f32 v20, v22, v23
	v_cvt_pk_bf16_f32 v21, v24, v25
	global_store_dwordx4 v[34:35], v[18:21], off offset:256
	v_pk_mul_f32 v[22:23], v[4:5], v[146:147] op_sel_hi:[1,0]
	s_nop 0
	v_mad_i64_i32 v[18:19], s[20:21], v165, s53, v[148:149]
	v_lshl_add_u64 v[18:19], v[18:19], 0, v[150:151]
	v_pk_mul_f32 v[20:21], v[2:3], v[146:147] op_sel_hi:[1,0]
	v_cvt_pk_bf16_f32 v2, v6, v7
	v_cvt_pk_bf16_f32 v3, v8, v9
	v_pk_mul_f32 v[6:7], v[14:15], v[146:147] op_sel_hi:[1,0]
	v_cvt_pk_bf16_f32 v4, v20, v21
	v_cvt_pk_bf16_f32 v5, v22, v23
	global_store_dwordx4 v[18:19], v[2:5], off
	v_pk_mul_f32 v[8:9], v[16:17], v[146:147] op_sel_hi:[1,0]
	s_nop 0
	v_pk_mul_f32 v[2:3], v[10:11], v[146:147] op_sel_hi:[1,0]
	v_pk_mul_f32 v[4:5], v[12:13], v[146:147] op_sel_hi:[1,0]
	v_cvt_pk_bf16_f32 v2, v2, v3
	s_nop 0
	v_cvt_pk_bf16_f32 v3, v4, v5
	v_cvt_pk_bf16_f32 v4, v6, v7
	v_cvt_pk_bf16_f32 v5, v8, v9
	global_store_dwordx4 v[18:19], v[2:5], off offset:256
	s_cbranch_vccnz .LBB0_1328
	s_andn2_b64 vcc, exec, s[2:3]
	v_mov_b64 v[118:119], 0
	v_mov_b64 v[120:121], 0
	v_mov_b64 v[114:115], 0
	v_mov_b64 v[116:117], 0
	v_mov_b64 v[102:103], 0
	v_mov_b64 v[104:105], 0
	v_mov_b64 v[98:99], 0
	v_mov_b64 v[100:101], 0
	v_mov_b64 v[86:87], 0
	v_mov_b64 v[88:89], 0
	v_mov_b64 v[82:83], 0
	v_mov_b64 v[84:85], 0
	v_mov_b64 v[70:71], 0
	v_mov_b64 v[72:73], 0
	v_mov_b64 v[66:67], 0
	v_mov_b64 v[68:69], 0
	v_mov_b64 v[126:127], 0
	v_mov_b64 v[128:129], 0
	v_mov_b64 v[122:123], 0
	v_mov_b64 v[124:125], 0
	v_mov_b64 v[110:111], 0
	v_mov_b64 v[112:113], 0
	v_mov_b64 v[106:107], 0
	v_mov_b64 v[108:109], 0
	v_mov_b64 v[94:95], 0
	v_mov_b64 v[96:97], 0
	v_mov_b64 v[90:91], 0
	v_mov_b64 v[92:93], 0
	v_mov_b64 v[78:79], 0
	v_mov_b64 v[80:81], 0
	v_mov_b64 v[74:75], 0
	v_mov_b64 v[76:77], 0
	v_mov_b64 v[54:55], 0
	v_mov_b64 v[56:57], 0
	v_mov_b64 v[50:51], 0
	v_mov_b64 v[52:53], 0
	v_mov_b64 v[38:39], 0
	v_mov_b64 v[40:41], 0
	v_mov_b64 v[34:35], 0
	v_mov_b64 v[36:37], 0
	v_mov_b64 v[22:23], 0
	v_mov_b64 v[24:25], 0
	v_mov_b64 v[18:19], 0
	v_mov_b64 v[20:21], 0
	v_mov_b64 v[6:7], 0
	v_mov_b64 v[8:9], 0
	v_mov_b64 v[2:3], 0
	v_mov_b64 v[4:5], 0
	v_mov_b64 v[62:63], 0
	v_mov_b64 v[64:65], 0
	v_mov_b64 v[58:59], 0
	v_mov_b64 v[60:61], 0
	v_mov_b64 v[46:47], 0
	v_mov_b64 v[48:49], 0
	v_mov_b64 v[42:43], 0
	v_mov_b64 v[44:45], 0
	v_mov_b64 v[30:31], 0
	v_mov_b64 v[32:33], 0
	v_mov_b64 v[26:27], 0
	v_mov_b64 v[28:29], 0
	v_mov_b64 v[10:11], 0
	v_mov_b64 v[12:13], 0
	v_mov_b64 v[14:15], 0
	v_mov_b64 v[16:17], 0
	s_cbranch_vccnz .LBB0_1327
	s_barrier
	s_branch .LBB0_1327

; #define PG8_STAGE(bufoff, gbase, voff) do { _Pragma("unroll") for (int _i = 0; _i < 2; ++_i) \
;         __builtin_amdgcn_global_load_lds((const unsigned*)((const char*)(gbase) + (voff)[_i]), (PG8_LAS unsigned*)(lds + (bufoff) + ldsw + _i * 8192), 16, 0, 0); } while (0)
; #define PG8_LDA(dst, b, h) do { _Pragma("unroll") for (int m = 0; m < 4; ++m) _Pragma("unroll") for (int k = 0; k < 2; ++k) dst[m][k] = *(const PG8_LAS bf16x8*)(lds + PG8_SA(b, h) + aoff + m * 2048 + k * 1024); } while (0)
; #define PG8_LDB(dst, b, h) do { _Pragma("unroll") for (int n = 0; n < 2; ++n) _Pragma("unroll") for (int k = 0; k < 2; ++k) dst[n][k] = *(const PG8_LAS bf16x8*)(lds + PG8_SB(b, h) + boff + n * 2048 + k * 1024); } while (0)
; #define PG8_MMA(ai, bj, At, Bt) do { __builtin_amdgcn_s_setprio(1); _Pragma("unroll") for (int m = 0; m < 4; ++m) _Pragma("unroll") for (int n = 0; n < 2; ++n) _Pragma("unroll") for (int k = 0; k < 2; ++k) \
;         acc[ai][bj][m][n] = __builtin_amdgcn_mfma_f32_16x16x32_bf16(Bt[n][k], At[m][k], acc[ai][bj][m][n], 0, 0, 0); __builtin_amdgcn_s_setprio(0); } while (0)
; #define PG8_WAIT_V(n) asm volatile("s_waitcnt vmcnt(" #n ")" ::: "memory")
; #define PG8_WAIT_L(n) asm volatile("s_waitcnt lgkmcnt(" #n ")" ::: "memory")
; #define PG8_BAR __builtin_amdgcn_s_barrier()
; #define PG8_SCHED __builtin_amdgcn_sched_barrier(0)
; template <class Epi, class Sched, bool ALIGN_EPI = false, bool SP2 = false>
; __device__ __forceinline__ void gemm_phase(PG8_LAS unsigned char* lds, const Gemm g, const Sched& S, const Epi& E) {
;     ...
;             PG8_LDB(B0, 0, 0); PG8_LDB(B1, 0, 1); PG8_SCHED; PG8_LDA(At, 0, 0); PG8_STAGE(PG8_SA(1, 1), a1 + hstep, voffA);
;             PG8_WAIT_V(8); PG8_WAIT_L(0); PG8_BAR; PG8_MMA(0, 0, At, B0); PG8_MMA(0, 1, At, B1); PG8_BAR; PG8_SCHED;
;             PG8_LDA(At, 0, 1); PG8_STAGE(PG8_SB(0, 0), b2, voffB); PG8_STAGE(PG8_SB(0, 1), b2 + hstep, voffB); PG8_STAGE(PG8_SA(0, 0), a2, voffA);
;             PG8_WAIT_V(8); PG8_WAIT_L(0); PG8_BAR; PG8_MMA(1, 0, At, B0); PG8_MMA(1, 1, At, B1); PG8_BAR; PG8_SCHED;
.LBB0_1681:
	ds_read_b128 v[160:163], v241 offset:0
	ds_read_b128 v[166:169], v241 offset:1024
	ds_read_b128 v[170:173], v241 offset:2048
	ds_read_b128 v[174:177], v241 offset:3072
	ds_read_b128 v[178:181], v241 offset:16384
	ds_read_b128 v[182:185], v241 offset:17408
	ds_read_b128 v[186:189], v241 offset:18432
	ds_read_b128 v[190:193], v241 offset:19456
	s_add_u32 s22, s24, 0xfff00080
	s_addc_u32 s23, s25, -1
	s_cmp_eq_u32 s52, 60
	s_cselect_b32 s27, s15, s23
	s_cselect_b32 s26, s48, s22
	s_cselect_b32 s23, s13, s51
	s_cselect_b32 s22, s49, s50
	s_add_i32 m0, s21, 0xc000
	ds_read_b128 v[194:197], v155
	ds_read_b128 v[198:201], v155 offset:1024
	ds_read_b128 v[202:205], v155 offset:2048
	ds_read_b128 v[206:209], v155 offset:3072
	ds_read_b128 v[210:213], v155 offset:4096
	ds_read_b128 v[214:217], v155 offset:5120
	ds_read_b128 v[218:221], v155 offset:6144
	ds_read_b128 v[222:225], v155 offset:7168
	global_load_lds_dwordx4 v138, s[24:25]
	s_add_i32 m0, s21, 0xe000
	s_nop 0
	global_load_lds_dwordx4 v140, s[24:25]
	s_waitcnt vmcnt(8)
	s_waitcnt lgkmcnt(0)
	s_barrier
	s_waitcnt lgkmcnt(0)
	v_mfma_f32_16x16x32_bf16 v[122:125], v[160:163], v[194:197], v[122:125]
	v_mfma_f32_16x16x32_bf16 v[122:125], v[166:169], v[198:201], v[122:125]
	v_mfma_f32_16x16x32_bf16 v[106:109], v[166:169], v[206:209], v[106:109]
	v_mfma_f32_16x16x32_bf16 v[106:109], v[160:163], v[202:205], v[106:109]
	v_mfma_f32_16x16x32_bf16 v[90:93], v[160:163], v[210:213], v[90:93]
	v_mfma_f32_16x16x32_bf16 v[90:93], v[166:169], v[214:217], v[90:93]
	v_mfma_f32_16x16x32_bf16 v[74:77], v[166:169], v[222:225], v[74:77]
	v_mfma_f32_16x16x32_bf16 v[74:77], v[160:163], v[218:221], v[74:77]
	v_mfma_f32_16x16x32_bf16 v[62:65], v[170:173], v[218:221], v[62:65]
	v_mfma_f32_16x16x32_bf16 v[62:65], v[174:177], v[222:225], v[62:65]
	v_mfma_f32_16x16x32_bf16 v[82:85], v[174:177], v[214:217], v[82:85]
	v_mfma_f32_16x16x32_bf16 v[82:85], v[170:173], v[210:213], v[82:85]
	v_mfma_f32_16x16x32_bf16 v[98:101], v[170:173], v[202:205], v[98:101]
	v_mfma_f32_16x16x32_bf16 v[98:101], v[174:177], v[206:209], v[98:101]
	v_mfma_f32_16x16x32_bf16 v[114:117], v[174:177], v[198:201], v[114:117]
	v_mfma_f32_16x16x32_bf16 v[114:117], v[170:173], v[194:197], v[114:117]
	v_mfma_f32_16x16x32_bf16 v[126:129], v[178:181], v[194:197], v[126:129]
	v_mfma_f32_16x16x32_bf16 v[126:129], v[182:185], v[198:201], v[126:129]
	v_mfma_f32_16x16x32_bf16 v[110:113], v[182:185], v[206:209], v[110:113]
	v_mfma_f32_16x16x32_bf16 v[110:113], v[178:181], v[202:205], v[110:113]
	v_mfma_f32_16x16x32_bf16 v[94:97], v[178:181], v[210:213], v[94:97]
	v_mfma_f32_16x16x32_bf16 v[94:97], v[182:185], v[214:217], v[94:97]
	v_mfma_f32_16x16x32_bf16 v[78:81], v[182:185], v[222:225], v[78:81]
	v_mfma_f32_16x16x32_bf16 v[78:81], v[178:181], v[218:221], v[78:81]
	v_mfma_f32_16x16x32_bf16 v[70:73], v[186:189], v[218:221], v[70:73]
	v_mfma_f32_16x16x32_bf16 v[70:73], v[190:193], v[222:225], v[70:73]
	v_mfma_f32_16x16x32_bf16 v[86:89], v[190:193], v[214:217], v[86:89]
	v_mfma_f32_16x16x32_bf16 v[86:89], v[186:189], v[210:213], v[86:89]
	v_mfma_f32_16x16x32_bf16 v[102:105], v[186:189], v[202:205], v[102:105]
	v_mfma_f32_16x16x32_bf16 v[102:105], v[190:193], v[206:209], v[102:105]
	v_mfma_f32_16x16x32_bf16 v[118:121], v[190:193], v[198:201], v[118:121]
	v_mfma_f32_16x16x32_bf16 v[118:121], v[186:189], v[194:197], v[118:121]
	s_barrier
	s_add_i32 s33, s44, s29
	s_mov_b32 m0, s33
	ds_read_b128 v[194:197], v155 offset:16384
	ds_read_b128 v[198:201], v155 offset:17408
	ds_read_b128 v[202:205], v155 offset:18432
	ds_read_b128 v[206:209], v155 offset:19456
	ds_read_b128 v[210:213], v155 offset:20480
	ds_read_b128 v[214:217], v155 offset:21504
	ds_read_b128 v[218:221], v155 offset:22528
	ds_read_b128 v[222:225], v155 offset:23552
	global_load_lds_dwordx4 v132, s[22:23]
	s_add_i32 m0, s33, 0x2000
	s_add_u32 s62, s22, 0x100000
	s_addc_u32 s63, s23, 0
	s_add_i32 s33, s45, s29
	global_load_lds_dwordx4 v136, s[22:23]
	s_mov_b32 m0, s33
	s_add_u32 s100, s26, 0x80
	s_addc_u32 s101, s27, 0
	global_load_lds_dwordx4 v132, s[62:63]
	s_add_i32 m0, s33, 0x2000
	s_nop 0
	global_load_lds_dwordx4 v136, s[62:63]
	s_mov_b32 m0, s21
	s_nop 0
	global_load_lds_dwordx4 v130, s[26:27]
	s_mov_b32 m0, s34
	s_nop 0
	global_load_lds_dwordx4 v134, s[26:27]
	s_waitcnt vmcnt(8)
	s_waitcnt lgkmcnt(0)
	s_barrier
	s_waitcnt lgkmcnt(0)
	v_mfma_f32_16x16x32_bf16 v[58:61], v[160:163], v[194:197], v[58:61]
	v_mfma_f32_16x16x32_bf16 v[58:61], v[166:169], v[198:201], v[58:61]
	v_mfma_f32_16x16x32_bf16 v[42:45], v[166:169], v[206:209], v[42:45]
	v_mfma_f32_16x16x32_bf16 v[42:45], v[160:163], v[202:205], v[42:45]
	v_mfma_f32_16x16x32_bf16 v[26:29], v[160:163], v[210:213], v[26:29]
	v_mfma_f32_16x16x32_bf16 v[26:29], v[166:169], v[214:217], v[26:29]
	v_mfma_f32_16x16x32_bf16 v[10:13], v[166:169], v[222:225], v[10:13]
	v_mfma_f32_16x16x32_bf16 v[10:13], v[160:163], v[218:221], v[10:13]
	v_mfma_f32_16x16x32_bf16 v[2:5], v[170:173], v[218:221], v[2:5]
	v_mfma_f32_16x16x32_bf16 v[2:5], v[174:177], v[222:225], v[2:5]
	v_mfma_f32_16x16x32_bf16 v[18:21], v[174:177], v[214:217], v[18:21]
	v_mfma_f32_16x16x32_bf16 v[18:21], v[170:173], v[210:213], v[18:21]
	v_mfma_f32_16x16x32_bf16 v[34:37], v[170:173], v[202:205], v[34:37]
	v_mfma_f32_16x16x32_bf16 v[34:37], v[174:177], v[206:209], v[34:37]
	v_mfma_f32_16x16x32_bf16 v[50:53], v[174:177], v[198:201], v[50:53]
	v_mfma_f32_16x16x32_bf16 v[50:53], v[170:173], v[194:197], v[50:53]
	v_mfma_f32_16x16x32_bf16 v[66:69], v[178:181], v[194:197], v[66:69]
	v_mfma_f32_16x16x32_bf16 v[66:69], v[182:185], v[198:201], v[66:69]
	v_mfma_f32_16x16x32_bf16 v[46:49], v[182:185], v[206:209], v[46:49]
	v_mfma_f32_16x16x32_bf16 v[46:49], v[178:181], v[202:205], v[46:49]
	v_mfma_f32_16x16x32_bf16 v[30:33], v[178:181], v[210:213], v[30:33]
	v_mfma_f32_16x16x32_bf16 v[30:33], v[182:185], v[214:217], v[30:33]
	v_mfma_f32_16x16x32_bf16 v[14:17], v[182:185], v[222:225], v[14:17]
	v_mfma_f32_16x16x32_bf16 v[14:17], v[178:181], v[218:221], v[14:17]
	v_mfma_f32_16x16x32_bf16 v[6:9], v[186:189], v[218:221], v[6:9]
	v_mfma_f32_16x16x32_bf16 v[6:9], v[190:193], v[222:225], v[6:9]
	v_mfma_f32_16x16x32_bf16 v[22:25], v[190:193], v[214:217], v[22:25]
	v_mfma_f32_16x16x32_bf16 v[22:25], v[186:189], v[210:213], v[22:25]
	v_mfma_f32_16x16x32_bf16 v[38:41], v[186:189], v[202:205], v[38:41]
	v_mfma_f32_16x16x32_bf16 v[38:41], v[190:193], v[206:209], v[38:41]
	v_mfma_f32_16x16x32_bf16 v[54:57], v[190:193], v[198:201], v[54:57]
	v_mfma_f32_16x16x32_bf16 v[54:57], v[186:189], v[194:197], v[54:57]
	s_barrier
; #define PG8_STAGE(bufoff, gbase, voff) do { _Pragma("unroll") for (int _i = 0; _i < 2; ++_i) \
;         __builtin_amdgcn_global_load_lds((const unsigned*)((const char*)(gbase) + (voff)[_i]), (PG8_LAS unsigned*)(lds + (bufoff) + ldsw + _i * 8192), 16, 0, 0); } while (0)
; #define PG8_LDA(dst, b, h) do { _Pragma("unroll") for (int m = 0; m < 4; ++m) _Pragma("unroll") for (int k = 0; k < 2; ++k) dst[m][k] = *(const PG8_LAS bf16x8*)(lds + PG8_SA(b, h) + aoff + m * 2048 + k * 1024); } while (0)
; #define PG8_LDB(dst, b, h) do { _Pragma("unroll") for (int n = 0; n < 2; ++n) _Pragma("unroll") for (int k = 0; k < 2; ++k) dst[n][k] = *(const PG8_LAS bf16x8*)(lds + PG8_SB(b, h) + boff + n * 2048 + k * 1024); } while (0)
; #define PG8_MMA(ai, bj, At, Bt) do { __builtin_amdgcn_s_setprio(1); _Pragma("unroll") for (int m = 0; m < 4; ++m) _Pragma("unroll") for (int n = 0; n < 2; ++n) _Pragma("unroll") for (int k = 0; k < 2; ++k) \
;         acc[ai][bj][m][n] = __builtin_amdgcn_mfma_f32_16x16x32_bf16(Bt[n][k], At[m][k], acc[ai][bj][m][n], 0, 0, 0); __builtin_amdgcn_s_setprio(0); } while (0)
; #define PG8_WAIT_V(n) asm volatile("s_waitcnt vmcnt(" #n ")" ::: "memory")
; #define PG8_WAIT_L(n) asm volatile("s_waitcnt lgkmcnt(" #n ")" ::: "memory")
; #define PG8_BAR __builtin_amdgcn_s_barrier()
; #define PG8_SCHED __builtin_amdgcn_sched_barrier(0)
; template <class Epi, class Sched, bool ALIGN_EPI = false, bool SP2 = false>
; __device__ __forceinline__ void gemm_phase(PG8_LAS unsigned char* lds, const Gemm g, const Sched& S, const Epi& E) {
;     ...
;             PG8_LDB(B0, 1, 0); PG8_LDB(B1, 1, 1); PG8_SCHED; PG8_LDA(At, 1, 0); PG8_STAGE(PG8_SA(0, 1), a2 + hstep, voffA);
;             PG8_WAIT_V(8); PG8_WAIT_L(0); PG8_BAR; PG8_MMA(0, 0, At, B0); PG8_MMA(0, 1, At, B1); PG8_BAR; PG8_SCHED;
;             PG8_LDA(At, 1, 1); PG8_STAGE(PG8_SB(1, 0), b3, voffB); PG8_STAGE(PG8_SB(1, 1), b3 + hstep, voffB); PG8_STAGE(PG8_SA(1, 0), a3, voffA);
;             PG8_WAIT_V(8); PG8_WAIT_L(0); PG8_BAR; PG8_MMA(1, 0, At, B0); PG8_MMA(1, 1, At, B1); PG8_BAR; PG8_SCHED;
	s_add_i32 s33, 0, 0x18000
	s_add_i32 s42, 0, 0x1c000
	ds_read_b128 v[160:163], v241 offset:32768
	ds_read_b128 v[166:169], v241 offset:33792
	ds_read_b128 v[170:173], v241 offset:34816
	ds_read_b128 v[174:177], v241 offset:35840
	ds_read_b128 v[178:181], v241 offset:49152
	ds_read_b128 v[182:185], v241 offset:50176
	ds_read_b128 v[186:189], v241 offset:51200
	ds_read_b128 v[190:193], v241 offset:52224
	s_add_u32 s26, s26, 0x100000
	s_addc_u32 s27, s27, 0
	s_mov_b32 m0, s35
	ds_read_b128 v[194:197], v155 offset:32768
	ds_read_b128 v[198:201], v155 offset:33792
	ds_read_b128 v[202:205], v155 offset:34816
	ds_read_b128 v[206:209], v155 offset:35840
	ds_read_b128 v[210:213], v155 offset:36864
	ds_read_b128 v[214:217], v155 offset:37888
	ds_read_b128 v[218:221], v155 offset:38912
	ds_read_b128 v[222:225], v155 offset:39936
	global_load_lds_dwordx4 v130, s[26:27]
	s_mov_b32 m0, s36
	s_nop 0
	global_load_lds_dwordx4 v134, s[26:27]
	s_waitcnt vmcnt(8)
	s_waitcnt lgkmcnt(0)
	s_barrier
	s_waitcnt lgkmcnt(0)
	v_mfma_f32_16x16x32_bf16 v[122:125], v[160:163], v[194:197], v[122:125]
	v_mfma_f32_16x16x32_bf16 v[122:125], v[166:169], v[198:201], v[122:125]
	v_mfma_f32_16x16x32_bf16 v[106:109], v[166:169], v[206:209], v[106:109]
	v_mfma_f32_16x16x32_bf16 v[106:109], v[160:163], v[202:205], v[106:109]
	v_mfma_f32_16x16x32_bf16 v[90:93], v[160:163], v[210:213], v[90:93]
	v_mfma_f32_16x16x32_bf16 v[90:93], v[166:169], v[214:217], v[90:93]
	v_mfma_f32_16x16x32_bf16 v[74:77], v[166:169], v[222:225], v[74:77]
	v_mfma_f32_16x16x32_bf16 v[74:77], v[160:163], v[218:221], v[74:77]
	v_mfma_f32_16x16x32_bf16 v[62:65], v[170:173], v[218:221], v[62:65]
	v_mfma_f32_16x16x32_bf16 v[62:65], v[174:177], v[222:225], v[62:65]
	v_mfma_f32_16x16x32_bf16 v[82:85], v[174:177], v[214:217], v[82:85]
	v_mfma_f32_16x16x32_bf16 v[82:85], v[170:173], v[210:213], v[82:85]
	v_mfma_f32_16x16x32_bf16 v[98:101], v[170:173], v[202:205], v[98:101]
	v_mfma_f32_16x16x32_bf16 v[98:101], v[174:177], v[206:209], v[98:101]
	v_mfma_f32_16x16x32_bf16 v[114:117], v[174:177], v[198:201], v[114:117]
	v_mfma_f32_16x16x32_bf16 v[114:117], v[170:173], v[194:197], v[114:117]
	v_mfma_f32_16x16x32_bf16 v[126:129], v[178:181], v[194:197], v[126:129]
	v_mfma_f32_16x16x32_bf16 v[126:129], v[182:185], v[198:201], v[126:129]
	v_mfma_f32_16x16x32_bf16 v[110:113], v[182:185], v[206:209], v[110:113]
	v_mfma_f32_16x16x32_bf16 v[110:113], v[178:181], v[202:205], v[110:113]
	v_mfma_f32_16x16x32_bf16 v[94:97], v[178:181], v[210:213], v[94:97]
	v_mfma_f32_16x16x32_bf16 v[94:97], v[182:185], v[214:217], v[94:97]
	v_mfma_f32_16x16x32_bf16 v[78:81], v[182:185], v[222:225], v[78:81]
	v_mfma_f32_16x16x32_bf16 v[78:81], v[178:181], v[218:221], v[78:81]
	v_mfma_f32_16x16x32_bf16 v[70:73], v[186:189], v[218:221], v[70:73]
	v_mfma_f32_16x16x32_bf16 v[70:73], v[190:193], v[222:225], v[70:73]
	v_mfma_f32_16x16x32_bf16 v[86:89], v[190:193], v[214:217], v[86:89]
	v_mfma_f32_16x16x32_bf16 v[86:89], v[186:189], v[210:213], v[86:89]
	v_mfma_f32_16x16x32_bf16 v[102:105], v[186:189], v[202:205], v[102:105]
	v_mfma_f32_16x16x32_bf16 v[102:105], v[190:193], v[206:209], v[102:105]
	v_mfma_f32_16x16x32_bf16 v[118:121], v[190:193], v[198:201], v[118:121]
	v_mfma_f32_16x16x32_bf16 v[118:121], v[186:189], v[194:197], v[118:121]
	s_barrier
	s_add_i32 s26, s33, s29
	s_add_i32 m0, s26, 0xffffff80
	ds_read_b128 v[194:197], v155 offset:49152
	ds_read_b128 v[198:201], v155 offset:50176
	ds_read_b128 v[202:205], v155 offset:51200
	ds_read_b128 v[206:209], v155 offset:52224
	ds_read_b128 v[210:213], v155 offset:53248
	ds_read_b128 v[214:217], v155 offset:54272
	ds_read_b128 v[218:221], v155 offset:55296
	ds_read_b128 v[222:225], v155 offset:56320
	global_load_lds_dwordx4 v132, s[22:23] offset:128
	s_add_i32 m0, s26, 0x1f80
	s_add_i32 s26, s42, s29
	global_load_lds_dwordx4 v136, s[22:23] offset:128
	s_add_u32 s22, s22, 0x100080
	s_addc_u32 s23, s23, 0
	s_mov_b32 m0, s26
	s_nop 0
	global_load_lds_dwordx4 v132, s[22:23]
	s_add_i32 m0, s26, 0x2000
	s_nop 0
	global_load_lds_dwordx4 v136, s[22:23]
	s_mov_b32 m0, s41
	s_nop 0
	global_load_lds_dwordx4 v130, s[100:101]
	s_mov_b32 m0, s43
	s_nop 0
	global_load_lds_dwordx4 v134, s[100:101]
	s_waitcnt vmcnt(8)
	s_waitcnt lgkmcnt(0)
	s_barrier
; __device__ __forceinline__ float ssq_rstd(const ssq_t* ssq, int row) { return __builtin_amdgcn_rsqf((float)ssq[row] * (SSQ_UNFIX * RMS_INV_D) + RMS_EPS); }
; #define PG8_STAGE(bufoff, gbase, voff) do { _Pragma("unroll") for (int _i = 0; _i < 2; ++_i) \
;         __builtin_amdgcn_global_load_lds((const unsigned*)((const char*)(gbase) + (voff)[_i]), (PG8_LAS unsigned*)(lds + (bufoff) + ldsw + _i * 8192), 16, 0, 0); } while (0)
; #define PG8_LDA(dst, b, h) do { _Pragma("unroll") for (int m = 0; m < 4; ++m) _Pragma("unroll") for (int k = 0; k < 2; ++k) dst[m][k] = *(const PG8_LAS bf16x8*)(lds + PG8_SA(b, h) + aoff + m * 2048 + k * 1024); } while (0)
; #define PG8_MMA(ai, bj, At, Bt) do { __builtin_amdgcn_s_setprio(1); _Pragma("unroll") for (int m = 0; m < 4; ++m) _Pragma("unroll") for (int n = 0; n < 2; ++n) _Pragma("unroll") for (int k = 0; k < 2; ++k) \
;         acc[ai][bj][m][n] = __builtin_amdgcn_mfma_f32_16x16x32_bf16(Bt[n][k], At[m][k], acc[ai][bj][m][n], 0, 0, 0); __builtin_amdgcn_s_setprio(0); } while (0)
; #define PG8_WAIT_V(n) asm volatile("s_waitcnt vmcnt(" #n ")" ::: "memory")
; #define PG8_WAIT_L(n) asm volatile("s_waitcnt lgkmcnt(" #n ")" ::: "memory")
; #define PG8_BAR __builtin_amdgcn_s_barrier()
; #define PG8_SCHED __builtin_amdgcn_sched_barrier(0)
;     __device__ __forceinline__ void operator()(const f32x4 (&acc)[2][2][4][2], const Unit& u, int wr, int wc, int fr, int fq) const {
;         const int row0 = u.pm * BM + wr * 64 + fr, col0 = u.pn * HALF + wc * 32 + 8 * fq;
;         float rs[2][4];
; #pragma unroll
;         for (int ai = 0; ai < 2; ++ai)
; #pragma unroll
;             for (int m = 0; m < 4; ++m) rs[ai][m] = ssq_rstd(ssq, row0 + ai * HALF + m * 16);
; template <class Epi, class Sched, bool ALIGN_EPI = false, bool SP2 = false>
; __device__ __forceinline__ void gemm_phase(PG8_LAS unsigned char* lds, const Gemm g, const Sched& S, const Epi& E) {
;     ...
;             PG8_WAIT_V(8); PG8_WAIT_L(0); PG8_BAR; PG8_MMA(0, 0, At, B0); PG8_MMA(0, 1, At, B1); PG8_BAR; PG8_SCHED;
;             PG8_LDA(At, 1, 1); PG8_STAGE(PG8_SB(1, 0), b3, voffB); PG8_STAGE(PG8_SB(1, 1), b3 + hstep, voffB); PG8_STAGE(PG8_SA(1, 0), a3, voffA);
;             PG8_WAIT_V(8); PG8_WAIT_L(0); PG8_BAR; PG8_MMA(1, 0, At, B0); PG8_MMA(1, 1, At, B1); PG8_BAR; PG8_SCHED;
	s_waitcnt lgkmcnt(0)
	v_mfma_f32_16x16x32_bf16 v[58:61], v[160:163], v[194:197], v[58:61]
	v_mfma_f32_16x16x32_bf16 v[58:61], v[166:169], v[198:201], v[58:61]
	v_mfma_f32_16x16x32_bf16 v[42:45], v[166:169], v[206:209], v[42:45]
	v_mfma_f32_16x16x32_bf16 v[42:45], v[160:163], v[202:205], v[42:45]
	v_mfma_f32_16x16x32_bf16 v[26:29], v[160:163], v[210:213], v[26:29]
	v_mfma_f32_16x16x32_bf16 v[26:29], v[166:169], v[214:217], v[26:29]
	v_mfma_f32_16x16x32_bf16 v[10:13], v[166:169], v[222:225], v[10:13]
	v_mfma_f32_16x16x32_bf16 v[10:13], v[160:163], v[218:221], v[10:13]
	v_mfma_f32_16x16x32_bf16 v[2:5], v[170:173], v[218:221], v[2:5]
	v_mfma_f32_16x16x32_bf16 v[2:5], v[174:177], v[222:225], v[2:5]
	v_mfma_f32_16x16x32_bf16 v[18:21], v[174:177], v[214:217], v[18:21]
	v_mfma_f32_16x16x32_bf16 v[18:21], v[170:173], v[210:213], v[18:21]
	v_mfma_f32_16x16x32_bf16 v[34:37], v[170:173], v[202:205], v[34:37]
	v_mfma_f32_16x16x32_bf16 v[34:37], v[174:177], v[206:209], v[34:37]
	v_mfma_f32_16x16x32_bf16 v[50:53], v[174:177], v[198:201], v[50:53]
	v_mfma_f32_16x16x32_bf16 v[50:53], v[170:173], v[194:197], v[50:53]
	v_mfma_f32_16x16x32_bf16 v[66:69], v[178:181], v[194:197], v[66:69]
	v_mfma_f32_16x16x32_bf16 v[66:69], v[182:185], v[198:201], v[66:69]
	v_mfma_f32_16x16x32_bf16 v[46:49], v[182:185], v[206:209], v[46:49]
	v_mfma_f32_16x16x32_bf16 v[46:49], v[178:181], v[202:205], v[46:49]
	v_mfma_f32_16x16x32_bf16 v[30:33], v[178:181], v[210:213], v[30:33]
	v_mfma_f32_16x16x32_bf16 v[30:33], v[182:185], v[214:217], v[30:33]
	v_mfma_f32_16x16x32_bf16 v[14:17], v[182:185], v[222:225], v[14:17]
	v_mfma_f32_16x16x32_bf16 v[14:17], v[178:181], v[218:221], v[14:17]
	v_mfma_f32_16x16x32_bf16 v[6:9], v[186:189], v[218:221], v[6:9]
	v_mfma_f32_16x16x32_bf16 v[6:9], v[190:193], v[222:225], v[6:9]
	v_mfma_f32_16x16x32_bf16 v[22:25], v[190:193], v[214:217], v[22:25]
	v_mfma_f32_16x16x32_bf16 v[22:25], v[186:189], v[210:213], v[22:25]
	v_mfma_f32_16x16x32_bf16 v[38:41], v[186:189], v[202:205], v[38:41]
	v_mfma_f32_16x16x32_bf16 v[38:41], v[190:193], v[206:209], v[38:41]
	v_mfma_f32_16x16x32_bf16 v[54:57], v[190:193], v[198:201], v[54:57]
	v_mfma_f32_16x16x32_bf16 v[54:57], v[186:189], v[194:197], v[54:57]
	s_barrier
	s_add_i32 s52, s52, 2
	s_add_u32 s24, s24, 0x100
	s_addc_u32 s25, s25, 0
	s_add_u32 s50, s50, 0x100
	s_addc_u32 s51, s51, 0
	s_cmp_gt_u32 s52, 61
	s_cbranch_scc0 .LBB0_1681
	s_and_b64 vcc, exec, s[8:9]
	s_cbranch_vccz .LBB0_1684
	v_lshl_add_u32 v168, s20, 8, v147
	v_ashrrev_i32_e32 v169, 31, v168
	v_or_b32_e32 v166, 16, v168
	v_or_b32_e32 v160, 32, v168
	v_or_b32_e32 v156, 48, v168
	v_lshl_add_u64 v[148:149], v[168:169], 3, s[4:5]
	v_ashrrev_i32_e32 v167, 31, v166
	v_ashrrev_i32_e32 v161, 31, v160
	v_ashrrev_i32_e32 v157, 31, v156
	v_lshl_add_u64 v[162:163], v[166:167], 3, s[4:5]
	v_lshl_add_u64 v[170:171], v[160:161], 3, s[4:5]
	global_load_dwordx2 v[172:173], v[148:149], off
	global_load_dwordx2 v[174:175], v[148:149], off offset:1024
	global_load_dwordx2 v[176:177], v[148:149], off offset:1152
	global_load_dwordx2 v[178:179], v[148:149], off offset:1280
	v_lshl_add_u64 v[180:181], v[156:157], 3, s[4:5]
	global_load_dwordx2 v[182:183], v[162:163], off
	s_nop 0
	global_load_dwordx2 v[170:171], v[170:171], off
	s_nop 0
	global_load_dwordx2 v[180:181], v[180:181], off
	s_nop 0
	global_load_dwordx2 v[148:149], v[148:149], off offset:1408
	s_barrier
	s_branch .Lepi_rest_1684

; __device__ __forceinline__ unsigned cvt_pk_bf16(float lo, float hi) { unsigned r; asm volatile("v_cvt_pk_bf16_f32 %0, %1, %2" : "=v"(r) : "v"(lo), "v"(hi)); return r; }
; __device__ __forceinline__ unsigned cvt_pk_bf16(float lo, float hi) { unsigned r; asm volatile("v_cvt_pk_bf16_f32 %0, %1, %2" : "=v"(r) : "v"(lo), "v"(hi)); return r; }
; __device__ __forceinline__ float ssq_rstd(const ssq_t* ssq, int row) { return __builtin_amdgcn_rsqf((float)ssq[row] * (SSQ_UNFIX * RMS_INV_D) + RMS_EPS); }
;     __device__ __forceinline__ void operator()(const f32x4 (&acc)[2][2][4][2], const Unit& u, int wr, int wc, int fr, int fq) const {
;         const int row0 = u.pm * BM + wr * 64 + fr, col0 = u.pn * HALF + wc * 32 + 8 * fq;
;         float rs[2][4];
; #pragma unroll
;         for (int ai = 0; ai < 2; ++ai)
; #pragma unroll
;             for (int m = 0; m < 4; ++m) rs[ai][m] = ssq_rstd(ssq, row0 + ai * HALF + m * 16);
; #pragma unroll
;         for (int ai = 0; ai < 2; ++ai)
; #pragma unroll
;             for (int m = 0; m < 4; ++m) { const int row = row0 + ai * HALF + m * 16; bf16_t* rowp = O + (size_t)row * ldc + col0; float a[8];
; #pragma unroll
;                 for (int n = 0; n < 2; ++n)
; #pragma unroll
;                     for (int i = 0; i < 4; i += 2) {
;                         const f32x2 r2 = {rs[ai][m], rs[ai][m]};
;                         const f32x2 g = (f32x2){acc[ai][0][m][n][i], acc[ai][0][m][n][i + 1]} * r2, up = (f32x2){acc[ai][1][m][n][i], acc[ai][1][m][n][i + 1]} * r2;
;                         const f32x2 t = g * (f32x2){-1.4426950408889634f, -1.4426950408889634f};
;                         const f32x2 d = (f32x2){__builtin_amdgcn_exp2f(t.x), __builtin_amdgcn_exp2f(t.y)} + (f32x2){1.0f, 1.0f};
;                         const f32x2 o2 = (g * up) * (f32x2){__builtin_amdgcn_rcpf(d.x), __builtin_amdgcn_rcpf(d.y)};
;                         a[4 * n + i] = o2.x; a[4 * n + i + 1] = o2.y; }
;                 u32x4 w; w.x = cvt_pk_bf16(a[0], a[1]); w.y = cvt_pk_bf16(a[2], a[3]); w.z = cvt_pk_bf16(a[4], a[5]); w.w = cvt_pk_bf16(a[6], a[7]);
;                 *(u32x4*)rowp = w; }
.Lepi_rest_1684:
	v_add_u32_e32 v165, 0x80, v168
	v_add_u32_e32 v163, 0x90, v168
	v_add_u32_e32 v161, 0xa0, v168
	s_andn2_b64 vcc, exec, s[0:1]
	s_mov_b64 s[0:1], -1
	s_waitcnt vmcnt(0)
	v_ffbh_u32_e32 v146, v173
	v_min_u32_e32 v146, 32, v146
	v_lshlrev_b64 v[172:173], v146, v[172:173]
	v_ffbh_u32_e32 v158, v171
	v_min_u32_e32 v158, 32, v158
	v_min_u32_e32 v169, 1, v172
	v_lshlrev_b64 v[170:171], v158, v[170:171]
	v_or_b32_e32 v169, v173, v169
	v_min_u32_e32 v170, 1, v170
	v_cvt_f32_u32_e32 v169, v169
	v_ffbh_u32_e32 v150, v175
	v_ffbh_u32_e32 v152, v177
	v_ffbh_u32_e32 v154, v179
	v_ffbh_u32_e32 v162, v181
	v_or_b32_e32 v170, v171, v170
	v_min_u32_e32 v150, 32, v150
	v_min_u32_e32 v152, 32, v152
	v_min_u32_e32 v154, 32, v154
	v_min_u32_e32 v162, 32, v162
	v_cvt_f32_u32_e32 v170, v170
	v_sub_u32_e32 v146, 32, v146
	v_lshlrev_b64 v[174:175], v150, v[174:175]
	v_lshlrev_b64 v[176:177], v152, v[176:177]
	v_lshlrev_b64 v[178:179], v154, v[178:179]
	v_lshlrev_b64 v[180:181], v162, v[180:181]
	v_min_u32_e32 v172, 1, v174
	v_min_u32_e32 v174, 1, v176
	v_min_u32_e32 v176, 1, v178
	v_min_u32_e32 v178, 1, v180
	v_ldexp_f32 v146, v169, v146
	v_sub_u32_e32 v158, 32, v158
	v_or_b32_e32 v171, v181, v178
	v_fmamk_f32 v146, v146, 0x2d800000, v159
	v_cvt_f32_u32_e32 v171, v171
	v_ldexp_f32 v158, v170, v158
	v_rsq_f32_e32 v170, v146
	v_or_b32_e32 v172, v175, v172
	v_or_b32_e32 v174, v177, v174
	v_or_b32_e32 v175, v179, v176
	v_pk_mul_f32 v[122:123], v[122:123], v[170:171] op_sel_hi:[1,0]
	v_pk_mul_f32 v[124:125], v[124:125], v[170:171] op_sel_hi:[1,0]
	v_pk_mul_f32 v[176:177], v[122:123], s[10:11] op_sel_hi:[1,0]
	v_pk_mul_f32 v[178:179], v[124:125], s[10:11] op_sel_hi:[1,0]
	v_exp_f32_e32 v176, v176
	v_exp_f32_e32 v177, v177
	v_exp_f32_e32 v178, v178
	v_exp_f32_e32 v179, v179
	v_ffbh_u32_e32 v157, v183
	v_pk_add_f32 v[176:177], v[176:177], 1.0 op_sel_hi:[1,0]
	v_min_u32_e32 v157, 32, v157
	v_pk_mul_f32 v[126:127], v[126:127], v[170:171] op_sel_hi:[1,0]
	v_rcp_f32_e32 v176, v176
	v_rcp_f32_e32 v177, v177
	v_lshlrev_b64 v[182:183], v157, v[182:183]
	v_pk_mul_f32 v[122:123], v[122:123], v[126:127]
	v_pk_mul_f32 v[126:127], v[128:129], v[170:171] op_sel_hi:[1,0]
	v_pk_add_f32 v[128:129], v[178:179], 1.0 op_sel_hi:[1,0]
	v_min_u32_e32 v173, 1, v182
	v_rcp_f32_e32 v128, v128
	v_rcp_f32_e32 v129, v129
	v_or_b32_e32 v173, v183, v173
	v_pk_mul_f32 v[114:115], v[114:115], v[170:171] op_sel_hi:[1,0]
	v_cvt_f32_u32_e32 v173, v173
	v_pk_mul_f32 v[122:123], v[122:123], v[176:177]
	v_pk_mul_f32 v[176:177], v[114:115], s[10:11] op_sel_hi:[1,0]
	v_pk_mul_f32 v[124:125], v[124:125], v[126:127]
	v_exp_f32_e32 v176, v176
	v_exp_f32_e32 v177, v177
	v_pk_mul_f32 v[116:117], v[116:117], v[170:171] op_sel_hi:[1,0]
	v_ffbh_u32_e32 v167, v149
	v_cvt_f32_u32_e32 v172, v172
	v_pk_mul_f32 v[124:125], v[124:125], v[128:129]
	v_pk_mul_f32 v[128:129], v[116:117], s[10:11] op_sel_hi:[1,0]
	v_min_u32_e32 v167, 32, v167
	v_sub_u32_e32 v157, 32, v157
	v_exp_f32_e32 v128, v128
	v_exp_f32_e32 v129, v129
	v_lshlrev_b64 v[148:149], v167, v[148:149]
	v_ldexp_f32 v157, v173, v157
	v_sub_u32_e32 v150, 32, v150
	v_min_u32_e32 v148, 1, v148
	v_fmamk_f32 v146, v157, 0x2d800000, v159
	v_pk_mul_f32 v[118:119], v[118:119], v[170:171] op_sel_hi:[1,0]
	v_pk_add_f32 v[126:127], v[176:177], 1.0 op_sel_hi:[1,0]
	v_cvt_f32_u32_e32 v174, v174
	v_cvt_f32_u32_e32 v175, v175
	v_ldexp_f32 v150, v172, v150
	v_rsq_f32_e32 v172, v146
	v_or_b32_e32 v146, v149, v148
	v_pk_mul_f32 v[114:115], v[114:115], v[118:119]
	v_rcp_f32_e32 v118, v126
	v_rcp_f32_e32 v119, v127
	v_cvt_f32_u32_e32 v146, v146
	v_pk_add_f32 v[126:127], v[128:129], 1.0 op_sel_hi:[1,0]
	v_sub_u32_e32 v152, 32, v152
	v_rcp_f32_e32 v126, v126
	v_rcp_f32_e32 v127, v127
	v_sub_u32_e32 v154, 32, v154
	v_sub_u32_e32 v162, 32, v162
	v_ldexp_f32 v152, v174, v152
	v_ldexp_f32 v154, v175, v154
	v_sub_u32_e32 v148, 32, v167
	v_lshl_or_b32 v174, s47, 7, v153
	v_pk_mul_f32 v[118:119], v[114:115], v[118:119]
	v_pk_mul_f32 v[114:115], v[120:121], v[170:171] op_sel_hi:[1,0]
	v_ldexp_f32 v162, v171, v162
	v_fmamk_f32 v150, v150, 0x2d800000, v159
	v_fmamk_f32 v169, v154, 0x2d800000, v159
	v_fmamk_f32 v157, v158, 0x2d800000, v159
	v_ldexp_f32 v146, v146, v148
	v_ashrrev_i32_e32 v175, 31, v174
	v_mov_b64_e32 v[148:149], s[38:39]
	v_pk_mul_f32 v[114:115], v[116:117], v[114:115]
	v_fmamk_f32 v158, v162, 0x2d800000, v159
	v_rsq_f32_e32 v154, v150
	v_rsq_f32_e32 v162, v157
	v_rsq_f32_e32 v150, v169
	v_add_u32_e32 v157, 0xb0, v168
	v_mad_i64_i32 v[168:169], s[22:23], v168, s46, v[148:149]
	v_pk_mul_f32 v[120:121], v[114:115], v[126:127]
	v_lshlrev_b64 v[114:115], 1, v[174:175]
	v_lshl_add_u64 v[126:127], v[168:169], 0, v[114:115]
	v_cvt_pk_bf16_f32 v116, v122, v123
	v_cvt_pk_bf16_f32 v117, v124, v125
	v_pk_mul_f32 v[106:107], v[106:107], v[172:173] op_sel_hi:[1,0]
	v_cvt_pk_bf16_f32 v118, v118, v119
	v_cvt_pk_bf16_f32 v119, v120, v121
	global_store_dwordx4 v[126:127], v[116:119], off
	v_pk_mul_f32 v[108:109], v[108:109], v[172:173] op_sel_hi:[1,0]
	v_pk_mul_f32 v[110:111], v[110:111], v[172:173] op_sel_hi:[1,0]
	v_pk_mul_f32 v[116:117], v[106:107], s[10:11] op_sel_hi:[1,0]
	v_pk_mul_f32 v[120:121], v[108:109], s[10:11] op_sel_hi:[1,0]
	v_exp_f32_e32 v116, v116
	v_exp_f32_e32 v117, v117
	v_exp_f32_e32 v120, v120
	v_exp_f32_e32 v121, v121
	v_pk_mul_f32 v[106:107], v[106:107], v[110:111]
	v_pk_add_f32 v[116:117], v[116:117], 1.0 op_sel_hi:[1,0]
	v_pk_mul_f32 v[110:111], v[112:113], v[172:173] op_sel_hi:[1,0]
	v_rcp_f32_e32 v116, v116
	v_rcp_f32_e32 v117, v117
	v_pk_add_f32 v[112:113], v[120:121], 1.0 op_sel_hi:[1,0]
	v_pk_mul_f32 v[98:99], v[98:99], v[172:173] op_sel_hi:[1,0]
; __device__ __forceinline__ unsigned cvt_pk_bf16(float lo, float hi) { unsigned r; asm volatile("v_cvt_pk_bf16_f32 %0, %1, %2" : "=v"(r) : "v"(lo), "v"(hi)); return r; }
; __device__ __forceinline__ unsigned cvt_pk_bf16(float lo, float hi) { unsigned r; asm volatile("v_cvt_pk_bf16_f32 %0, %1, %2" : "=v"(r) : "v"(lo), "v"(hi)); return r; }
;     __device__ __forceinline__ void operator()(const f32x4 (&acc)[2][2][4][2], const Unit& u, int wr, int wc, int fr, int fq) const {
;     ...
;             for (int m = 0; m < 4; ++m) { const int row = row0 + ai * HALF + m * 16; bf16_t* rowp = O + (size_t)row * ldc + col0; float a[8];
; #pragma unroll
;                 for (int n = 0; n < 2; ++n)
; #pragma unroll
;                     for (int i = 0; i < 4; i += 2) {
;                         const f32x2 r2 = {rs[ai][m], rs[ai][m]};
;                         const f32x2 g = (f32x2){acc[ai][0][m][n][i], acc[ai][0][m][n][i + 1]} * r2, up = (f32x2){acc[ai][1][m][n][i], acc[ai][1][m][n][i + 1]} * r2;
;                         const f32x2 t = g * (f32x2){-1.4426950408889634f, -1.4426950408889634f};
;                         const f32x2 d = (f32x2){__builtin_amdgcn_exp2f(t.x), __builtin_amdgcn_exp2f(t.y)} + (f32x2){1.0f, 1.0f};
;                         const f32x2 o2 = (g * up) * (f32x2){__builtin_amdgcn_rcpf(d.x), __builtin_amdgcn_rcpf(d.y)};
;                         a[4 * n + i] = o2.x; a[4 * n + i + 1] = o2.y; }
;                 u32x4 w; w.x = cvt_pk_bf16(a[0], a[1]); w.y = cvt_pk_bf16(a[2], a[3]); w.z = cvt_pk_bf16(a[4], a[5]); w.w = cvt_pk_bf16(a[6], a[7]);
;                 *(u32x4*)rowp = w; }
	v_rcp_f32_e32 v112, v112
	v_rcp_f32_e32 v113, v113
	v_pk_mul_f32 v[106:107], v[106:107], v[116:117]
	v_pk_mul_f32 v[116:117], v[98:99], s[10:11] op_sel_hi:[1,0]
	v_pk_mul_f32 v[108:109], v[108:109], v[110:111]
	v_exp_f32_e32 v116, v116
	v_exp_f32_e32 v117, v117
	v_pk_mul_f32 v[100:101], v[100:101], v[172:173] op_sel_hi:[1,0]
	v_pk_mul_f32 v[108:109], v[108:109], v[112:113]
	v_pk_mul_f32 v[112:113], v[100:101], s[10:11] op_sel_hi:[1,0]
	v_pk_mul_f32 v[102:103], v[102:103], v[172:173] op_sel_hi:[1,0]
	v_exp_f32_e32 v112, v112
	v_exp_f32_e32 v113, v113
	v_pk_add_f32 v[110:111], v[116:117], 1.0 op_sel_hi:[1,0]
	v_pk_mul_f32 v[98:99], v[98:99], v[102:103]
	v_rcp_f32_e32 v102, v110
	v_rcp_f32_e32 v103, v111
	v_pk_add_f32 v[110:111], v[112:113], 1.0 op_sel_hi:[1,0]
	v_mad_i64_i32 v[118:119], s[22:23], v166, s46, v[148:149]
	v_rcp_f32_e32 v110, v110
	v_rcp_f32_e32 v111, v111
	v_pk_mul_f32 v[102:103], v[98:99], v[102:103]
	v_pk_mul_f32 v[98:99], v[104:105], v[172:173] op_sel_hi:[1,0]
	v_pk_mul_f32 v[90:91], v[90:91], v[162:163] op_sel_hi:[1,0]
	v_pk_mul_f32 v[98:99], v[100:101], v[98:99]
	v_pk_mul_f32 v[92:93], v[92:93], v[162:163] op_sel_hi:[1,0]
	v_pk_mul_f32 v[104:105], v[98:99], v[110:111]
	v_lshl_add_u64 v[110:111], v[118:119], 0, v[114:115]
	v_cvt_pk_bf16_f32 v98, v106, v107
	v_cvt_pk_bf16_f32 v99, v108, v109
	v_cvt_pk_bf16_f32 v100, v102, v103
	v_cvt_pk_bf16_f32 v101, v104, v105
	global_store_dwordx4 v[110:111], v[98:101], off
	v_pk_mul_f32 v[102:103], v[92:93], s[10:11] op_sel_hi:[1,0]
	v_pk_mul_f32 v[94:95], v[94:95], v[162:163] op_sel_hi:[1,0]
	v_pk_mul_f32 v[98:99], v[90:91], s[10:11] op_sel_hi:[1,0]
	v_exp_f32_e32 v102, v102
	v_exp_f32_e32 v98, v98
	v_exp_f32_e32 v99, v99
	v_exp_f32_e32 v103, v103
	v_pk_mul_f32 v[90:91], v[90:91], v[94:95]
	v_pk_mul_f32 v[94:95], v[96:97], v[162:163] op_sel_hi:[1,0]
	v_pk_add_f32 v[98:99], v[98:99], 1.0 op_sel_hi:[1,0]
	v_pk_add_f32 v[96:97], v[102:103], 1.0 op_sel_hi:[1,0]
	v_rcp_f32_e32 v98, v98
	v_rcp_f32_e32 v99, v99
	v_rcp_f32_e32 v96, v96
	v_rcp_f32_e32 v97, v97
	v_pk_mul_f32 v[82:83], v[82:83], v[162:163] op_sel_hi:[1,0]
	v_pk_mul_f32 v[90:91], v[90:91], v[98:99]
	v_pk_mul_f32 v[98:99], v[82:83], s[10:11] op_sel_hi:[1,0]
	v_pk_mul_f32 v[92:93], v[92:93], v[94:95]
	v_exp_f32_e32 v98, v98
	v_exp_f32_e32 v99, v99
	v_pk_mul_f32 v[84:85], v[84:85], v[162:163] op_sel_hi:[1,0]
	v_pk_mul_f32 v[92:93], v[92:93], v[96:97]
	v_pk_mul_f32 v[96:97], v[84:85], s[10:11] op_sel_hi:[1,0]
	v_pk_mul_f32 v[86:87], v[86:87], v[162:163] op_sel_hi:[1,0]
	v_exp_f32_e32 v96, v96
	v_exp_f32_e32 v97, v97
	v_pk_add_f32 v[94:95], v[98:99], 1.0 op_sel_hi:[1,0]
	v_pk_mul_f32 v[82:83], v[82:83], v[86:87]
	v_rcp_f32_e32 v86, v94
	v_rcp_f32_e32 v87, v95
	v_pk_add_f32 v[94:95], v[96:97], 1.0 op_sel_hi:[1,0]
	v_rsq_f32_e32 v158, v158
	v_rcp_f32_e32 v94, v94
	v_rcp_f32_e32 v95, v95
	v_pk_mul_f32 v[86:87], v[82:83], v[86:87]
	v_pk_mul_f32 v[82:83], v[88:89], v[162:163] op_sel_hi:[1,0]
	v_mad_i64_i32 v[100:101], s[22:23], v160, s46, v[148:149]
	v_pk_mul_f32 v[82:83], v[84:85], v[82:83]
	v_pk_mul_f32 v[74:75], v[74:75], v[158:159] op_sel_hi:[1,0]
	v_pk_mul_f32 v[88:89], v[82:83], v[94:95]
	v_lshl_add_u64 v[94:95], v[100:101], 0, v[114:115]
	v_cvt_pk_bf16_f32 v82, v90, v91
	v_cvt_pk_bf16_f32 v83, v92, v93
	v_cvt_pk_bf16_f32 v84, v86, v87
	v_cvt_pk_bf16_f32 v85, v88, v89
	global_store_dwordx4 v[94:95], v[82:85], off
	v_pk_mul_f32 v[76:77], v[76:77], v[158:159] op_sel_hi:[1,0]
	v_pk_mul_f32 v[78:79], v[78:79], v[158:159] op_sel_hi:[1,0]
	v_pk_mul_f32 v[82:83], v[74:75], s[10:11] op_sel_hi:[1,0]
	v_pk_mul_f32 v[86:87], v[76:77], s[10:11] op_sel_hi:[1,0]
	v_exp_f32_e32 v82, v82
	v_exp_f32_e32 v83, v83
	v_exp_f32_e32 v86, v86
	v_exp_f32_e32 v87, v87
	v_pk_mul_f32 v[74:75], v[74:75], v[78:79]
	v_pk_add_f32 v[82:83], v[82:83], 1.0 op_sel_hi:[1,0]
	v_pk_mul_f32 v[78:79], v[80:81], v[158:159] op_sel_hi:[1,0]
	v_rcp_f32_e32 v82, v82
	v_rcp_f32_e32 v83, v83
	v_pk_add_f32 v[80:81], v[86:87], 1.0 op_sel_hi:[1,0]
	v_pk_mul_f32 v[62:63], v[62:63], v[158:159] op_sel_hi:[1,0]
	v_rcp_f32_e32 v80, v80
	v_rcp_f32_e32 v81, v81
	v_pk_mul_f32 v[74:75], v[74:75], v[82:83]
	v_pk_mul_f32 v[82:83], v[62:63], s[10:11] op_sel_hi:[1,0]
	v_pk_mul_f32 v[76:77], v[76:77], v[78:79]
	v_exp_f32_e32 v82, v82
	v_exp_f32_e32 v83, v83
	v_pk_mul_f32 v[64:65], v[64:65], v[158:159] op_sel_hi:[1,0]
	v_pk_mul_f32 v[76:77], v[76:77], v[80:81]
	v_pk_mul_f32 v[80:81], v[64:65], s[10:11] op_sel_hi:[1,0]
	v_pk_mul_f32 v[70:71], v[70:71], v[158:159] op_sel_hi:[1,0]
	v_exp_f32_e32 v80, v80
	v_exp_f32_e32 v81, v81
	v_pk_add_f32 v[78:79], v[82:83], 1.0 op_sel_hi:[1,0]
	v_pk_mul_f32 v[62:63], v[62:63], v[70:71]
	v_rcp_f32_e32 v70, v78
	v_rcp_f32_e32 v71, v79
	v_pk_add_f32 v[78:79], v[80:81], 1.0 op_sel_hi:[1,0]
	v_mad_i64_i32 v[84:85], s[22:23], v156, s46, v[148:149]
	v_rcp_f32_e32 v78, v78
	v_rcp_f32_e32 v79, v79
	v_pk_mul_f32 v[70:71], v[62:63], v[70:71]
	v_pk_mul_f32 v[62:63], v[72:73], v[158:159] op_sel_hi:[1,0]
	v_pk_mul_f32 v[58:59], v[58:59], v[154:155] op_sel_hi:[1,0]
	v_pk_mul_f32 v[62:63], v[64:65], v[62:63]
	v_pk_mul_f32 v[60:61], v[60:61], v[154:155] op_sel_hi:[1,0]
	v_pk_mul_f32 v[72:73], v[62:63], v[78:79]
	v_lshl_add_u64 v[78:79], v[84:85], 0, v[114:115]
	v_cvt_pk_bf16_f32 v62, v74, v75
	v_cvt_pk_bf16_f32 v63, v76, v77
	v_cvt_pk_bf16_f32 v64, v70, v71
	v_cvt_pk_bf16_f32 v65, v72, v73
	global_store_dwordx4 v[78:79], v[62:65], off
	v_pk_mul_f32 v[70:71], v[60:61], s[10:11] op_sel_hi:[1,0]
	v_pk_mul_f32 v[66:67], v[66:67], v[154:155] op_sel_hi:[1,0]
	v_pk_mul_f32 v[62:63], v[58:59], s[10:11] op_sel_hi:[1,0]
	v_exp_f32_e32 v70, v70
	v_exp_f32_e32 v62, v62
	v_exp_f32_e32 v63, v63
; __device__ __forceinline__ unsigned cvt_pk_bf16(float lo, float hi) { unsigned r; asm volatile("v_cvt_pk_bf16_f32 %0, %1, %2" : "=v"(r) : "v"(lo), "v"(hi)); return r; }
; __device__ __forceinline__ unsigned cvt_pk_bf16(float lo, float hi) { unsigned r; asm volatile("v_cvt_pk_bf16_f32 %0, %1, %2" : "=v"(r) : "v"(lo), "v"(hi)); return r; }
;     __device__ __forceinline__ void operator()(const f32x4 (&acc)[2][2][4][2], const Unit& u, int wr, int wc, int fr, int fq) const {
;     ...
;             for (int m = 0; m < 4; ++m) { const int row = row0 + ai * HALF + m * 16; bf16_t* rowp = O + (size_t)row * ldc + col0; float a[8];
; #pragma unroll
;                 for (int n = 0; n < 2; ++n)
; #pragma unroll
;                     for (int i = 0; i < 4; i += 2) {
;                         const f32x2 r2 = {rs[ai][m], rs[ai][m]};
;                         const f32x2 g = (f32x2){acc[ai][0][m][n][i], acc[ai][0][m][n][i + 1]} * r2, up = (f32x2){acc[ai][1][m][n][i], acc[ai][1][m][n][i + 1]} * r2;
;                         const f32x2 t = g * (f32x2){-1.4426950408889634f, -1.4426950408889634f};
;                         const f32x2 d = (f32x2){__builtin_amdgcn_exp2f(t.x), __builtin_amdgcn_exp2f(t.y)} + (f32x2){1.0f, 1.0f};
;                         const f32x2 o2 = (g * up) * (f32x2){__builtin_amdgcn_rcpf(d.x), __builtin_amdgcn_rcpf(d.y)};
;                         a[4 * n + i] = o2.x; a[4 * n + i + 1] = o2.y; }
;                 u32x4 w; w.x = cvt_pk_bf16(a[0], a[1]); w.y = cvt_pk_bf16(a[2], a[3]); w.z = cvt_pk_bf16(a[4], a[5]); w.w = cvt_pk_bf16(a[6], a[7]);
;                 *(u32x4*)rowp = w; }
	v_exp_f32_e32 v71, v71
	v_pk_mul_f32 v[58:59], v[58:59], v[66:67]
	v_pk_mul_f32 v[50:51], v[50:51], v[154:155] op_sel_hi:[1,0]
	v_pk_add_f32 v[62:63], v[62:63], 1.0 op_sel_hi:[1,0]
	v_pk_add_f32 v[66:67], v[70:71], 1.0 op_sel_hi:[1,0]
	v_rcp_f32_e32 v62, v62
	v_rcp_f32_e32 v63, v63
	v_rcp_f32_e32 v66, v66
	v_rcp_f32_e32 v67, v67
	v_pk_mul_f32 v[52:53], v[52:53], v[154:155] op_sel_hi:[1,0]
	v_pk_mul_f32 v[58:59], v[58:59], v[62:63]
	v_pk_mul_f32 v[62:63], v[68:69], v[154:155] op_sel_hi:[1,0]
	v_pk_mul_f32 v[68:69], v[50:51], s[10:11] op_sel_hi:[1,0]
	v_pk_mul_f32 v[60:61], v[60:61], v[62:63]
	v_exp_f32_e32 v68, v68
	v_exp_f32_e32 v69, v69
	v_pk_mul_f32 v[60:61], v[60:61], v[66:67]
	v_pk_mul_f32 v[66:67], v[52:53], s[10:11] op_sel_hi:[1,0]
	v_pk_mul_f32 v[54:55], v[54:55], v[154:155] op_sel_hi:[1,0]
	v_exp_f32_e32 v66, v66
	v_exp_f32_e32 v67, v67
	v_pk_add_f32 v[62:63], v[68:69], 1.0 op_sel_hi:[1,0]
	v_pk_mul_f32 v[50:51], v[50:51], v[54:55]
	v_rcp_f32_e32 v54, v62
	v_rcp_f32_e32 v55, v63
	v_fmamk_f32 v152, v152, 0x2d800000, v159
	v_pk_add_f32 v[62:63], v[66:67], 1.0 op_sel_hi:[1,0]
	v_rsq_f32_e32 v152, v152
	v_rcp_f32_e32 v62, v62
	v_rcp_f32_e32 v63, v63
	v_pk_mul_f32 v[54:55], v[50:51], v[54:55]
	v_pk_mul_f32 v[50:51], v[56:57], v[154:155] op_sel_hi:[1,0]
	v_mad_i64_i32 v[64:65], s[22:23], v165, s46, v[148:149]
	v_pk_mul_f32 v[50:51], v[52:53], v[50:51]
	v_pk_mul_f32 v[42:43], v[42:43], v[152:153] op_sel_hi:[1,0]
	v_pk_mul_f32 v[56:57], v[50:51], v[62:63]
	v_lshl_add_u64 v[62:63], v[64:65], 0, v[114:115]
	v_cvt_pk_bf16_f32 v50, v58, v59
	v_cvt_pk_bf16_f32 v51, v60, v61
	v_cvt_pk_bf16_f32 v52, v54, v55
	v_cvt_pk_bf16_f32 v53, v56, v57
	global_store_dwordx4 v[62:63], v[50:53], off
	v_pk_mul_f32 v[44:45], v[44:45], v[152:153] op_sel_hi:[1,0]
	v_pk_mul_f32 v[46:47], v[46:47], v[152:153] op_sel_hi:[1,0]
	v_pk_mul_f32 v[50:51], v[42:43], s[10:11] op_sel_hi:[1,0]
	v_pk_mul_f32 v[54:55], v[44:45], s[10:11] op_sel_hi:[1,0]
	v_exp_f32_e32 v50, v50
	v_exp_f32_e32 v51, v51
	v_exp_f32_e32 v54, v54
	v_exp_f32_e32 v55, v55
	v_pk_mul_f32 v[42:43], v[42:43], v[46:47]
	v_pk_add_f32 v[50:51], v[50:51], 1.0 op_sel_hi:[1,0]
	v_pk_mul_f32 v[46:47], v[48:49], v[152:153] op_sel_hi:[1,0]
	v_rcp_f32_e32 v50, v50
	v_rcp_f32_e32 v51, v51
	v_pk_add_f32 v[48:49], v[54:55], 1.0 op_sel_hi:[1,0]
	v_pk_mul_f32 v[34:35], v[34:35], v[152:153] op_sel_hi:[1,0]
	v_rcp_f32_e32 v48, v48
	v_rcp_f32_e32 v49, v49
	v_pk_mul_f32 v[42:43], v[42:43], v[50:51]
	v_pk_mul_f32 v[50:51], v[34:35], s[10:11] op_sel_hi:[1,0]
	v_pk_mul_f32 v[44:45], v[44:45], v[46:47]
	v_exp_f32_e32 v50, v50
	v_exp_f32_e32 v51, v51
	v_pk_mul_f32 v[36:37], v[36:37], v[152:153] op_sel_hi:[1,0]
	v_pk_mul_f32 v[44:45], v[44:45], v[48:49]
	v_pk_mul_f32 v[48:49], v[36:37], s[10:11] op_sel_hi:[1,0]
	v_pk_mul_f32 v[38:39], v[38:39], v[152:153] op_sel_hi:[1,0]
	v_exp_f32_e32 v48, v48
	v_exp_f32_e32 v49, v49
	v_pk_add_f32 v[46:47], v[50:51], 1.0 op_sel_hi:[1,0]
	v_pk_mul_f32 v[34:35], v[34:35], v[38:39]
	v_rcp_f32_e32 v38, v46
	v_rcp_f32_e32 v39, v47
	v_pk_add_f32 v[46:47], v[48:49], 1.0 op_sel_hi:[1,0]
	v_mad_i64_i32 v[52:53], s[22:23], v163, s46, v[148:149]
	v_rcp_f32_e32 v46, v46
	v_rcp_f32_e32 v47, v47
	v_pk_mul_f32 v[38:39], v[34:35], v[38:39]
	v_pk_mul_f32 v[34:35], v[40:41], v[152:153] op_sel_hi:[1,0]
	v_pk_mul_f32 v[26:27], v[26:27], v[150:151] op_sel_hi:[1,0]
	v_pk_mul_f32 v[34:35], v[36:37], v[34:35]
	v_pk_mul_f32 v[28:29], v[28:29], v[150:151] op_sel_hi:[1,0]
	v_pk_mul_f32 v[40:41], v[34:35], v[46:47]
	v_lshl_add_u64 v[46:47], v[52:53], 0, v[114:115]
	v_cvt_pk_bf16_f32 v34, v42, v43
	v_cvt_pk_bf16_f32 v35, v44, v45
	v_cvt_pk_bf16_f32 v36, v38, v39
	v_cvt_pk_bf16_f32 v37, v40, v41
	global_store_dwordx4 v[46:47], v[34:37], off
	v_pk_mul_f32 v[38:39], v[28:29], s[10:11] op_sel_hi:[1,0]
	v_pk_mul_f32 v[30:31], v[30:31], v[150:151] op_sel_hi:[1,0]
	v_pk_mul_f32 v[34:35], v[26:27], s[10:11] op_sel_hi:[1,0]
	v_exp_f32_e32 v38, v38
	v_exp_f32_e32 v34, v34
	v_exp_f32_e32 v35, v35
	v_exp_f32_e32 v39, v39
	v_pk_mul_f32 v[26:27], v[26:27], v[30:31]
	v_pk_mul_f32 v[30:31], v[32:33], v[150:151] op_sel_hi:[1,0]
	v_pk_add_f32 v[34:35], v[34:35], 1.0 op_sel_hi:[1,0]
	v_pk_add_f32 v[32:33], v[38:39], 1.0 op_sel_hi:[1,0]
	v_rcp_f32_e32 v34, v34
	v_rcp_f32_e32 v35, v35
	v_rcp_f32_e32 v32, v32
	v_rcp_f32_e32 v33, v33
	v_pk_mul_f32 v[18:19], v[18:19], v[150:151] op_sel_hi:[1,0]
	v_pk_mul_f32 v[26:27], v[26:27], v[34:35]
	v_pk_mul_f32 v[34:35], v[18:19], s[10:11] op_sel_hi:[1,0]
	v_pk_mul_f32 v[28:29], v[28:29], v[30:31]
	v_exp_f32_e32 v34, v34
	v_exp_f32_e32 v35, v35
; __device__ __forceinline__ unsigned cvt_pk_bf16(float lo, float hi) { unsigned r; asm volatile("v_cvt_pk_bf16_f32 %0, %1, %2" : "=v"(r) : "v"(lo), "v"(hi)); return r; }
; __device__ __forceinline__ unsigned cvt_pk_bf16(float lo, float hi) { unsigned r; asm volatile("v_cvt_pk_bf16_f32 %0, %1, %2" : "=v"(r) : "v"(lo), "v"(hi)); return r; }
; #define PG8_BAR __builtin_amdgcn_s_barrier()
;     __device__ __forceinline__ void operator()(const f32x4 (&acc)[2][2][4][2], const Unit& u, int wr, int wc, int fr, int fq) const {
;     ...
;             for (int m = 0; m < 4; ++m) { const int row = row0 + ai * HALF + m * 16; bf16_t* rowp = O + (size_t)row * ldc + col0; float a[8];
; #pragma unroll
;                 for (int n = 0; n < 2; ++n)
; #pragma unroll
;                     for (int i = 0; i < 4; i += 2) {
;                         const f32x2 r2 = {rs[ai][m], rs[ai][m]};
;                         const f32x2 g = (f32x2){acc[ai][0][m][n][i], acc[ai][0][m][n][i + 1]} * r2, up = (f32x2){acc[ai][1][m][n][i], acc[ai][1][m][n][i + 1]} * r2;
;                         const f32x2 t = g * (f32x2){-1.4426950408889634f, -1.4426950408889634f};
;                         const f32x2 d = (f32x2){__builtin_amdgcn_exp2f(t.x), __builtin_amdgcn_exp2f(t.y)} + (f32x2){1.0f, 1.0f};
;                         const f32x2 o2 = (g * up) * (f32x2){__builtin_amdgcn_rcpf(d.x), __builtin_amdgcn_rcpf(d.y)};
;                         a[4 * n + i] = o2.x; a[4 * n + i + 1] = o2.y; }
;                 u32x4 w; w.x = cvt_pk_bf16(a[0], a[1]); w.y = cvt_pk_bf16(a[2], a[3]); w.z = cvt_pk_bf16(a[4], a[5]); w.w = cvt_pk_bf16(a[6], a[7]);
;                 *(u32x4*)rowp = w; }
; template <class Epi, class Sched, bool ALIGN_EPI = false, bool SP2 = false>
; __device__ __forceinline__ void gemm_phase(PG8_LAS unsigned char* lds, const Gemm g, const Sched& S, const Epi& E) {
;     ...
; #pragma unroll
;         for (int a = 0; a < 2; ++a)
; #pragma unroll
;             for (int b = 0; b < 2; ++b)
; #pragma unroll
;                 for (int m = 0; m < 4; ++m)
; #pragma unroll
;                     for (int n = 0; n < 2; ++n) { d64x2 z_; asm volatile("v_mov_b64 %0, 0\n\tv_mov_b64 %1, 0" : "=v"(z_.x), "=v"(z_.y)); acc[a][b][m][n] = __builtin_bit_cast(f32x4, z_); }
;         cur = nxt; cA = nA; cB = nB; ++ui;
;         if constexpr (ALIGN_EPI) { if (wr == 1) PG8_BAR; }
	v_pk_mul_f32 v[20:21], v[20:21], v[150:151] op_sel_hi:[1,0]
	v_pk_mul_f32 v[28:29], v[28:29], v[32:33]
	v_pk_mul_f32 v[32:33], v[20:21], s[10:11] op_sel_hi:[1,0]
	v_pk_mul_f32 v[22:23], v[22:23], v[150:151] op_sel_hi:[1,0]
	v_exp_f32_e32 v32, v32
	v_exp_f32_e32 v33, v33
	v_pk_add_f32 v[30:31], v[34:35], 1.0 op_sel_hi:[1,0]
	v_pk_mul_f32 v[18:19], v[18:19], v[22:23]
	v_rcp_f32_e32 v22, v30
	v_rcp_f32_e32 v23, v31
	v_fmamk_f32 v146, v146, 0x2d800000, v159
	v_pk_add_f32 v[30:31], v[32:33], 1.0 op_sel_hi:[1,0]
	v_rsq_f32_e32 v146, v146
	v_rcp_f32_e32 v30, v30
	v_rcp_f32_e32 v31, v31
	v_pk_mul_f32 v[22:23], v[18:19], v[22:23]
	v_pk_mul_f32 v[18:19], v[24:25], v[150:151] op_sel_hi:[1,0]
	v_mad_i64_i32 v[36:37], s[22:23], v161, s46, v[148:149]
	v_pk_mul_f32 v[18:19], v[20:21], v[18:19]
	v_pk_mul_f32 v[10:11], v[10:11], v[146:147] op_sel_hi:[1,0]
	v_pk_mul_f32 v[24:25], v[18:19], v[30:31]
	v_lshl_add_u64 v[30:31], v[36:37], 0, v[114:115]
	v_cvt_pk_bf16_f32 v18, v26, v27
	v_cvt_pk_bf16_f32 v19, v28, v29
	v_cvt_pk_bf16_f32 v20, v22, v23
	v_cvt_pk_bf16_f32 v21, v24, v25
	global_store_dwordx4 v[30:31], v[18:21], off
	v_pk_mul_f32 v[12:13], v[12:13], v[146:147] op_sel_hi:[1,0]
	v_pk_mul_f32 v[14:15], v[14:15], v[146:147] op_sel_hi:[1,0]
	v_pk_mul_f32 v[18:19], v[10:11], s[10:11] op_sel_hi:[1,0]
	v_pk_mul_f32 v[22:23], v[12:13], s[10:11] op_sel_hi:[1,0]
	v_exp_f32_e32 v18, v18
	v_exp_f32_e32 v19, v19
	v_exp_f32_e32 v22, v22
	v_exp_f32_e32 v23, v23
	v_pk_mul_f32 v[10:11], v[10:11], v[14:15]
	v_pk_add_f32 v[18:19], v[18:19], 1.0 op_sel_hi:[1,0]
	v_pk_mul_f32 v[14:15], v[16:17], v[146:147] op_sel_hi:[1,0]
	v_rcp_f32_e32 v18, v18
	v_rcp_f32_e32 v19, v19
	v_pk_add_f32 v[16:17], v[22:23], 1.0 op_sel_hi:[1,0]
	v_pk_mul_f32 v[2:3], v[2:3], v[146:147] op_sel_hi:[1,0]
	v_rcp_f32_e32 v16, v16
	v_rcp_f32_e32 v17, v17
	v_pk_mul_f32 v[10:11], v[10:11], v[18:19]
	v_pk_mul_f32 v[18:19], v[2:3], s[10:11] op_sel_hi:[1,0]
	v_pk_mul_f32 v[12:13], v[12:13], v[14:15]
	v_exp_f32_e32 v18, v18
	v_exp_f32_e32 v19, v19
	v_pk_mul_f32 v[4:5], v[4:5], v[146:147] op_sel_hi:[1,0]
	v_pk_mul_f32 v[12:13], v[12:13], v[16:17]
	v_pk_mul_f32 v[16:17], v[4:5], s[10:11] op_sel_hi:[1,0]
	v_pk_mul_f32 v[6:7], v[6:7], v[146:147] op_sel_hi:[1,0]
	v_exp_f32_e32 v16, v16
	v_exp_f32_e32 v17, v17
	v_pk_add_f32 v[14:15], v[18:19], 1.0 op_sel_hi:[1,0]
	v_pk_mul_f32 v[2:3], v[2:3], v[6:7]
	v_rcp_f32_e32 v6, v14
	v_rcp_f32_e32 v7, v15
	v_pk_add_f32 v[14:15], v[16:17], 1.0 op_sel_hi:[1,0]
	v_mad_i64_i32 v[20:21], s[22:23], v157, s46, v[148:149]
	v_rcp_f32_e32 v14, v14
	v_rcp_f32_e32 v15, v15
	v_pk_mul_f32 v[6:7], v[2:3], v[6:7]
	v_pk_mul_f32 v[2:3], v[8:9], v[146:147] op_sel_hi:[1,0]
	s_nop 0
	v_pk_mul_f32 v[2:3], v[4:5], v[2:3]
	s_nop 0
	v_pk_mul_f32 v[8:9], v[2:3], v[14:15]
	v_lshl_add_u64 v[14:15], v[20:21], 0, v[114:115]
	v_cvt_pk_bf16_f32 v2, v10, v11
	v_cvt_pk_bf16_f32 v3, v12, v13
	v_cvt_pk_bf16_f32 v4, v6, v7
	v_cvt_pk_bf16_f32 v5, v8, v9
	global_store_dwordx4 v[14:15], v[2:5], off
	s_cbranch_vccnz .LBB0_1677
	s_andn2_b64 vcc, exec, s[2:3]
	v_mov_b64 v[122:123], 0
	v_mov_b64 v[124:125], 0
	v_mov_b64 v[114:115], 0
	v_mov_b64 v[116:117], 0
	v_mov_b64 v[106:107], 0
	v_mov_b64 v[108:109], 0
	v_mov_b64 v[98:99], 0
	v_mov_b64 v[100:101], 0
	v_mov_b64 v[90:91], 0
	v_mov_b64 v[92:93], 0
	v_mov_b64 v[82:83], 0
	v_mov_b64 v[84:85], 0
	v_mov_b64 v[74:75], 0
	v_mov_b64 v[76:77], 0
	v_mov_b64 v[62:63], 0
	v_mov_b64 v[64:65], 0
	v_mov_b64 v[126:127], 0
	v_mov_b64 v[128:129], 0
	v_mov_b64 v[118:119], 0
	v_mov_b64 v[120:121], 0
	v_mov_b64 v[110:111], 0
	v_mov_b64 v[112:113], 0
	v_mov_b64 v[102:103], 0
	v_mov_b64 v[104:105], 0
	v_mov_b64 v[94:95], 0
	v_mov_b64 v[96:97], 0
	v_mov_b64 v[86:87], 0
	v_mov_b64 v[88:89], 0
	v_mov_b64 v[78:79], 0
	v_mov_b64 v[80:81], 0
	v_mov_b64 v[70:71], 0
	v_mov_b64 v[72:73], 0
	v_mov_b64 v[58:59], 0
	v_mov_b64 v[60:61], 0
	v_mov_b64 v[50:51], 0
	v_mov_b64 v[52:53], 0
	v_mov_b64 v[42:43], 0
	v_mov_b64 v[44:45], 0
	v_mov_b64 v[34:35], 0
	v_mov_b64 v[36:37], 0
	v_mov_b64 v[26:27], 0
	v_mov_b64 v[28:29], 0
	v_mov_b64 v[18:19], 0
	v_mov_b64 v[20:21], 0
	v_mov_b64 v[10:11], 0
	v_mov_b64 v[12:13], 0
	v_mov_b64 v[2:3], 0
	v_mov_b64 v[4:5], 0
	v_mov_b64 v[66:67], 0
	v_mov_b64 v[68:69], 0
	v_mov_b64 v[54:55], 0
	v_mov_b64 v[56:57], 0
	v_mov_b64 v[46:47], 0
	v_mov_b64 v[48:49], 0
	v_mov_b64 v[38:39], 0
	v_mov_b64 v[40:41], 0
	v_mov_b64 v[30:31], 0
	v_mov_b64 v[32:33], 0
	v_mov_b64 v[22:23], 0
	v_mov_b64 v[24:25], 0
	v_mov_b64 v[14:15], 0
	v_mov_b64 v[16:17], 0
	v_mov_b64 v[6:7], 0
	v_mov_b64 v[8:9], 0
	s_cbranch_vccnz .LBB0_1676
	s_barrier
	s_branch .LBB0_1676
